# GEMM K-loops: 38 LDS-DMA stage loads rewritten to scalar-base form (v_lshl_add_u64 + global_load_lds vT,off -> global_load_lds v_off32, s_base); on top of v52
# baseline (speedup 1.0000x reference)
; #define PG8_STAGE(bufoff, gbase, voff) do { _Pragma("unroll") for (int _i = 0; _i < 2; ++_i) \
;     __builtin_amdgcn_global_load_lds((const unsigned*)((const char*)(gbase) + (voff)[_i]), (LAS unsigned*)(lds + (bufoff) + ldsw + _i * 8192), 16, 0, 0); } while (0)
; #define PG8_WAIT_V(n) asm volatile("s_waitcnt vmcnt(" #n ")" ::: "memory")
; #define PG8_BAR __builtin_amdgcn_s_barrier()
; #define PG8_WAIT_V(n) asm volatile("s_waitcnt vmcnt(" #n ")" ::: "memory")
; #define PG8_BAR __builtin_amdgcn_s_barrier()
; template <class Epi>
; DI void gemm_phase(char* smem, const bf16_t* A, int lda, const bf16_t* Bt, int ldb, int K, const Order& S_, const Epi& E) {
;     ...
;   const int aoff = lds_byte(wr * 64 + fr, fq * 8), boff = lds_byte(wc * 32 + fr, fq * 8);
;     ...
;   const char* cA = (const char*)A + (size_t)cur.pm * tstepA; const char* cB = (const char*)Bt + (size_t)cur.pn * tstepB;
;   PG8_STAGE(PG8_SB(0, 0), cB, voffB); PG8_STAGE(PG8_SA(0, 0), cA, voffA); PG8_STAGE(PG8_SB(0, 1), cB + hstepB, voffB); PG8_STAGE(PG8_SA(0, 1), cA + hstepA, voffA);
;   if (wr == 1) PG8_BAR;
;   PG8_WAIT_V(4); PG8_BAR;
;   PG8_STAGE(PG8_SB(1, 0), cB + kstep, voffB); PG8_STAGE(PG8_SA(1, 0), cA + kstep, voffA); PG8_STAGE(PG8_SB(1, 1), cB + hstepB + kstep, voffB);
;   PG8_WAIT_V(6); PG8_BAR;
.LBB0_455:
	v_lshl_add_u64 v[8:9], s[46:47], 0, v[220:221]
	v_mov_b32_e32 v129, v221
	s_lshl_b32 s0, s16, 5
	v_lshl_add_u64 v[10:11], s[46:47], 0, v[128:129]
	v_mov_b32_e32 v131, v221
	s_and_b32 s27, s0, 0x60
	v_lshl_add_u64 v[8:9], v[8:9], 0, s[58:59]
	s_add_i32 m0, s5, 0x18000
	v_lshl_add_u64 v[12:13], s[44:45], 0, v[130:131]
	v_mov_b32_e32 v133, v221
	s_lshl_b32 s26, s29, 13
	s_lshl_b32 s34, s27, 7
	s_waitcnt vmcnt(4)
	s_barrier
	global_load_lds_dwordx4 v[8:9], off
	v_lshl_add_u64 v[8:9], v[10:11], 0, s[58:59]
	s_add_i32 m0, s5, 0x1a000
	s_add_i32 s16, s5, 0x8000
	s_add_i32 s20, s5, 0xa000
	v_lshl_add_u64 v[14:15], s[44:45], 0, v[132:133]
	global_load_lds_dwordx4 v[8:9], off
	v_lshl_add_u64 v[8:9], v[12:13], 0, s[58:59]
	s_mov_b32 m0, s16
	s_add_u32 s0, s46, 0x40080
	global_load_lds_dwordx4 v[8:9], off
	v_lshl_add_u64 v[8:9], v[14:15], 0, s[58:59]
	s_mov_b32 m0, s20
	s_addc_u32 s1, s47, 0
	global_load_lds_dwordx4 v[8:9], off
	s_add_i32 m0, s5, 0x1c000
	v_and_b32_e32 v7, 15, v0
	global_load_lds_dwordx4 v220, s[0:1]
	s_add_i32 m0, s5, 0x1e000
	v_lshl_or_b32 v140, s29, 6, v7
	global_load_lds_dwordx4 v128, s[0:1]
	v_lshrrev_b32_e32 v8, 1, v0
	v_and_b32_e32 v8, 24, v8
	v_lshlrev_b32_e32 v9, 1, v8
	v_lshlrev_b32_e32 v0, 2, v0
	v_lshl_or_b32 v7, v7, 6, v9
	v_and_b32_e32 v0, 32, v0
	v_bitop3_b32 v9, v7, s26, v0 bitop3:0xde
	v_bitop3_b32 v141, v7, s34, v0 bitop3:0xde
	v_lshlrev_b32_e32 v0, 14, v1
	v_and_b32_e32 v0, 0xffff8000, v0
	v_lshl_add_u32 v0, v2, 11, v0
	v_and_b32_e32 v1, 1, v1
	v_lshl_or_b32 v0, v1, 6, v0
	v_lshl_add_u32 v134, v4, 1, v0
	v_lshlrev_b32_e32 v0, 14, v3
	v_and_b32_e32 v0, 0xffff8000, v0
	s_waitcnt vmcnt(6)
	v_lshl_add_u32 v0, v5, 11, v0
	v_and_b32_e32 v1, 1, v3
	v_lshl_or_b32 v0, v1, 6, v0
	v_or_b32_e32 v142, s27, v8
	v_mov_b32_e32 v135, v221
	v_lshl_add_u32 v136, v6, 1, v0
	v_mov_b32_e32 v137, v221
	s_mov_b32 s29, 0
	v_add_u32_e32 v143, 0, v9
	s_barrier
	s_branch .LBB0_457

; #define PG8_LDA(dst, b, h) do { _Pragma("unroll") for (int m = 0; m < 4; ++m) _Pragma("unroll") for (int k = 0; k < 2; ++k) dst[m][k] = *(const LAS bf16x8*)(lds + PG8_SA(b, h) + aoff + m * 2048 + k * 1024); } while (0)
; #define PG8_LDB(dst, b, h) do { _Pragma("unroll") for (int n = 0; n < 2; ++n) _Pragma("unroll") for (int k = 0; k < 2; ++k) dst[n][k] = *(const LAS bf16x8*)(lds + PG8_SB(b, h) + boff + n * 2048 + k * 1024); } while (0)
; #define PG8_MMA(ai, bj, At, Bt_) do { __builtin_amdgcn_s_setprio(1); _Pragma("unroll") for (int m = 0; m < 4; ++m) _Pragma("unroll") for (int n = 0; n < 2; ++n) _Pragma("unroll") for (int k = 0; k < 2; ++k) \
;     acc[ai][bj][m][n] = __builtin_amdgcn_mfma_f32_16x16x32_bf16(Bt_[n][k], At[m][k], acc[ai][bj][m][n], 0, 0, 0); __builtin_amdgcn_s_setprio(0); } while (0)
; #define PG8_WAIT_V(n) asm volatile("s_waitcnt vmcnt(" #n ")" ::: "memory")
; template <class Epi>
; DI void gemm_phase(char* smem, const bf16_t* A, int lda, const bf16_t* Bt, int ldb, int K, const Order& S_, const Epi& E) {
;     ...
;     const bool has_next = S_.next(ui + 1, nxt);
;     const char* nA = has_next ? (const char*)A + (size_t)nxt.pm * tstepA : cA; const char* nB = has_next ? (const char*)Bt + (size_t)nxt.pn * tstepB : cB;
; template <class Sched, class Epi>
; DI void gemm_stream(char* smem, const Sched& S_, const Epi& E) {
;     ...
;     for (int t = 0; t < nt; t += 2) {
;       const bool last = (t == nt - 2);
;       const char* a1 = cA + (size_t)(t + 1) * kstep;
;       const char* a2 = last ? nA : cA + (size_t)(t + 2) * kstep; const char* b2 = last ? nB : cB + (size_t)(t + 2) * kstep;
;       const char* a3 = a2 + kstep; const char* b3 = b2 + kstep;
;       const int xa2 = (last ? nxt.lda : cur.lda) * 2, xb2 = (last ? nxt.ldb : cur.ldb) * 2;
;       const size_t xhA = (size_t)HALF * xa2, xhB = (size_t)HALF * xb2;
;       PG8_LDB(B0, 0, 0); PG8_SCHED; PG8_LDA(At, 0, 0); PG8_STA(PG8_SA(1, 1), a1 + hA, la2);
;       PG8_WAIT_L(8); PG8_BAR; PG8_WAIT_L(0); PG8_MMA(0, 0, At, B0); PG8_BAR; PG8_SCHED;
;       PG8_LDB(B1, 0, 1); PG8_STB(PG8_SB(0, 0), b2, xb2);
;       PG8_BAR; PG8_WAIT_L(0); PG8_MMA(0, 1, At, B1); PG8_BAR;
;       PG8_LDA(At, 0, 1); PG8_STA(PG8_SA(0, 0), a2, xa2);
;       PG8_BAR; PG8_WAIT_L(0); PG8_MMA(1, 0, At, B0); PG8_BAR; PG8_SCHED;
;       PG8_STB(PG8_SB(0, 1), b2 + xhB, xb2);
;       PG8_WAIT_V(6); PG8_BAR; PG8_MMA(1, 1, At, B1); PG8_BAR;
.LBB0_466:
	s_add_u32 s46, s44, 0xfffc0080
	s_addc_u32 s47, s45, -1
	s_add_i32 s52, 0, 0x10000
	v_add_u32_e32 v138, s52, v141
	ds_read_b128 v[144:147], v138
	ds_read_b128 v[148:151], v138 offset:1024
	ds_read_b128 v[152:155], v138 offset:2048
	ds_read_b128 v[156:159], v138 offset:3072
	s_cmp_eq_u32 s49, 12
	s_cselect_b32 s51, s37, s47
	s_cselect_b32 s50, s36, s46
	s_cselect_b32 s47, s41, s27
	s_cselect_b32 s46, s40, s1
	s_add_i32 m0, s5, 0xc000
	ds_read_b128 v[160:163], v143
	ds_read_b128 v[164:167], v143 offset:1024
	ds_read_b128 v[168:171], v143 offset:2048
	ds_read_b128 v[172:175], v143 offset:3072
	ds_read_b128 v[176:179], v143 offset:4096
	ds_read_b128 v[180:183], v143 offset:5120
	ds_read_b128 v[184:187], v143 offset:6144
	ds_read_b128 v[188:191], v143 offset:7168
	global_load_lds_dwordx4 v134, s[44:45]
	s_add_i32 m0, s5, 0xe000
	s_nop 0
	global_load_lds_dwordx4 v136, s[44:45]
	s_waitcnt lgkmcnt(8)
	s_barrier
	s_waitcnt lgkmcnt(0)
	s_setprio 1
	s_waitcnt lgkmcnt(0)
	v_mfma_f32_16x16x32_bf16 v[124:127], v[144:147], v[160:163], v[124:127]
	v_mfma_f32_16x16x32_bf16 v[120:123], v[152:155], v[160:163], v[120:123]
	v_mfma_f32_16x16x32_bf16 v[116:119], v[144:147], v[168:171], v[116:119]
	v_mfma_f32_16x16x32_bf16 v[112:115], v[152:155], v[168:171], v[112:115]
	v_mfma_f32_16x16x32_bf16 v[108:111], v[144:147], v[176:179], v[108:111]
	v_mfma_f32_16x16x32_bf16 v[100:103], v[152:155], v[176:179], v[100:103]
	v_mfma_f32_16x16x32_bf16 v[92:95], v[144:147], v[184:187], v[92:95]
	v_mfma_f32_16x16x32_bf16 v[84:87], v[152:155], v[184:187], v[84:87]
	v_mfma_f32_16x16x32_bf16 v[124:127], v[148:151], v[164:167], v[124:127]
	v_mfma_f32_16x16x32_bf16 v[120:123], v[156:159], v[164:167], v[120:123]
	v_mfma_f32_16x16x32_bf16 v[116:119], v[148:151], v[172:175], v[116:119]
	v_mfma_f32_16x16x32_bf16 v[112:115], v[156:159], v[172:175], v[112:115]
	v_mfma_f32_16x16x32_bf16 v[108:111], v[148:151], v[180:183], v[108:111]
	v_mfma_f32_16x16x32_bf16 v[100:103], v[156:159], v[180:183], v[100:103]
	v_mfma_f32_16x16x32_bf16 v[92:95], v[148:151], v[188:191], v[92:95]
	v_mfma_f32_16x16x32_bf16 v[84:87], v[156:159], v[188:191], v[84:87]
	s_setprio 0
	s_barrier
	s_add_i32 s56, 0, 0x14000
	v_add_u32_e32 v138, s56, v141
	s_add_i32 s52, s52, s4
	ds_read_b128 v[210:213], v138
	ds_read_b128 v[214:217], v138 offset:1024
	ds_read_b128 v[234:237], v138 offset:2048
	ds_read_b128 v[238:241], v138 offset:3072
	v_lshl_add_u64 v[138:139], s[46:47], 0, v[220:221]
	s_mov_b32 m0, s52
	v_lshl_add_u64 v[218:219], s[46:47], 0, v[128:129]
	global_load_lds_dwordx4 v[138:139], off
	s_add_i32 m0, s52, 0x2000
	s_nop 0
	global_load_lds_dwordx4 v[218:219], off
	s_barrier
	s_waitcnt lgkmcnt(0)
	s_setprio 1
	s_waitcnt lgkmcnt(0)
	v_mfma_f32_16x16x32_bf16 v[104:107], v[210:213], v[160:163], v[104:107]
	v_mfma_f32_16x16x32_bf16 v[96:99], v[234:237], v[160:163], v[96:99]
	v_mfma_f32_16x16x32_bf16 v[88:91], v[210:213], v[168:171], v[88:91]
	v_mfma_f32_16x16x32_bf16 v[80:83], v[234:237], v[168:171], v[80:83]
	v_mfma_f32_16x16x32_bf16 v[76:79], v[210:213], v[176:179], v[76:79]
	v_mfma_f32_16x16x32_bf16 v[72:75], v[234:237], v[176:179], v[72:75]
	v_mfma_f32_16x16x32_bf16 v[68:71], v[210:213], v[184:187], v[68:71]
	v_mfma_f32_16x16x32_bf16 v[64:67], v[234:237], v[184:187], v[64:67]
	v_mfma_f32_16x16x32_bf16 v[104:107], v[214:217], v[164:167], v[104:107]
	v_mfma_f32_16x16x32_bf16 v[96:99], v[238:241], v[164:167], v[96:99]
	v_mfma_f32_16x16x32_bf16 v[88:91], v[214:217], v[172:175], v[88:91]
	v_mfma_f32_16x16x32_bf16 v[80:83], v[238:241], v[172:175], v[80:83]
	v_mfma_f32_16x16x32_bf16 v[76:79], v[214:217], v[180:183], v[76:79]
	v_mfma_f32_16x16x32_bf16 v[72:75], v[238:241], v[180:183], v[72:75]
	v_mfma_f32_16x16x32_bf16 v[68:71], v[214:217], v[188:191], v[68:71]
	v_mfma_f32_16x16x32_bf16 v[64:67], v[238:241], v[188:191], v[64:67]
	s_setprio 0
	s_mov_b32 m0, s5
	v_lshl_add_u64 v[242:243], s[50:51], 0, v[130:131]
	s_barrier
	ds_read_b128 v[160:163], v143 offset:16384
	ds_read_b128 v[164:167], v143 offset:17408
	ds_read_b128 v[168:171], v143 offset:18432
	ds_read_b128 v[172:175], v143 offset:19456
	ds_read_b128 v[176:179], v143 offset:20480
	ds_read_b128 v[180:183], v143 offset:21504
	ds_read_b128 v[184:187], v143 offset:22528
	ds_read_b128 v[188:191], v143 offset:23552
	global_load_lds_dwordx4 v[242:243], off
	v_lshl_add_u64 v[244:245], s[50:51], 0, v[132:133]
	s_mov_b32 m0, s9
	s_nop 0
	global_load_lds_dwordx4 v[244:245], off
	s_barrier
	s_waitcnt lgkmcnt(0)
	s_setprio 1
	s_waitcnt lgkmcnt(0)
	v_mfma_f32_16x16x32_bf16 v[60:63], v[144:147], v[160:163], v[60:63]
	v_mfma_f32_16x16x32_bf16 v[56:59], v[152:155], v[160:163], v[56:59]
	v_mfma_f32_16x16x32_bf16 v[52:55], v[144:147], v[168:171], v[52:55]
	v_mfma_f32_16x16x32_bf16 v[48:51], v[152:155], v[168:171], v[48:51]
	v_mfma_f32_16x16x32_bf16 v[44:47], v[144:147], v[176:179], v[44:47]
	v_mfma_f32_16x16x32_bf16 v[36:39], v[152:155], v[176:179], v[36:39]
	v_mfma_f32_16x16x32_bf16 v[28:31], v[144:147], v[184:187], v[28:31]
	v_mfma_f32_16x16x32_bf16 v[20:23], v[152:155], v[184:187], v[20:23]
	v_mfma_f32_16x16x32_bf16 v[60:63], v[148:151], v[164:167], v[60:63]
	v_mfma_f32_16x16x32_bf16 v[56:59], v[156:159], v[164:167], v[56:59]
	v_mfma_f32_16x16x32_bf16 v[52:55], v[148:151], v[172:175], v[52:55]
	v_mfma_f32_16x16x32_bf16 v[48:51], v[156:159], v[172:175], v[48:51]
	v_mfma_f32_16x16x32_bf16 v[44:47], v[148:151], v[180:183], v[44:47]
	v_mfma_f32_16x16x32_bf16 v[36:39], v[156:159], v[180:183], v[36:39]
	v_mfma_f32_16x16x32_bf16 v[28:31], v[148:151], v[188:191], v[28:31]
	v_mfma_f32_16x16x32_bf16 v[20:23], v[156:159], v[188:191], v[20:23]
	s_setprio 0
	s_barrier
; #define PG8_LDA(dst, b, h) do { _Pragma("unroll") for (int m = 0; m < 4; ++m) _Pragma("unroll") for (int k = 0; k < 2; ++k) dst[m][k] = *(const LAS bf16x8*)(lds + PG8_SA(b, h) + aoff + m * 2048 + k * 1024); } while (0)
; #define PG8_LDB(dst, b, h) do { _Pragma("unroll") for (int n = 0; n < 2; ++n) _Pragma("unroll") for (int k = 0; k < 2; ++k) dst[n][k] = *(const LAS bf16x8*)(lds + PG8_SB(b, h) + boff + n * 2048 + k * 1024); } while (0)
; #define PG8_MMA(ai, bj, At, Bt_) do { __builtin_amdgcn_s_setprio(1); _Pragma("unroll") for (int m = 0; m < 4; ++m) _Pragma("unroll") for (int n = 0; n < 2; ++n) _Pragma("unroll") for (int k = 0; k < 2; ++k) \
;     acc[ai][bj][m][n] = __builtin_amdgcn_mfma_f32_16x16x32_bf16(Bt_[n][k], At[m][k], acc[ai][bj][m][n], 0, 0, 0); __builtin_amdgcn_s_setprio(0); } while (0)
; #define PG8_WAIT_V(n) asm volatile("s_waitcnt vmcnt(" #n ")" ::: "memory")
; #define PG8_WAIT_L(n) asm volatile("s_waitcnt lgkmcnt(" #n ")" ::: "memory")
; #define PG8_BAR __builtin_amdgcn_s_barrier()
; #define PG8_SCHED __builtin_amdgcn_sched_barrier(0)
; #define PG8_STA(bufoff, gbase, ld2) PG8_STAGE3(bufoff, gbase, ld2, R0, R1)
; #define PG8_STB(bufoff, gbase, ld2) PG8_STAGE3(bufoff, gbase, ld2, Rb0, Rb1)
; #define PG8_LDA(dst, b, h) do { _Pragma("unroll") for (int m = 0; m < 4; ++m) _Pragma("unroll") for (int k = 0; k < 2; ++k) dst[m][k] = *(const LAS bf16x8*)(lds + PG8_SA(b, h) + aoff + m * 2048 + k * 1024); } while (0)
; #define PG8_WAIT_V(n) asm volatile("s_waitcnt vmcnt(" #n ")" ::: "memory")
; #define PG8_WAIT_L(n) asm volatile("s_waitcnt lgkmcnt(" #n ")" ::: "memory")
; template <class Sched, class Epi>
; DI void gemm_stream(char* smem, const Sched& S_, const Epi& E) {
;     ...
;       PG8_STB(PG8_SB(0, 1), b2 + xhB, xb2);
;       PG8_WAIT_V(6); PG8_BAR; PG8_MMA(1, 1, At, B1); PG8_BAR;
;       PG8_LDB(B0, 1, 0); PG8_SCHED; PG8_LDA(At, 1, 0); PG8_STA(PG8_SA(0, 1), a2 + xhA, xa2);
;       PG8_WAIT_L(8); PG8_BAR; PG8_WAIT_L(0); PG8_MMA(0, 0, At, B0); PG8_BAR; PG8_SCHED;
;       PG8_LDB(B1, 1, 1); PG8_STB(PG8_SB(1, 0), b3, xb2);
;       PG8_BAR; PG8_WAIT_L(0); PG8_MMA(0, 1, At, B1); PG8_BAR;
;       PG8_LDA(At, 1, 1); PG8_STA(PG8_SA(1, 0), a3, xa2);
;       PG8_BAR; PG8_WAIT_L(0); PG8_MMA(1, 0, At, B0); PG8_BAR; PG8_SCHED;
;       PG8_STB(PG8_SB(1, 1), b3 + xhB, xb2);
;       PG8_WAIT_V(6); PG8_BAR; PG8_MMA(1, 1, At, B1); PG8_BAR;
	s_add_u32 s52, s46, 0x40000
	s_addc_u32 s53, s47, 0
	s_add_i32 s56, s56, s4
	s_mov_b32 m0, s56
	s_nop 0
	global_load_lds_dwordx4 v220, s[52:53]
	s_add_i32 m0, s56, 0x2000
	s_nop 0
	global_load_lds_dwordx4 v128, s[52:53]
	s_waitcnt vmcnt(6)
	s_barrier
	s_setprio 1
	v_mfma_f32_16x16x32_bf16 v[40:43], v[210:213], v[160:163], v[40:43]
	v_mfma_f32_16x16x32_bf16 v[32:35], v[234:237], v[160:163], v[32:35]
	v_mfma_f32_16x16x32_bf16 v[24:27], v[210:213], v[168:171], v[24:27]
	v_mfma_f32_16x16x32_bf16 v[16:19], v[234:237], v[168:171], v[16:19]
	v_mfma_f32_16x16x32_bf16 v[12:15], v[210:213], v[176:179], v[12:15]
	v_mfma_f32_16x16x32_bf16 v[8:11], v[234:237], v[176:179], v[8:11]
	v_mfma_f32_16x16x32_bf16 v[4:7], v[210:213], v[184:187], v[4:7]
	v_mfma_f32_16x16x32_bf16 v[0:3], v[234:237], v[184:187], v[0:3]
	v_mfma_f32_16x16x32_bf16 v[40:43], v[214:217], v[164:167], v[40:43]
	v_mfma_f32_16x16x32_bf16 v[32:35], v[238:241], v[164:167], v[32:35]
	v_mfma_f32_16x16x32_bf16 v[24:27], v[214:217], v[172:175], v[24:27]
	v_mfma_f32_16x16x32_bf16 v[16:19], v[238:241], v[172:175], v[16:19]
	v_mfma_f32_16x16x32_bf16 v[12:15], v[214:217], v[180:183], v[12:15]
	v_mfma_f32_16x16x32_bf16 v[8:11], v[238:241], v[180:183], v[8:11]
	v_mfma_f32_16x16x32_bf16 v[4:7], v[214:217], v[188:191], v[4:7]
	v_mfma_f32_16x16x32_bf16 v[0:3], v[238:241], v[188:191], v[0:3]
	s_setprio 0
	s_add_i32 s52, 0, 0x18000
	v_add_u32_e32 v156, s52, v141
	s_barrier
	ds_read_b128 v[144:147], v156
	ds_read_b128 v[148:151], v156 offset:1024
	ds_read_b128 v[152:155], v156 offset:2048
	ds_read_b128 v[156:159], v156 offset:3072
	s_add_u32 s50, s50, 0x40000
	s_addc_u32 s51, s51, 0
	s_mov_b32 m0, s13
	ds_read_b128 v[160:163], v143 offset:32768
	ds_read_b128 v[164:167], v143 offset:33792
	ds_read_b128 v[168:171], v143 offset:34816
	ds_read_b128 v[172:175], v143 offset:35840
	ds_read_b128 v[176:179], v143 offset:36864
	ds_read_b128 v[180:183], v143 offset:37888
	ds_read_b128 v[184:187], v143 offset:38912
	ds_read_b128 v[188:191], v143 offset:39936
	global_load_lds_dwordx4 v130, s[50:51]
	s_mov_b32 m0, s15
	s_nop 0
	global_load_lds_dwordx4 v132, s[50:51]
	s_waitcnt lgkmcnt(8)
	s_barrier
	s_waitcnt lgkmcnt(0)
	s_setprio 1
	s_waitcnt lgkmcnt(0)
	v_mfma_f32_16x16x32_bf16 v[124:127], v[144:147], v[160:163], v[124:127]
	v_mfma_f32_16x16x32_bf16 v[120:123], v[152:155], v[160:163], v[120:123]
	v_mfma_f32_16x16x32_bf16 v[116:119], v[144:147], v[168:171], v[116:119]
	v_mfma_f32_16x16x32_bf16 v[112:115], v[152:155], v[168:171], v[112:115]
	v_mfma_f32_16x16x32_bf16 v[108:111], v[144:147], v[176:179], v[108:111]
	v_mfma_f32_16x16x32_bf16 v[100:103], v[152:155], v[176:179], v[100:103]
	v_mfma_f32_16x16x32_bf16 v[92:95], v[144:147], v[184:187], v[92:95]
	v_mfma_f32_16x16x32_bf16 v[84:87], v[152:155], v[184:187], v[84:87]
	v_mfma_f32_16x16x32_bf16 v[124:127], v[148:151], v[164:167], v[124:127]
	v_mfma_f32_16x16x32_bf16 v[120:123], v[156:159], v[164:167], v[120:123]
	v_mfma_f32_16x16x32_bf16 v[116:119], v[148:151], v[172:175], v[116:119]
	v_mfma_f32_16x16x32_bf16 v[112:115], v[156:159], v[172:175], v[112:115]
	v_mfma_f32_16x16x32_bf16 v[108:111], v[148:151], v[180:183], v[108:111]
	v_mfma_f32_16x16x32_bf16 v[100:103], v[156:159], v[180:183], v[100:103]
	v_mfma_f32_16x16x32_bf16 v[92:95], v[148:151], v[188:191], v[92:95]
	v_mfma_f32_16x16x32_bf16 v[84:87], v[156:159], v[188:191], v[84:87]
	s_setprio 0
	s_barrier
	s_add_i32 s50, 0, 0x1c000
	s_add_i32 s51, s52, s4
	v_add_u32_e32 v194, s50, v141
	v_lshl_add_u64 v[138:139], v[138:139], 0, s[58:59]
	s_mov_b32 m0, s51
	ds_read_b128 v[210:213], v194
	ds_read_b128 v[214:217], v194 offset:1024
	ds_read_b128 v[234:237], v194 offset:2048
	ds_read_b128 v[238:241], v194 offset:3072
	global_load_lds_dwordx4 v[138:139], off
	v_lshl_add_u64 v[138:139], v[218:219], 0, s[58:59]
	s_add_i32 m0, s51, 0x2000
	s_nop 0
	global_load_lds_dwordx4 v[138:139], off
	s_barrier
	s_waitcnt lgkmcnt(0)
	s_setprio 1
	s_waitcnt lgkmcnt(0)
	v_mfma_f32_16x16x32_bf16 v[104:107], v[210:213], v[160:163], v[104:107]
	v_mfma_f32_16x16x32_bf16 v[96:99], v[234:237], v[160:163], v[96:99]
	v_mfma_f32_16x16x32_bf16 v[88:91], v[210:213], v[168:171], v[88:91]
	v_mfma_f32_16x16x32_bf16 v[80:83], v[234:237], v[168:171], v[80:83]
	v_mfma_f32_16x16x32_bf16 v[76:79], v[210:213], v[176:179], v[76:79]
	v_mfma_f32_16x16x32_bf16 v[72:75], v[234:237], v[176:179], v[72:75]
	v_mfma_f32_16x16x32_bf16 v[68:71], v[210:213], v[184:187], v[68:71]
	v_mfma_f32_16x16x32_bf16 v[64:67], v[234:237], v[184:187], v[64:67]
	v_mfma_f32_16x16x32_bf16 v[104:107], v[214:217], v[164:167], v[104:107]
	v_mfma_f32_16x16x32_bf16 v[96:99], v[238:241], v[164:167], v[96:99]
	v_mfma_f32_16x16x32_bf16 v[88:91], v[214:217], v[172:175], v[88:91]
	v_mfma_f32_16x16x32_bf16 v[80:83], v[238:241], v[172:175], v[80:83]
	v_mfma_f32_16x16x32_bf16 v[76:79], v[214:217], v[180:183], v[76:79]
	v_mfma_f32_16x16x32_bf16 v[72:75], v[238:241], v[180:183], v[72:75]
	v_mfma_f32_16x16x32_bf16 v[68:71], v[214:217], v[188:191], v[68:71]
	v_mfma_f32_16x16x32_bf16 v[64:67], v[238:241], v[188:191], v[64:67]
	s_setprio 0
	s_mov_b32 m0, s16
	v_lshl_add_u64 v[138:139], v[242:243], 0, s[58:59]
	s_barrier
	ds_read_b128 v[160:163], v143 offset:49152
	ds_read_b128 v[164:167], v143 offset:50176
	ds_read_b128 v[168:171], v143 offset:51200
	ds_read_b128 v[172:175], v143 offset:52224
	ds_read_b128 v[176:179], v143 offset:53248
	ds_read_b128 v[180:183], v143 offset:54272
	ds_read_b128 v[184:187], v143 offset:55296
	ds_read_b128 v[188:191], v143 offset:56320
	global_load_lds_dwordx4 v[138:139], off
	v_lshl_add_u64 v[138:139], v[244:245], 0, s[58:59]
	s_mov_b32 m0, s20
	s_nop 0
	global_load_lds_dwordx4 v[138:139], off
	s_barrier
; #define PG8_MMA(ai, bj, At, Bt_) do { __builtin_amdgcn_s_setprio(1); _Pragma("unroll") for (int m = 0; m < 4; ++m) _Pragma("unroll") for (int n = 0; n < 2; ++n) _Pragma("unroll") for (int k = 0; k < 2; ++k) \
;     acc[ai][bj][m][n] = __builtin_amdgcn_mfma_f32_16x16x32_bf16(Bt_[n][k], At[m][k], acc[ai][bj][m][n], 0, 0, 0); __builtin_amdgcn_s_setprio(0); } while (0)
; #define PG8_WAIT_V(n) asm volatile("s_waitcnt vmcnt(" #n ")" ::: "memory")
; #define PG8_BAR __builtin_amdgcn_s_barrier()
; DI u32x4 pack8v(const f32x4& a, const f32x4& b) { u32x4 w; w.x = pk2(a[0], a[1]); w.y = pk2(a[2], a[3]); w.z = pk2(b[0], b[1]); w.w = pk2(b[2], b[3]); return w; }
; #define PG8_STB(bufoff, gbase, ld2) PG8_STAGE3(bufoff, gbase, ld2, Rb0, Rb1)
; #define PG8_MMA(ai, bj, At, Bt_) do { __builtin_amdgcn_s_setprio(1); _Pragma("unroll") for (int m = 0; m < 4; ++m) _Pragma("unroll") for (int n = 0; n < 2; ++n) _Pragma("unroll") for (int k = 0; k < 2; ++k) \
;     acc[ai][bj][m][n] = __builtin_amdgcn_mfma_f32_16x16x32_bf16(Bt_[n][k], At[m][k], acc[ai][bj][m][n], 0, 0, 0); __builtin_amdgcn_s_setprio(0); } while (0)
; #define PG8_WAIT_V(n) asm volatile("s_waitcnt vmcnt(" #n ")" ::: "memory")
; #define PG8_BAR __builtin_amdgcn_s_barrier()
; template <class Sched, class Epi>
; DI void gemm_stream(char* smem, const Sched& S_, const Epi& E) {
;     ...
;       PG8_STB(PG8_SB(1, 1), b3 + xhB, xb2);
;       PG8_WAIT_V(6); PG8_BAR; PG8_MMA(1, 1, At, B1); PG8_BAR;
;     }
;     E(acc, cur, wr, wc, fr, fq);
;   DI void operator()(const acc_t& acc, const Desc& u, int wr, int wc, int fr, int fq) const {
;     ...
;           for (int bj = 0; bj < 2; ++bj) *(u32x4*)(rowp + bj * HALF) = pack8v(acc[ai][bj][m][0], acc[ai][bj][m][1]); }
;     ...
;           for (int bj = 0; bj < 2; ++bj) *(u32x4*)(rowp + bj * HALF) = pack8v(acc[ai][bj][m][0], acc[ai][bj][m][1]); }
	s_waitcnt lgkmcnt(0)
	s_setprio 1
	s_waitcnt lgkmcnt(0)
	v_mfma_f32_16x16x32_bf16 v[60:63], v[144:147], v[160:163], v[60:63]
	v_mfma_f32_16x16x32_bf16 v[56:59], v[152:155], v[160:163], v[56:59]
	v_mfma_f32_16x16x32_bf16 v[52:55], v[144:147], v[168:171], v[52:55]
	v_mfma_f32_16x16x32_bf16 v[48:51], v[152:155], v[168:171], v[48:51]
	v_mfma_f32_16x16x32_bf16 v[44:47], v[144:147], v[176:179], v[44:47]
	v_mfma_f32_16x16x32_bf16 v[36:39], v[152:155], v[176:179], v[36:39]
	v_mfma_f32_16x16x32_bf16 v[28:31], v[144:147], v[184:187], v[28:31]
	v_mfma_f32_16x16x32_bf16 v[20:23], v[152:155], v[184:187], v[20:23]
	v_mfma_f32_16x16x32_bf16 v[60:63], v[148:151], v[164:167], v[60:63]
	v_mfma_f32_16x16x32_bf16 v[56:59], v[156:159], v[164:167], v[56:59]
	v_mfma_f32_16x16x32_bf16 v[52:55], v[148:151], v[172:175], v[52:55]
	v_mfma_f32_16x16x32_bf16 v[48:51], v[156:159], v[172:175], v[48:51]
	v_mfma_f32_16x16x32_bf16 v[44:47], v[148:151], v[180:183], v[44:47]
	v_mfma_f32_16x16x32_bf16 v[36:39], v[156:159], v[180:183], v[36:39]
	v_mfma_f32_16x16x32_bf16 v[28:31], v[148:151], v[188:191], v[28:31]
	v_mfma_f32_16x16x32_bf16 v[20:23], v[156:159], v[188:191], v[20:23]
	s_setprio 0
	s_barrier
	s_add_u32 s46, s46, 0x40080
	s_addc_u32 s47, s47, 0
	s_add_i32 s50, s50, s4
	s_mov_b32 m0, s50
	s_nop 0
	global_load_lds_dwordx4 v220, s[46:47]
	s_add_i32 m0, s50, 0x2000
	s_nop 0
	global_load_lds_dwordx4 v128, s[46:47]
	s_waitcnt vmcnt(6)
	s_barrier
	s_setprio 1
	v_mfma_f32_16x16x32_bf16 v[40:43], v[210:213], v[160:163], v[40:43]
	v_mfma_f32_16x16x32_bf16 v[32:35], v[234:237], v[160:163], v[32:35]
	v_mfma_f32_16x16x32_bf16 v[24:27], v[210:213], v[168:171], v[24:27]
	v_mfma_f32_16x16x32_bf16 v[16:19], v[234:237], v[168:171], v[16:19]
	v_mfma_f32_16x16x32_bf16 v[12:15], v[210:213], v[176:179], v[12:15]
	v_mfma_f32_16x16x32_bf16 v[8:11], v[234:237], v[176:179], v[8:11]
	v_mfma_f32_16x16x32_bf16 v[4:7], v[210:213], v[184:187], v[4:7]
	v_mfma_f32_16x16x32_bf16 v[0:3], v[234:237], v[184:187], v[0:3]
	v_mfma_f32_16x16x32_bf16 v[40:43], v[214:217], v[164:167], v[40:43]
	v_mfma_f32_16x16x32_bf16 v[32:35], v[238:241], v[164:167], v[32:35]
	v_mfma_f32_16x16x32_bf16 v[24:27], v[214:217], v[172:175], v[24:27]
	v_mfma_f32_16x16x32_bf16 v[16:19], v[238:241], v[172:175], v[16:19]
	v_mfma_f32_16x16x32_bf16 v[12:15], v[214:217], v[180:183], v[12:15]
	v_mfma_f32_16x16x32_bf16 v[8:11], v[238:241], v[180:183], v[8:11]
	v_mfma_f32_16x16x32_bf16 v[4:7], v[214:217], v[188:191], v[4:7]
	v_mfma_f32_16x16x32_bf16 v[0:3], v[238:241], v[188:191], v[0:3]
	s_setprio 0
	s_add_i32 s49, s49, 2
	s_add_u32 s44, s44, 0x100
	s_addc_u32 s45, s45, 0
	s_add_u32 s1, s1, 0x100
	s_addc_u32 s27, s27, 0
	s_cmp_gt_u32 s49, 13
	s_barrier
	s_cbranch_scc0 .LBB0_466
	s_lshl_b32 s1, s33, 8
	v_lshl_add_u32 v138, s43, 8, v140
	s_cmp_lg_u32 s42, 0
	v_cvt_pk_bf16_f32 v124, v124, v125
	v_cvt_pk_bf16_f32 v125, v126, v127
	v_cvt_pk_bf16_f32 v126, v120, v121
	v_cvt_pk_bf16_f32 v127, v122, v123
	v_cvt_pk_bf16_f32 v104, v104, v105
	v_cvt_pk_bf16_f32 v105, v106, v107
	v_cvt_pk_bf16_f32 v106, v96, v97
	v_cvt_pk_bf16_f32 v107, v98, v99
	v_cvt_pk_bf16_f32 v96, v116, v117
	v_cvt_pk_bf16_f32 v97, v118, v119
	v_cvt_pk_bf16_f32 v98, v112, v113
	v_cvt_pk_bf16_f32 v99, v114, v115
	v_cvt_pk_bf16_f32 v88, v88, v89
	v_cvt_pk_bf16_f32 v89, v90, v91
	v_cvt_pk_bf16_f32 v90, v80, v81
	v_cvt_pk_bf16_f32 v91, v82, v83
	v_cvt_pk_bf16_f32 v80, v108, v109
	v_cvt_pk_bf16_f32 v81, v110, v111
	v_cvt_pk_bf16_f32 v82, v100, v101
	v_cvt_pk_bf16_f32 v83, v102, v103
	v_cvt_pk_bf16_f32 v76, v76, v77
	v_cvt_pk_bf16_f32 v77, v78, v79
	v_cvt_pk_bf16_f32 v78, v72, v73
	v_cvt_pk_bf16_f32 v79, v74, v75
	v_cvt_pk_bf16_f32 v72, v92, v93
	v_cvt_pk_bf16_f32 v73, v94, v95
	v_cvt_pk_bf16_f32 v74, v84, v85
	v_cvt_pk_bf16_f32 v75, v86, v87
	v_cvt_pk_bf16_f32 v68, v68, v69
	v_cvt_pk_bf16_f32 v69, v70, v71
	v_cvt_pk_bf16_f32 v70, v64, v65
	v_cvt_pk_bf16_f32 v71, v66, v67
	v_cvt_pk_bf16_f32 v60, v60, v61
	v_cvt_pk_bf16_f32 v61, v62, v63
	v_cvt_pk_bf16_f32 v62, v56, v57
	v_cvt_pk_bf16_f32 v63, v58, v59
	v_cvt_pk_bf16_f32 v40, v40, v41
	v_cvt_pk_bf16_f32 v41, v42, v43
	v_cvt_pk_bf16_f32 v42, v32, v33
	v_cvt_pk_bf16_f32 v43, v34, v35
	v_cvt_pk_bf16_f32 v32, v52, v53
	v_cvt_pk_bf16_f32 v33, v54, v55
	v_cvt_pk_bf16_f32 v34, v48, v49
	v_cvt_pk_bf16_f32 v35, v50, v51
	v_cvt_pk_bf16_f32 v24, v24, v25
	v_cvt_pk_bf16_f32 v25, v26, v27
	v_cvt_pk_bf16_f32 v26, v16, v17
	v_cvt_pk_bf16_f32 v27, v18, v19
	v_cvt_pk_bf16_f32 v16, v44, v45
	v_cvt_pk_bf16_f32 v17, v46, v47
	v_cvt_pk_bf16_f32 v18, v36, v37
	v_cvt_pk_bf16_f32 v19, v38, v39
	v_cvt_pk_bf16_f32 v12, v12, v13
	v_cvt_pk_bf16_f32 v13, v14, v15
	v_cvt_pk_bf16_f32 v14, v8, v9
	v_cvt_pk_bf16_f32 v15, v10, v11
	v_cvt_pk_bf16_f32 v8, v28, v29
	v_cvt_pk_bf16_f32 v9, v30, v31
	v_cvt_pk_bf16_f32 v10, v20, v21
	v_cvt_pk_bf16_f32 v11, v22, v23
	v_readlane_b32 s49, v254, 50
	s_cbranch_scc0 .LBB0_469
; DI u32x4 pack8v(const f32x4& a, const f32x4& b) { u32x4 w; w.x = pk2(a[0], a[1]); w.y = pk2(a[2], a[3]); w.z = pk2(b[0], b[1]); w.w = pk2(b[2], b[3]); return w; }
; template <class Epi>
; DI void gemm_phase(char* smem, const bf16_t* A, int lda, const bf16_t* Bt, int ldb, int K, const Order& S_, const Epi& E) {
;     ...
;     cur = nxt; cA = nA; cB = nB; ++ui;
;   DI void operator()(const acc_t& acc, const Desc& u, int wr, int wc, int fr, int fq) const {
;     ...
;       const int t0 = u.pn * BM, b = t0 / S, s0 = t0 - b * S + wc * 32 + 8 * fq;
; #pragma unroll
;       for (int ai = 0; ai < 2; ++ai)
; #pragma unroll
;         for (int m = 0; m < 4; ++m) { bf16_t* rowp = RVT + ((size_t)b * 512 + row0 + ai * HALF + m * 16) * S + s0;
; #pragma unroll
;           for (int bj = 0; bj < 2; ++bj) *(u32x4*)(rowp + bj * HALF) = pack8v(acc[ai][bj][m][0], acc[ai][bj][m][1]); }
	s_mul_hi_i32 s27, s33, 0x78787879
	s_lshr_b32 s33, s27, 31
	s_ashr_i32 s27, s27, 3
	s_add_i32 s42, s27, s33
	s_ashr_i32 s43, s42, 31
	s_mul_i32 s27, s42, 0xffffef00
	s_lshl_b64 s[42:43], s[42:43], 9
	v_ashrrev_i32_e32 v139, 31, v138
	v_lshl_add_u64 v[22:23], s[42:43], 0, v[138:139]
	v_readlane_b32 s42, v251, 41
	s_add_i32 s27, s27, s1
	v_readlane_b32 s43, v251, 42
	v_or_b32_e32 v20, s27, v142
	s_movk_i32 s27, 0x2200
	v_mov_b64_e32 v[28:29], s[42:43]
	v_mad_u64_u32 v[28:29], s[42:43], v22, s27, v[28:29]
	v_ashrrev_i32_e32 v21, 31, v20
	v_mad_i32_i24 v29, v23, s27, v29
	v_lshl_add_u64 v[22:23], v[20:21], 1, v[28:29]
	s_mov_b32 s27, 0x22000
	v_add_co_u32_e32 v28, vcc, s27, v22
	s_mov_b64 s[42:43], 0x22000
	s_nop 0
	v_addc_co_u32_e32 v29, vcc, 0, v23, vcc
	s_mov_b32 s27, 0x44000
	global_store_dwordx4 v[22:23], v[124:127], off
	global_store_dwordx4 v[22:23], v[104:107], off offset:256
	v_lshl_add_u64 v[20:21], v[22:23], 0, s[42:43]
	global_store_dwordx4 v[28:29], v[96:99], off
	global_store_dwordx4 v[20:21], v[88:91], off offset:256
	v_add_co_u32_e32 v28, vcc, s27, v22
	s_mov_b64 s[42:43], 0x44000
	s_nop 0
	v_addc_co_u32_e32 v29, vcc, 0, v23, vcc
	s_mov_b32 s27, 0x66000
	v_lshl_add_u64 v[20:21], v[22:23], 0, s[42:43]
	global_store_dwordx4 v[28:29], v[80:83], off
	global_store_dwordx4 v[20:21], v[76:79], off offset:256
	v_add_co_u32_e32 v28, vcc, s27, v22
	s_mov_b64 s[42:43], 0x66000
	s_nop 0
	v_addc_co_u32_e32 v29, vcc, 0, v23, vcc
	s_mov_b32 s27, 0x110000
	v_lshl_add_u64 v[20:21], v[22:23], 0, s[42:43]
	global_store_dwordx4 v[28:29], v[72:75], off
	global_store_dwordx4 v[20:21], v[68:71], off offset:256
	v_add_co_u32_e32 v28, vcc, s27, v22
	s_mov_b64 s[42:43], 0x110000
	s_nop 0
	v_addc_co_u32_e32 v29, vcc, 0, v23, vcc
	s_mov_b32 s27, 0x132000
	v_lshl_add_u64 v[20:21], v[22:23], 0, s[42:43]
	global_store_dwordx4 v[28:29], v[60:63], off
	global_store_dwordx4 v[20:21], v[40:43], off offset:256
	v_add_co_u32_e32 v28, vcc, s27, v22
	s_mov_b64 s[42:43], 0x132000
	s_nop 0
	v_addc_co_u32_e32 v29, vcc, 0, v23, vcc
	s_mov_b32 s27, 0x154000
	v_lshl_add_u64 v[20:21], v[22:23], 0, s[42:43]
	global_store_dwordx4 v[28:29], v[32:35], off
	global_store_dwordx4 v[20:21], v[24:27], off offset:256
	s_mov_b64 s[42:43], 0x154000
	v_add_co_u32_e32 v28, vcc, s27, v22
	v_lshl_add_u64 v[20:21], v[22:23], 0, s[42:43]
	s_nop 0
	v_addc_co_u32_e32 v29, vcc, 0, v23, vcc
	s_mov_b64 s[42:43], 0x176000
	global_store_dwordx4 v[28:29], v[16:19], off
	global_store_dwordx4 v[20:21], v[12:15], off offset:256
	v_lshl_add_u64 v[20:21], v[22:23], 0, s[42:43]
	v_add_co_u32_e32 v22, vcc, 0x176000, v22
	s_nop 1
	v_addc_co_u32_e32 v23, vcc, 0, v23, vcc
	global_store_dwordx4 v[22:23], v[8:11], off
	s_movk_i32 s50, 0x100
	s_mov_b32 s51, 0x78787879
	s_cbranch_execnz .LBB0_456
	s_branch .LBB0_470

; #define PG8_WAIT_V(n) asm volatile("s_waitcnt vmcnt(" #n ")" ::: "memory")
; #define PG8_BAR __builtin_amdgcn_s_barrier()
; #define PG8_STA(bufoff, gbase, ld2) PG8_STAGE3(bufoff, gbase, ld2, R0, R1)
; #define PG8_STB(bufoff, gbase, ld2) PG8_STAGE3(bufoff, gbase, ld2, Rb0, Rb1)
; #define PG8_WAIT_V(n) asm volatile("s_waitcnt vmcnt(" #n ")" ::: "memory")
; #define PG8_BAR __builtin_amdgcn_s_barrier()
; template <class Sched, class Epi>
; DI void gemm_stream(char* smem, const Sched& S_, const Epi& E) {
;     ...
;     const int la2 = cur.lda * 2, lb2 = cur.ldb * 2; const size_t hA = (size_t)HALF * la2, hB = (size_t)HALF * lb2;
;     PG8_STB(PG8_SB(0, 0), cB, lb2); PG8_STA(PG8_SA(0, 0), cA, la2); PG8_STB(PG8_SB(0, 1), cB + hB, lb2); PG8_STA(PG8_SA(0, 1), cA + hA, la2);
;     if (wr == 1) PG8_BAR;
;     PG8_WAIT_V(4); PG8_BAR;
;     PG8_STB(PG8_SB(1, 0), cB + kstep, lb2); PG8_STA(PG8_SA(1, 0), cA + kstep, la2); PG8_STB(PG8_SB(1, 1), cB + hB + kstep, lb2);
;     PG8_WAIT_V(6); PG8_BAR;
.LBB0_1152:
	v_lshrrev_b32_e32 v16, 1, v10
	v_and_b32_e32 v16, 24, v16
	s_lshl_b32 s0, s0, 5
	v_and_b32_e32 v15, 15, v10
	v_lshlrev_b32_e32 v17, 1, v16
	v_lshlrev_b32_e32 v10, 2, v10
	s_and_b32 s3, s0, 0x60
	v_lshl_add_u64 v[8:9], v[8:9], 0, s[58:59]
	s_add_i32 m0, s39, 0x18000
	v_lshl_or_b32 v238, s1, 6, v15
	v_lshl_or_b32 v15, v15, 6, v17
	s_lshl_b32 s1, s1, 13
	v_and_b32_e32 v10, 32, v10
	s_lshl_b32 s0, s3, 7
	s_waitcnt vmcnt(4)
	s_barrier
	global_load_lds_dwordx4 v[8:9], off
	v_lshl_add_u64 v[6:7], v[6:7], 0, s[58:59]
	s_add_i32 m0, s39, 0x1a000
	s_add_i32 s27, s39, 0x8000
	s_add_i32 s33, s39, 0xa000
	v_bitop3_b32 v239, v15, s0, v10 bitop3:0xde
	global_load_lds_dwordx4 v[6:7], off
	v_lshl_add_u64 v[4:5], v[4:5], 0, s[58:59]
	s_mov_b32 m0, s27
	s_add_u32 s0, s46, 0x20080
	v_bitop3_b32 v17, v15, s1, v10 bitop3:0xde
	global_load_lds_dwordx4 v[4:5], off
	v_lshl_add_u64 v[2:3], v[2:3], 0, s[58:59]
	s_mov_b32 m0, s33
	s_addc_u32 s1, s47, 0
	global_load_lds_dwordx4 v[2:3], off
	s_add_i32 m0, s39, 0x1c000
	global_load_lds_dwordx4 v220, s[0:1]
	s_add_i32 m0, s39, 0x1e000
	s_lshr_b32 s67, s82, 1
	global_load_lds_dwordx4 v0, s[0:1]
	v_readlane_b32 s0, v254, 60
	v_readlane_b32 s1, v254, 61
	s_add_u32 s68, s0, 0xdd0000
	s_waitcnt vmcnt(6)
	s_addc_u32 s69, s1, 0
	v_and_b32_e32 v0, 1, v11
	v_lshlrev_b32_e32 v1, 1, v12
	s_add_u32 s70, s0, 0x680000
	v_lshl_add_u32 v194, v0, 6, v1
	v_and_b32_e32 v0, 1, v13
	v_lshlrev_b32_e32 v1, 1, v14
	s_mov_b32 s87, s61
	s_addc_u32 s71, s1, 0
	v_or_b32_e32 v240, s3, v16
	v_lshl_add_u32 v208, v0, 6, v1
	s_movk_i32 s20, 0xb00
	s_movk_i32 s16, 0x200
	s_mov_b32 s5, 8
	s_mov_b32 s4, 0
	v_add_u32_e32 v241, 0, v17
	s_mov_b32 s52, 0
	s_barrier
	s_branch .LBB0_1154

; #define PG8_STAGE(bufoff, gbase, voff) do { _Pragma("unroll") for (int _i = 0; _i < 2; ++_i) \
;     __builtin_amdgcn_global_load_lds((const unsigned*)((const char*)(gbase) + (voff)[_i]), (LAS unsigned*)(lds + (bufoff) + ldsw + _i * 8192), 16, 0, 0); } while (0)
; #define PG8_WAIT_V(n) asm volatile("s_waitcnt vmcnt(" #n ")" ::: "memory")
; #define PG8_BAR __builtin_amdgcn_s_barrier()
; #define PG8_WAIT_V(n) asm volatile("s_waitcnt vmcnt(" #n ")" ::: "memory")
; #define PG8_BAR __builtin_amdgcn_s_barrier()
; template <class Epi>
; DI void gemm_phase(char* smem, const bf16_t* A, int lda, const bf16_t* Bt, int ldb, int K, const Order& S_, const Epi& E) {
;     ...
;   for (int i = 0; i < 2; ++i) { int R, C; stage_rc(tid * 16 + i * 8192, R, C); const int Rb = Epi::PERM ? ((R & ~31) + perm32(R & 31)) : R;
;     voffA[i] = (unsigned)(R * lda + C) * 2u; voffB[i] = (unsigned)(Rb * ldb + C) * 2u; }
;     ...
;   PG8_STAGE(PG8_SB(0, 0), cB, voffB); PG8_STAGE(PG8_SA(0, 0), cA, voffA); PG8_STAGE(PG8_SB(0, 1), cB + hstepB, voffB); PG8_STAGE(PG8_SA(0, 1), cA + hstepA, voffA);
;   if (wr == 1) PG8_BAR;
;   PG8_WAIT_V(4); PG8_BAR;
;   PG8_STAGE(PG8_SB(1, 0), cB + kstep, voffB); PG8_STAGE(PG8_SA(1, 0), cA + kstep, voffA); PG8_STAGE(PG8_SB(1, 1), cB + hstepB + kstep, voffB);
;   PG8_WAIT_V(6); PG8_BAR;
.LBB0_1693:
	v_bfe_u32 v17, v8, 4, 2
	v_and_b32_e32 v18, 15, v8
	v_lshlrev_b32_e32 v19, 4, v17
	v_lshlrev_b32_e32 v8, 2, v8
	v_lshl_or_b32 v184, s0, 6, v18
	v_lshl_or_b32 v18, v18, 6, v19
	s_lshl_b32 s0, s0, 13
	v_and_b32_e32 v8, 32, v8
	v_bitop3_b32 v19, v18, s0, v8 bitop3:0xde
	s_lshl_b32 s0, s1, 5
	s_and_b32 s3, s0, 0x60
	s_add_i32 m0, s27, 0x18000
	v_lshl_add_u64 v[6:7], v[6:7], 0, s[58:59]
	s_lshl_b32 s0, s3, 7
	s_waitcnt vmcnt(4)
	s_barrier
	global_load_lds_dwordx4 v[6:7], off
	v_lshl_add_u64 v[4:5], v[4:5], 0, s[58:59]
	s_add_i32 m0, s27, 0x1a000
	s_add_i32 s39, s27, 0x8000
	s_add_i32 s49, s27, 0xa000
	v_bitop3_b32 v185, v18, s0, v8 bitop3:0xde
	global_load_lds_dwordx4 v[4:5], off
	v_lshl_add_u64 v[2:3], v[2:3], 0, s[58:59]
	s_mov_b32 m0, s39
	s_add_u32 s0, s46, 0x40080
	global_load_lds_dwordx4 v[2:3], off
	v_lshl_add_u64 v[0:1], v[0:1], 0, s[58:59]
	s_mov_b32 m0, s49
	s_addc_u32 s1, s47, 0
	global_load_lds_dwordx4 v[0:1], off
	s_add_i32 m0, s27, 0x1c000
	global_load_lds_dwordx4 v220, s[0:1]
	s_add_i32 m0, s27, 0x1e000
	v_lshl_or_b32 v186, v17, 2, s3
	global_load_lds_dwordx4 v164, s[0:1]
	v_lshrrev_b32_e32 v1, 1, v9
	v_mul_lo_u32 v0, v11, s15
	s_mov_b32 s3, 0xb000
	v_mad_u64_u32 v[0:1], s[0:1], v1, s3, v[0:1]
	v_or_b32_e32 v0, v0, v10
	v_add_lshl_u32 v0, v0, v12, 1
	v_mov_b32_e32 v1, v221
	s_mov_b64 s[36:37], 0xb0080
	v_lshl_add_u64 v[166:167], v[0:1], 0, s[36:37]
	v_lshrrev_b32_e32 v1, 1, v13
	v_mul_lo_u32 v0, v15, s15
	v_mad_u64_u32 v[0:1], s[0:1], v1, s3, v[0:1]
	s_waitcnt vmcnt(6)
	v_or_b32_e32 v0, v0, v14
	v_add_lshl_u32 v0, v0, v16, 1
	v_mov_b32_e32 v1, v221
	s_mov_b32 s87, s61
	s_lshr_b32 s60, s82, 1
	v_lshl_add_u64 v[168:169], v[0:1], 0, s[36:37]
	s_mov_b32 s97, 0
	v_add_u32_e32 v187, 0, v19
	s_barrier
	s_branch .LBB0_1695

; #define PG8_STAGE(bufoff, gbase, voff) do { _Pragma("unroll") for (int _i = 0; _i < 2; ++_i) \
;     __builtin_amdgcn_global_load_lds((const unsigned*)((const char*)(gbase) + (voff)[_i]), (LAS unsigned*)(lds + (bufoff) + ldsw + _i * 8192), 16, 0, 0); } while (0)
; #define PG8_LDA(dst, b, h) do { _Pragma("unroll") for (int m = 0; m < 4; ++m) _Pragma("unroll") for (int k = 0; k < 2; ++k) dst[m][k] = *(const LAS bf16x8*)(lds + PG8_SA(b, h) + aoff + m * 2048 + k * 1024); } while (0)
; #define PG8_LDB(dst, b, h) do { _Pragma("unroll") for (int n = 0; n < 2; ++n) _Pragma("unroll") for (int k = 0; k < 2; ++k) dst[n][k] = *(const LAS bf16x8*)(lds + PG8_SB(b, h) + boff + n * 2048 + k * 1024); } while (0)
; #define PG8_MMA(ai, bj, At, Bt_) do { __builtin_amdgcn_s_setprio(1); _Pragma("unroll") for (int m = 0; m < 4; ++m) _Pragma("unroll") for (int n = 0; n < 2; ++n) _Pragma("unroll") for (int k = 0; k < 2; ++k) \
;     acc[ai][bj][m][n] = __builtin_amdgcn_mfma_f32_16x16x32_bf16(Bt_[n][k], At[m][k], acc[ai][bj][m][n], 0, 0, 0); __builtin_amdgcn_s_setprio(0); } while (0)
; #define PG8_WAIT_V(n) asm volatile("s_waitcnt vmcnt(" #n ")" ::: "memory")
; #define PG8_WAIT_L(n) asm volatile("s_waitcnt lgkmcnt(" #n ")" ::: "memory")
; #define PG8_BAR __builtin_amdgcn_s_barrier()
; #define PG8_SCHED __builtin_amdgcn_sched_barrier(0)
; template <class Epi>
; DI void gemm_phase(char* smem, const bf16_t* A, int lda, const bf16_t* Bt, int ldb, int K, const Order& S_, const Epi& E) {
;     ...
;     for (int t = 0; t < nt; t += 2) {
;       const bool last = (t == nt - 2);
;       const char* a1 = cA + (size_t)(t + 1) * kstep;
;       const char* a2 = last ? nA : cA + (size_t)(t + 2) * kstep; const char* b2 = last ? nB : cB + (size_t)(t + 2) * kstep;
;       const char* a3 = a2 + kstep; const char* b3 = b2 + kstep;
;       PG8_LDB(B0, 0, 0); PG8_SCHED; PG8_LDA(At, 0, 0); PG8_STAGE(PG8_SA(1, 1), a1 + hstepA, voffA);
;       PG8_WAIT_L(8); PG8_BAR; PG8_WAIT_L(0); PG8_MMA(0, 0, At, B0); PG8_BAR; PG8_SCHED;
;       PG8_LDB(B1, 0, 1); PG8_STAGE(PG8_SB(0, 0), b2, voffB);
;       PG8_BAR; PG8_WAIT_L(0); PG8_MMA(0, 1, At, B1); PG8_BAR;
;       PG8_LDA(At, 0, 1); PG8_STAGE(PG8_SA(0, 0), a2, voffA);
;       PG8_BAR; PG8_WAIT_L(0); PG8_MMA(1, 0, At, B0); PG8_BAR; PG8_SCHED;
;       PG8_STAGE(PG8_SB(0, 1), b2 + hstepB, voffB);
;       PG8_WAIT_V(6); PG8_BAR; PG8_MMA(1, 1, At, B1); PG8_BAR;
.LBB0_1701:
	s_add_u32 s0, s90, 0x100
	s_addc_u32 s1, s91, 0
	s_add_i32 s41, 0, 0x10000
	v_add_u32_e32 v76, s41, v185
	ds_read_b128 v[64:67], v76
	ds_read_b128 v[68:71], v76 offset:1024
	ds_read_b128 v[72:75], v76 offset:2048
	ds_read_b128 v[76:79], v76 offset:3072
	s_cmp_eq_u32 s29, 12
	s_cselect_b32 s51, s45, s1
	s_cselect_b32 s50, s44, s0
	s_cselect_b32 s47, s5, s20
	s_cselect_b32 s46, s15, s16
	v_lshl_add_u64 v[182:183], s[90:91], 0, v[166:167]
	s_add_i32 m0, s27, 0xc000
	ds_read_b128 v[144:147], v187
	ds_read_b128 v[148:151], v187 offset:1024
	ds_read_b128 v[152:155], v187 offset:2048
	ds_read_b128 v[156:159], v187 offset:3072
	ds_read_b128 v[170:173], v187 offset:4096
	ds_read_b128 v[174:177], v187 offset:5120
	ds_read_b128 v[178:181], v187 offset:6144
	ds_read_b128 v[188:191], v187 offset:7168
	global_load_lds_dwordx4 v[182:183], off
	v_lshl_add_u64 v[182:183], s[90:91], 0, v[168:169]
	s_add_i32 m0, s27, 0xe000
	s_nop 0
	global_load_lds_dwordx4 v[182:183], off
	s_waitcnt lgkmcnt(8)
	s_barrier
	s_waitcnt lgkmcnt(0)
	s_setprio 1
	s_waitcnt lgkmcnt(0)
	v_mfma_f32_16x16x32_bf16 v[140:143], v[64:67], v[144:147], v[140:143]
	v_mfma_f32_16x16x32_bf16 v[136:139], v[72:75], v[144:147], v[136:139]
	v_mfma_f32_16x16x32_bf16 v[132:135], v[64:67], v[152:155], v[132:135]
	v_mfma_f32_16x16x32_bf16 v[124:127], v[72:75], v[152:155], v[124:127]
	v_mfma_f32_16x16x32_bf16 v[108:111], v[64:67], v[170:173], v[108:111]
	v_mfma_f32_16x16x32_bf16 v[104:107], v[72:75], v[170:173], v[104:107]
	v_mfma_f32_16x16x32_bf16 v[100:103], v[64:67], v[178:181], v[100:103]
	v_mfma_f32_16x16x32_bf16 v[92:95], v[72:75], v[178:181], v[92:95]
	v_mfma_f32_16x16x32_bf16 v[140:143], v[68:71], v[148:151], v[140:143]
	v_mfma_f32_16x16x32_bf16 v[136:139], v[76:79], v[148:151], v[136:139]
	v_mfma_f32_16x16x32_bf16 v[132:135], v[68:71], v[156:159], v[132:135]
	v_mfma_f32_16x16x32_bf16 v[124:127], v[76:79], v[156:159], v[124:127]
	v_mfma_f32_16x16x32_bf16 v[108:111], v[68:71], v[174:177], v[108:111]
	v_mfma_f32_16x16x32_bf16 v[104:107], v[76:79], v[174:177], v[104:107]
	v_mfma_f32_16x16x32_bf16 v[100:103], v[68:71], v[188:191], v[100:103]
	v_mfma_f32_16x16x32_bf16 v[92:95], v[76:79], v[188:191], v[92:95]
	s_setprio 0
	s_barrier
	s_add_i32 s43, 0, 0x14000
	v_add_u32_e32 v182, s43, v185
	s_add_i32 s41, s41, s26
	ds_read_b128 v[210:213], v182
	ds_read_b128 v[214:217], v182 offset:1024
	ds_read_b128 v[234:237], v182 offset:2048
	ds_read_b128 v[238:241], v182 offset:3072
	v_lshl_add_u64 v[182:183], s[46:47], 0, v[220:221]
	s_mov_b32 m0, s41
	v_lshl_add_u64 v[194:195], s[46:47], 0, v[164:165]
	global_load_lds_dwordx4 v[182:183], off
	s_add_i32 m0, s41, 0x2000
	s_nop 0
	global_load_lds_dwordx4 v[194:195], off
	s_barrier
	s_waitcnt lgkmcnt(0)
	s_setprio 1
	s_waitcnt lgkmcnt(0)
	v_mfma_f32_16x16x32_bf16 v[128:131], v[210:213], v[144:147], v[128:131]
	v_mfma_f32_16x16x32_bf16 v[120:123], v[234:237], v[144:147], v[120:123]
	v_mfma_f32_16x16x32_bf16 v[116:119], v[210:213], v[152:155], v[116:119]
	v_mfma_f32_16x16x32_bf16 v[112:115], v[234:237], v[152:155], v[112:115]
	v_mfma_f32_16x16x32_bf16 v[96:99], v[210:213], v[170:173], v[96:99]
	v_mfma_f32_16x16x32_bf16 v[88:91], v[234:237], v[170:173], v[88:91]
	v_mfma_f32_16x16x32_bf16 v[84:87], v[210:213], v[178:181], v[84:87]
	v_mfma_f32_16x16x32_bf16 v[80:83], v[234:237], v[178:181], v[80:83]
	v_mfma_f32_16x16x32_bf16 v[128:131], v[214:217], v[148:151], v[128:131]
	v_mfma_f32_16x16x32_bf16 v[120:123], v[238:241], v[148:151], v[120:123]
	v_mfma_f32_16x16x32_bf16 v[116:119], v[214:217], v[156:159], v[116:119]
	v_mfma_f32_16x16x32_bf16 v[112:115], v[238:241], v[156:159], v[112:115]
	v_mfma_f32_16x16x32_bf16 v[96:99], v[214:217], v[174:177], v[96:99]
	v_mfma_f32_16x16x32_bf16 v[88:91], v[238:241], v[174:177], v[88:91]
	v_mfma_f32_16x16x32_bf16 v[84:87], v[214:217], v[188:191], v[84:87]
	v_mfma_f32_16x16x32_bf16 v[80:83], v[238:241], v[188:191], v[80:83]
	s_setprio 0
	s_mov_b32 m0, s27
	v_lshl_add_u64 v[200:201], s[50:51], 0, v[160:161]
	s_barrier
	ds_read_b128 v[144:147], v187 offset:16384
	ds_read_b128 v[148:151], v187 offset:17408
	ds_read_b128 v[152:155], v187 offset:18432
	ds_read_b128 v[156:159], v187 offset:19456
	ds_read_b128 v[170:173], v187 offset:20480
	ds_read_b128 v[174:177], v187 offset:21504
	ds_read_b128 v[178:181], v187 offset:22528
	ds_read_b128 v[188:191], v187 offset:23552
	global_load_lds_dwordx4 v[200:201], off
	v_lshl_add_u64 v[202:203], s[50:51], 0, v[162:163]
	s_mov_b32 m0, s33
	s_nop 0
	global_load_lds_dwordx4 v[202:203], off
	s_barrier
	s_waitcnt lgkmcnt(0)
	s_setprio 1
	s_waitcnt lgkmcnt(0)
	v_mfma_f32_16x16x32_bf16 v[60:63], v[64:67], v[144:147], v[60:63]
	v_mfma_f32_16x16x32_bf16 v[56:59], v[72:75], v[144:147], v[56:59]
	v_mfma_f32_16x16x32_bf16 v[52:55], v[64:67], v[152:155], v[52:55]
	v_mfma_f32_16x16x32_bf16 v[44:47], v[72:75], v[152:155], v[44:47]
	v_mfma_f32_16x16x32_bf16 v[28:31], v[64:67], v[170:173], v[28:31]
	v_mfma_f32_16x16x32_bf16 v[24:27], v[72:75], v[170:173], v[24:27]
	v_mfma_f32_16x16x32_bf16 v[20:23], v[64:67], v[178:181], v[20:23]
	v_mfma_f32_16x16x32_bf16 v[12:15], v[72:75], v[178:181], v[12:15]
	v_mfma_f32_16x16x32_bf16 v[60:63], v[68:71], v[148:151], v[60:63]
	v_mfma_f32_16x16x32_bf16 v[56:59], v[76:79], v[148:151], v[56:59]
	v_mfma_f32_16x16x32_bf16 v[52:55], v[68:71], v[156:159], v[52:55]
	v_mfma_f32_16x16x32_bf16 v[44:47], v[76:79], v[156:159], v[44:47]
	v_mfma_f32_16x16x32_bf16 v[28:31], v[68:71], v[174:177], v[28:31]
	v_mfma_f32_16x16x32_bf16 v[24:27], v[76:79], v[174:177], v[24:27]
	v_mfma_f32_16x16x32_bf16 v[20:23], v[68:71], v[188:191], v[20:23]
	v_mfma_f32_16x16x32_bf16 v[12:15], v[76:79], v[188:191], v[12:15]
	s_setprio 0
	s_barrier
; #define PG8_STAGE(bufoff, gbase, voff) do { _Pragma("unroll") for (int _i = 0; _i < 2; ++_i) \
;     __builtin_amdgcn_global_load_lds((const unsigned*)((const char*)(gbase) + (voff)[_i]), (LAS unsigned*)(lds + (bufoff) + ldsw + _i * 8192), 16, 0, 0); } while (0)
; #define PG8_LDA(dst, b, h) do { _Pragma("unroll") for (int m = 0; m < 4; ++m) _Pragma("unroll") for (int k = 0; k < 2; ++k) dst[m][k] = *(const LAS bf16x8*)(lds + PG8_SA(b, h) + aoff + m * 2048 + k * 1024); } while (0)
; #define PG8_LDB(dst, b, h) do { _Pragma("unroll") for (int n = 0; n < 2; ++n) _Pragma("unroll") for (int k = 0; k < 2; ++k) dst[n][k] = *(const LAS bf16x8*)(lds + PG8_SB(b, h) + boff + n * 2048 + k * 1024); } while (0)
; #define PG8_MMA(ai, bj, At, Bt_) do { __builtin_amdgcn_s_setprio(1); _Pragma("unroll") for (int m = 0; m < 4; ++m) _Pragma("unroll") for (int n = 0; n < 2; ++n) _Pragma("unroll") for (int k = 0; k < 2; ++k) \
;     acc[ai][bj][m][n] = __builtin_amdgcn_mfma_f32_16x16x32_bf16(Bt_[n][k], At[m][k], acc[ai][bj][m][n], 0, 0, 0); __builtin_amdgcn_s_setprio(0); } while (0)
; #define PG8_WAIT_V(n) asm volatile("s_waitcnt vmcnt(" #n ")" ::: "memory")
; #define PG8_WAIT_L(n) asm volatile("s_waitcnt lgkmcnt(" #n ")" ::: "memory")
; #define PG8_BAR __builtin_amdgcn_s_barrier()
; #define PG8_SCHED __builtin_amdgcn_sched_barrier(0)
; #define PG8_LDA(dst, b, h) do { _Pragma("unroll") for (int m = 0; m < 4; ++m) _Pragma("unroll") for (int k = 0; k < 2; ++k) dst[m][k] = *(const LAS bf16x8*)(lds + PG8_SA(b, h) + aoff + m * 2048 + k * 1024); } while (0)
; #define PG8_WAIT_V(n) asm volatile("s_waitcnt vmcnt(" #n ")" ::: "memory")
; template <class Epi>
; DI void gemm_phase(char* smem, const bf16_t* A, int lda, const bf16_t* Bt, int ldb, int K, const Order& S_, const Epi& E) {
;     ...
;       PG8_STAGE(PG8_SB(0, 1), b2 + hstepB, voffB);
;       PG8_WAIT_V(6); PG8_BAR; PG8_MMA(1, 1, At, B1); PG8_BAR;
;       PG8_LDB(B0, 1, 0); PG8_SCHED; PG8_LDA(At, 1, 0); PG8_STAGE(PG8_SA(0, 1), a2 + hstepA, voffA);
;       PG8_WAIT_L(8); PG8_BAR; PG8_WAIT_L(0); PG8_MMA(0, 0, At, B0); PG8_BAR; PG8_SCHED;
;       PG8_LDB(B1, 1, 1); PG8_STAGE(PG8_SB(1, 0), b3, voffB);
;       PG8_BAR; PG8_WAIT_L(0); PG8_MMA(0, 1, At, B1); PG8_BAR;
;       PG8_LDA(At, 1, 1); PG8_STAGE(PG8_SA(1, 0), a3, voffA);
;       PG8_BAR; PG8_WAIT_L(0); PG8_MMA(1, 0, At, B0); PG8_BAR; PG8_SCHED;
	s_add_u32 s52, s46, 0x40000
	s_addc_u32 s53, s47, 0
	s_add_i32 s41, s43, s26
	s_mov_b32 m0, s41
	s_nop 0
	global_load_lds_dwordx4 v220, s[52:53]
	s_add_i32 m0, s41, 0x2000
	s_nop 0
	global_load_lds_dwordx4 v164, s[52:53]
	s_waitcnt vmcnt(6)
	s_barrier
	s_setprio 1
	v_mfma_f32_16x16x32_bf16 v[48:51], v[210:213], v[144:147], v[48:51]
	v_mfma_f32_16x16x32_bf16 v[40:43], v[234:237], v[144:147], v[40:43]
	v_mfma_f32_16x16x32_bf16 v[36:39], v[210:213], v[152:155], v[36:39]
	v_mfma_f32_16x16x32_bf16 v[32:35], v[234:237], v[152:155], v[32:35]
	v_mfma_f32_16x16x32_bf16 v[16:19], v[210:213], v[170:173], v[16:19]
	v_mfma_f32_16x16x32_bf16 v[8:11], v[234:237], v[170:173], v[8:11]
	v_mfma_f32_16x16x32_bf16 v[4:7], v[210:213], v[178:181], v[4:7]
	v_mfma_f32_16x16x32_bf16 v[0:3], v[234:237], v[178:181], v[0:3]
	v_mfma_f32_16x16x32_bf16 v[48:51], v[214:217], v[148:151], v[48:51]
	v_mfma_f32_16x16x32_bf16 v[40:43], v[238:241], v[148:151], v[40:43]
	v_mfma_f32_16x16x32_bf16 v[36:39], v[214:217], v[156:159], v[36:39]
	v_mfma_f32_16x16x32_bf16 v[32:35], v[238:241], v[156:159], v[32:35]
	v_mfma_f32_16x16x32_bf16 v[16:19], v[214:217], v[174:177], v[16:19]
	v_mfma_f32_16x16x32_bf16 v[8:11], v[238:241], v[174:177], v[8:11]
	v_mfma_f32_16x16x32_bf16 v[4:7], v[214:217], v[188:191], v[4:7]
	v_mfma_f32_16x16x32_bf16 v[0:3], v[238:241], v[188:191], v[0:3]
	s_setprio 0
	s_add_i32 s41, 0, 0x18000
	v_add_u32_e32 v76, s41, v185
	s_barrier
	ds_read_b128 v[64:67], v76
	ds_read_b128 v[68:71], v76 offset:1024
	ds_read_b128 v[72:75], v76 offset:2048
	ds_read_b128 v[76:79], v76 offset:3072
	s_add_u32 s50, s50, 0xb0000
	s_addc_u32 s51, s51, 0
	s_mov_b32 m0, s34
	ds_read_b128 v[144:147], v187 offset:32768
	ds_read_b128 v[148:151], v187 offset:33792
	ds_read_b128 v[152:155], v187 offset:34816
	ds_read_b128 v[156:159], v187 offset:35840
	ds_read_b128 v[170:173], v187 offset:36864
	ds_read_b128 v[174:177], v187 offset:37888
	ds_read_b128 v[178:181], v187 offset:38912
	ds_read_b128 v[188:191], v187 offset:39936
	global_load_lds_dwordx4 v160, s[50:51]
	s_mov_b32 m0, s38
	s_nop 0
	global_load_lds_dwordx4 v162, s[50:51]
	s_waitcnt lgkmcnt(8)
	s_barrier
	s_waitcnt lgkmcnt(0)
	s_setprio 1
	s_waitcnt lgkmcnt(0)
	v_mfma_f32_16x16x32_bf16 v[140:143], v[64:67], v[144:147], v[140:143]
	v_mfma_f32_16x16x32_bf16 v[136:139], v[72:75], v[144:147], v[136:139]
	v_mfma_f32_16x16x32_bf16 v[132:135], v[64:67], v[152:155], v[132:135]
	v_mfma_f32_16x16x32_bf16 v[124:127], v[72:75], v[152:155], v[124:127]
	v_mfma_f32_16x16x32_bf16 v[108:111], v[64:67], v[170:173], v[108:111]
	v_mfma_f32_16x16x32_bf16 v[104:107], v[72:75], v[170:173], v[104:107]
	v_mfma_f32_16x16x32_bf16 v[100:103], v[64:67], v[178:181], v[100:103]
	v_mfma_f32_16x16x32_bf16 v[92:95], v[72:75], v[178:181], v[92:95]
	v_mfma_f32_16x16x32_bf16 v[140:143], v[68:71], v[148:151], v[140:143]
	v_mfma_f32_16x16x32_bf16 v[136:139], v[76:79], v[148:151], v[136:139]
	v_mfma_f32_16x16x32_bf16 v[132:135], v[68:71], v[156:159], v[132:135]
	v_mfma_f32_16x16x32_bf16 v[124:127], v[76:79], v[156:159], v[124:127]
	v_mfma_f32_16x16x32_bf16 v[108:111], v[68:71], v[174:177], v[108:111]
	v_mfma_f32_16x16x32_bf16 v[104:107], v[76:79], v[174:177], v[104:107]
	v_mfma_f32_16x16x32_bf16 v[100:103], v[68:71], v[188:191], v[100:103]
	v_mfma_f32_16x16x32_bf16 v[92:95], v[76:79], v[188:191], v[92:95]
	s_setprio 0
	s_barrier
	s_add_i32 s43, 0, 0x1c000
	s_add_i32 s41, s41, s26
	v_add_u32_e32 v204, s43, v185
	v_lshl_add_u64 v[182:183], v[182:183], 0, s[58:59]
	s_mov_b32 m0, s41
	ds_read_b128 v[210:213], v204
	ds_read_b128 v[214:217], v204 offset:1024
	ds_read_b128 v[234:237], v204 offset:2048
	ds_read_b128 v[238:241], v204 offset:3072
	global_load_lds_dwordx4 v[182:183], off
	v_lshl_add_u64 v[182:183], v[194:195], 0, s[58:59]
	s_add_i32 m0, s41, 0x2000
	s_nop 0
	global_load_lds_dwordx4 v[182:183], off
	s_barrier
	s_waitcnt lgkmcnt(0)
	s_setprio 1
	s_waitcnt lgkmcnt(0)
	v_mfma_f32_16x16x32_bf16 v[128:131], v[210:213], v[144:147], v[128:131]
	v_mfma_f32_16x16x32_bf16 v[120:123], v[234:237], v[144:147], v[120:123]
	v_mfma_f32_16x16x32_bf16 v[116:119], v[210:213], v[152:155], v[116:119]
	v_mfma_f32_16x16x32_bf16 v[112:115], v[234:237], v[152:155], v[112:115]
	v_mfma_f32_16x16x32_bf16 v[96:99], v[210:213], v[170:173], v[96:99]
	v_mfma_f32_16x16x32_bf16 v[88:91], v[234:237], v[170:173], v[88:91]
	v_mfma_f32_16x16x32_bf16 v[84:87], v[210:213], v[178:181], v[84:87]
	v_mfma_f32_16x16x32_bf16 v[80:83], v[234:237], v[178:181], v[80:83]
	v_mfma_f32_16x16x32_bf16 v[128:131], v[214:217], v[148:151], v[128:131]
	v_mfma_f32_16x16x32_bf16 v[120:123], v[238:241], v[148:151], v[120:123]
	v_mfma_f32_16x16x32_bf16 v[116:119], v[214:217], v[156:159], v[116:119]
	v_mfma_f32_16x16x32_bf16 v[112:115], v[238:241], v[156:159], v[112:115]
	v_mfma_f32_16x16x32_bf16 v[96:99], v[214:217], v[174:177], v[96:99]
	v_mfma_f32_16x16x32_bf16 v[88:91], v[238:241], v[174:177], v[88:91]
	v_mfma_f32_16x16x32_bf16 v[84:87], v[214:217], v[188:191], v[84:87]
	v_mfma_f32_16x16x32_bf16 v[80:83], v[238:241], v[188:191], v[80:83]
	s_setprio 0
	s_mov_b32 m0, s39
	v_lshl_add_u64 v[182:183], v[200:201], 0, s[58:59]
	s_barrier
; #define MEMBAR() asm volatile("" ::: "memory")
; DI float* modp(const Params& p, int layer, int g, int chunk) { return (float*)(p.ws + OFF_MOD) + ((size_t)(layer * 9 + g) * 6 + chunk) * 1024; }
; #define PG8_STAGE(bufoff, gbase, voff) do { _Pragma("unroll") for (int _i = 0; _i < 2; ++_i) \
;     __builtin_amdgcn_global_load_lds((const unsigned*)((const char*)(gbase) + (voff)[_i]), (LAS unsigned*)(lds + (bufoff) + ldsw + _i * 8192), 16, 0, 0); } while (0)
; #define PG8_MMA(ai, bj, At, Bt_) do { __builtin_amdgcn_s_setprio(1); _Pragma("unroll") for (int m = 0; m < 4; ++m) _Pragma("unroll") for (int n = 0; n < 2; ++n) _Pragma("unroll") for (int k = 0; k < 2; ++k) \
;     acc[ai][bj][m][n] = __builtin_amdgcn_mfma_f32_16x16x32_bf16(Bt_[n][k], At[m][k], acc[ai][bj][m][n], 0, 0, 0); __builtin_amdgcn_s_setprio(0); } while (0)
; #define PG8_WAIT_V(n) asm volatile("s_waitcnt vmcnt(" #n ")" ::: "memory")
; #define PG8_BAR __builtin_amdgcn_s_barrier()
; #define PG8_WAIT_V(n) asm volatile("s_waitcnt vmcnt(" #n ")" ::: "memory")
; #define PG8_BAR __builtin_amdgcn_s_barrier()
; template <class Epi>
; DI void gemm_phase(char* smem, const bf16_t* A, int lda, const bf16_t* Bt, int ldb, int K, const Order& S_, const Epi& E) {
;     ...
;       PG8_STAGE(PG8_SB(1, 1), b3 + hstepB, voffB);
;       PG8_WAIT_V(6); PG8_BAR; PG8_MMA(1, 1, At, B1); PG8_BAR;
;     }
;     E(acc, cur, wr, wc, fr, fq);
;   DI void operator()(const acc_t& acc, const Unit& u, int wr, int wc, int fr, int fq) const {
;     const int row0 = u.pm * BM + wr * 64 + fr, col0 = u.pn * BM + wc * 32 + 4 * fq;
;     const int b = u.pm / 17, g = (u.pm - b * 17) == 0 ? 8 : b;
;     const float* gate = modp(p, layer, g, chunk);
;     f32x4 gv[2][2];
; #pragma unroll
;     for (int bj = 0; bj < 2; ++bj)
; #pragma unroll
;       for (int n = 0; n < 2; ++n) gv[bj][n] = *(const f32x4*)(gate + col0 + bj * HALF + n * 16);
; #pragma unroll
;     for (int q = 0; q < 4; ++q) {
;       const int ai = q >> 1, mh = q & 1;
;       MEMBAR();
;       f32x4 xv[2][2][2];
; #pragma unroll
;       for (int mm = 0; mm < 2; ++mm) { const int t = row0 + ai * HALF + (2 * mh + mm) * 16;
;         const float* xi = from_input ? xrow_in(p, t) : xrow_ws(p, t);
	ds_read_b128 v[144:147], v187 offset:49152
	ds_read_b128 v[148:151], v187 offset:50176
	ds_read_b128 v[152:155], v187 offset:51200
	ds_read_b128 v[156:159], v187 offset:52224
	ds_read_b128 v[170:173], v187 offset:53248
	ds_read_b128 v[174:177], v187 offset:54272
	ds_read_b128 v[178:181], v187 offset:55296
	ds_read_b128 v[188:191], v187 offset:56320
	global_load_lds_dwordx4 v[182:183], off
	v_lshl_add_u64 v[182:183], v[202:203], 0, s[58:59]
	s_mov_b32 m0, s49
	s_nop 0
	global_load_lds_dwordx4 v[182:183], off
	s_barrier
	s_waitcnt lgkmcnt(0)
	s_setprio 1
	s_waitcnt lgkmcnt(0)
	v_mfma_f32_16x16x32_bf16 v[60:63], v[64:67], v[144:147], v[60:63]
	v_mfma_f32_16x16x32_bf16 v[56:59], v[72:75], v[144:147], v[56:59]
	v_mfma_f32_16x16x32_bf16 v[52:55], v[64:67], v[152:155], v[52:55]
	v_mfma_f32_16x16x32_bf16 v[44:47], v[72:75], v[152:155], v[44:47]
	v_mfma_f32_16x16x32_bf16 v[28:31], v[64:67], v[170:173], v[28:31]
	v_mfma_f32_16x16x32_bf16 v[24:27], v[72:75], v[170:173], v[24:27]
	v_mfma_f32_16x16x32_bf16 v[20:23], v[64:67], v[178:181], v[20:23]
	v_mfma_f32_16x16x32_bf16 v[12:15], v[72:75], v[178:181], v[12:15]
	v_mfma_f32_16x16x32_bf16 v[60:63], v[68:71], v[148:151], v[60:63]
	v_mfma_f32_16x16x32_bf16 v[56:59], v[76:79], v[148:151], v[56:59]
	v_mfma_f32_16x16x32_bf16 v[52:55], v[68:71], v[156:159], v[52:55]
	v_mfma_f32_16x16x32_bf16 v[44:47], v[76:79], v[156:159], v[44:47]
	v_mfma_f32_16x16x32_bf16 v[28:31], v[68:71], v[174:177], v[28:31]
	v_mfma_f32_16x16x32_bf16 v[24:27], v[76:79], v[174:177], v[24:27]
	v_mfma_f32_16x16x32_bf16 v[20:23], v[68:71], v[188:191], v[20:23]
	v_mfma_f32_16x16x32_bf16 v[12:15], v[76:79], v[188:191], v[12:15]
	s_setprio 0
	s_barrier
	s_add_u32 s46, s46, 0x40080
	s_addc_u32 s47, s47, 0
	s_add_i32 s41, s43, s26
	s_mov_b32 m0, s41
	s_nop 0
	global_load_lds_dwordx4 v220, s[46:47]
	s_add_i32 m0, s41, 0x2000
	s_nop 0
	global_load_lds_dwordx4 v164, s[46:47]
	s_waitcnt vmcnt(6)
	s_barrier
	s_setprio 1
	v_mfma_f32_16x16x32_bf16 v[48:51], v[210:213], v[144:147], v[48:51]
	v_mfma_f32_16x16x32_bf16 v[40:43], v[234:237], v[144:147], v[40:43]
	v_mfma_f32_16x16x32_bf16 v[36:39], v[210:213], v[152:155], v[36:39]
	v_mfma_f32_16x16x32_bf16 v[32:35], v[234:237], v[152:155], v[32:35]
	v_mfma_f32_16x16x32_bf16 v[16:19], v[210:213], v[170:173], v[16:19]
	v_mfma_f32_16x16x32_bf16 v[8:11], v[234:237], v[170:173], v[8:11]
	v_mfma_f32_16x16x32_bf16 v[4:7], v[210:213], v[178:181], v[4:7]
	v_mfma_f32_16x16x32_bf16 v[0:3], v[234:237], v[178:181], v[0:3]
	v_mfma_f32_16x16x32_bf16 v[48:51], v[214:217], v[148:151], v[48:51]
	v_mfma_f32_16x16x32_bf16 v[40:43], v[238:241], v[148:151], v[40:43]
	v_mfma_f32_16x16x32_bf16 v[36:39], v[214:217], v[156:159], v[36:39]
	v_mfma_f32_16x16x32_bf16 v[32:35], v[238:241], v[156:159], v[32:35]
	v_mfma_f32_16x16x32_bf16 v[16:19], v[214:217], v[174:177], v[16:19]
	v_mfma_f32_16x16x32_bf16 v[8:11], v[238:241], v[174:177], v[8:11]
	v_mfma_f32_16x16x32_bf16 v[4:7], v[214:217], v[188:191], v[4:7]
	v_mfma_f32_16x16x32_bf16 v[0:3], v[238:241], v[188:191], v[0:3]
	s_setprio 0
	s_add_i32 s29, s29, 2
	s_add_u32 s16, s16, 0x100
	s_addc_u32 s20, s20, 0
	s_cmp_gt_u32 s29, 13
	s_mov_b64 s[90:91], s[0:1]
	s_barrier
	s_cbranch_scc0 .LBB0_1701
	s_mul_hi_i32 s0, s4, 0x78787879
	s_lshr_b32 s1, s0, 31
	s_ashr_i32 s0, s0, 3
	s_add_i32 s0, s0, s1
	s_mul_i32 s1, s0, 0xffffffef
	s_sub_i32 s5, 0, s4
	s_cmp_lg_u32 s1, s5
	s_cselect_b32 s0, s0, 8
	v_readlane_b32 s1, v254, 59
	s_add_i32 s0, s0, s1
	s_mul_i32 s0, s0, 6
	s_ashr_i32 s1, s0, 31
	s_lshl_b64 s[0:1], s[0:1], 12
	v_readlane_b32 s5, v253, 27
	v_lshl_or_b32 v172, s42, 8, v186
	s_add_u32 s0, s5, s0
	v_readlane_b32 s5, v253, 28
	s_addc_u32 s1, s5, s1
	v_ashrrev_i32_e32 v173, 31, v172
	v_lshl_add_u64 v[64:65], v[172:173], 2, s[0:1]
	global_load_dwordx4 v[76:79], v[64:65], off
	global_load_dwordx4 v[72:75], v[64:65], off offset:64
	global_load_dwordx4 v[68:71], v[64:65], off offset:512
	s_nop 0
	global_load_dwordx4 v[64:67], v[64:65], off offset:576
	v_lshl_add_u32 v188, s4, 8, v184
	s_mov_b32 s51, 0x78787879
	v_mul_hi_i32 v144, v188, s51
	v_lshrrev_b32_e32 v145, 31, v144
	v_ashrrev_i32_e32 v144, 11, v144
	v_add_u32_e32 v144, v144, v145
	s_movk_i32 s4, 0xef00
	v_mad_i32_i24 v145, v144, s4, v188
	v_readlane_b32 s90, v254, 51
	s_movk_i32 s50, 0x100
	v_readlane_b32 s91, v254, 52
	v_ashrrev_i32_e32 v146, 31, v145
	v_add_u32_e32 v147, 0xffffff00, v145
	v_cmp_gt_i32_e64 s[0:1], s50, v145
	s_mov_b64 s[42:43], -1
	s_and_b64 vcc, exec, s[90:91]
	v_cndmask_b32_e64 v175, 0, v146, s[0:1]
	v_cndmask_b32_e64 v174, v147, v145, s[0:1]
	v_readlane_b32 s29, v254, 42
	s_cbranch_vccz .LBB0_1704
	v_mov_b32_e32 v145, s93
	v_mov_b32_e32 v146, s83
	v_cndmask_b32_e64 v147, v145, v146, s[0:1]
	v_mov_b32_e32 v145, s92
	v_mov_b32_e32 v146, s29
	v_cndmask_b32_e64 v146, v145, v146, s[0:1]
	s_mov_b64 s[42:43], 0

; #define PG8_STAGE(bufoff, gbase, voff) do { _Pragma("unroll") for (int _i = 0; _i < 2; ++_i) \
;     __builtin_amdgcn_global_load_lds((const unsigned*)((const char*)(gbase) + (voff)[_i]), (LAS unsigned*)(lds + (bufoff) + ldsw + _i * 8192), 16, 0, 0); } while (0)
; #define PG8_WAIT_V(n) asm volatile("s_waitcnt vmcnt(" #n ")" ::: "memory")
; #define PG8_BAR __builtin_amdgcn_s_barrier()
; #define PG8_WAIT_V(n) asm volatile("s_waitcnt vmcnt(" #n ")" ::: "memory")
; #define PG8_BAR __builtin_amdgcn_s_barrier()
; template <class Epi>
; DI void gemm_phase(char* smem, const bf16_t* A, int lda, const bf16_t* Bt, int ldb, int K, const Order& S_, const Epi& E) {
;     ...
;   for (int i = 0; i < 2; ++i) { int R, C; stage_rc(tid * 16 + i * 8192, R, C); const int Rb = Epi::PERM ? ((R & ~31) + perm32(R & 31)) : R;
;     voffA[i] = (unsigned)(R * lda + C) * 2u; voffB[i] = (unsigned)(Rb * ldb + C) * 2u; }
;     ...
;   PG8_STAGE(PG8_SB(0, 0), cB, voffB); PG8_STAGE(PG8_SA(0, 0), cA, voffA); PG8_STAGE(PG8_SB(0, 1), cB + hstepB, voffB); PG8_STAGE(PG8_SA(0, 1), cA + hstepA, voffA);
;   if (wr == 1) PG8_BAR;
;   PG8_WAIT_V(4); PG8_BAR;
;   PG8_STAGE(PG8_SB(1, 0), cB + kstep, voffB); PG8_STAGE(PG8_SA(1, 0), cA + kstep, voffA); PG8_STAGE(PG8_SB(1, 1), cB + hstepB + kstep, voffB);
;   PG8_WAIT_V(6); PG8_BAR;
.LBB0_1853:
	v_lshrrev_b32_e32 v16, 1, v1
	v_and_b32_e32 v16, 24, v16
	v_and_b32_e32 v7, 15, v1
	v_lshlrev_b32_e32 v17, 1, v16
	v_lshlrev_b32_e32 v1, 2, v1
	v_lshl_or_b32 v138, s4, 6, v7
	v_lshl_or_b32 v7, v7, 6, v17
	s_lshl_b32 s4, s4, 13
	v_and_b32_e32 v1, 32, v1
	v_lshl_add_u64 v[8:9], s[88:89], 0, v[220:221]
	v_mov_b32_e32 v133, v221
	v_bitop3_b32 v17, v7, s4, v1 bitop3:0xde
	s_lshl_b32 s4, s5, 5
	v_lshl_add_u64 v[10:11], s[88:89], 0, v[132:133]
	v_mov_b32_e32 v129, v221
	s_and_b32 s15, s4, 0x60
	s_add_i32 m0, s1, 0x18000
	v_lshl_add_u64 v[8:9], v[8:9], 0, s[58:59]
	s_waitcnt vmcnt(0)
	v_lshl_add_u64 v[12:13], s[42:43], 0, v[128:129]
	v_mov_b32_e32 v131, v221
	s_lshl_b32 s4, s15, 7
	s_waitcnt vmcnt(4)
	s_barrier
	global_load_lds_dwordx4 v[8:9], off
	v_lshl_add_u64 v[8:9], v[10:11], 0, s[58:59]
	s_add_i32 m0, s1, 0x1a000
	s_add_i32 s47, s1, 0x8000
	s_add_i32 s49, s1, 0xa000
	v_lshl_add_u64 v[14:15], s[42:43], 0, v[130:131]
	v_bitop3_b32 v139, v7, s4, v1 bitop3:0xde
	global_load_lds_dwordx4 v[8:9], off
	v_lshl_add_u64 v[8:9], v[12:13], 0, s[58:59]
	s_mov_b32 m0, s47
	s_add_u32 s4, s88, 0x40080
	global_load_lds_dwordx4 v[8:9], off
	v_lshl_add_u64 v[8:9], v[14:15], 0, s[58:59]
	s_mov_b32 m0, s49
	s_addc_u32 s5, s89, 0
	global_load_lds_dwordx4 v[8:9], off
	s_add_i32 m0, s1, 0x1c000
	global_load_lds_dwordx4 v220, s[4:5]
	s_add_i32 m0, s1, 0x1e000
	v_lshlrev_b32_e32 v1, 14, v0
	global_load_lds_dwordx4 v132, s[4:5]
	v_and_b32_e32 v1, 0xffff8000, v1
	v_lshl_add_u32 v1, v2, 11, v1
	v_and_b32_e32 v0, 1, v0
	v_lshl_or_b32 v0, v0, 6, v1
	v_lshl_add_u32 v134, v3, 1, v0
	v_lshlrev_b32_e32 v0, 14, v4
	v_and_b32_e32 v0, 0xffff8000, v0
	s_waitcnt vmcnt(6)
	v_lshl_add_u32 v0, v5, 11, v0
	v_and_b32_e32 v1, 1, v4
	v_lshl_or_b32 v0, v1, 6, v0
	v_or_b32_e32 v140, s15, v16
	v_mov_b32_e32 v135, v221
	v_lshl_add_u32 v136, v6, 1, v0
	v_mov_b32_e32 v137, v221
	s_mov_b32 s97, 0
	v_add_u32_e32 v141, 0, v17
	s_barrier

; #define PG8_STAGE(bufoff, gbase, voff) do { _Pragma("unroll") for (int _i = 0; _i < 2; ++_i) \
;     __builtin_amdgcn_global_load_lds((const unsigned*)((const char*)(gbase) + (voff)[_i]), (LAS unsigned*)(lds + (bufoff) + ldsw + _i * 8192), 16, 0, 0); } while (0)
; #define PG8_LDA(dst, b, h) do { _Pragma("unroll") for (int m = 0; m < 4; ++m) _Pragma("unroll") for (int k = 0; k < 2; ++k) dst[m][k] = *(const LAS bf16x8*)(lds + PG8_SA(b, h) + aoff + m * 2048 + k * 1024); } while (0)
; #define PG8_LDB(dst, b, h) do { _Pragma("unroll") for (int n = 0; n < 2; ++n) _Pragma("unroll") for (int k = 0; k < 2; ++k) dst[n][k] = *(const LAS bf16x8*)(lds + PG8_SB(b, h) + boff + n * 2048 + k * 1024); } while (0)
; #define PG8_MMA(ai, bj, At, Bt_) do { __builtin_amdgcn_s_setprio(1); _Pragma("unroll") for (int m = 0; m < 4; ++m) _Pragma("unroll") for (int n = 0; n < 2; ++n) _Pragma("unroll") for (int k = 0; k < 2; ++k) \
;     acc[ai][bj][m][n] = __builtin_amdgcn_mfma_f32_16x16x32_bf16(Bt_[n][k], At[m][k], acc[ai][bj][m][n], 0, 0, 0); __builtin_amdgcn_s_setprio(0); } while (0)
; #define PG8_WAIT_V(n) asm volatile("s_waitcnt vmcnt(" #n ")" ::: "memory")
; #define PG8_WAIT_L(n) asm volatile("s_waitcnt lgkmcnt(" #n ")" ::: "memory")
; #define PG8_BAR __builtin_amdgcn_s_barrier()
; #define PG8_SCHED __builtin_amdgcn_sched_barrier(0)
; #define PG8_LDA(dst, b, h) do { _Pragma("unroll") for (int m = 0; m < 4; ++m) _Pragma("unroll") for (int k = 0; k < 2; ++k) dst[m][k] = *(const LAS bf16x8*)(lds + PG8_SA(b, h) + aoff + m * 2048 + k * 1024); } while (0)
; #define PG8_WAIT_V(n) asm volatile("s_waitcnt vmcnt(" #n ")" ::: "memory")
; template <class Epi>
; DI void gemm_phase(char* smem, const bf16_t* A, int lda, const bf16_t* Bt, int ldb, int K, const Order& S_, const Epi& E) {
;     ...
;       PG8_LDB(B0, 0, 0); PG8_SCHED; PG8_LDA(At, 0, 0); PG8_STAGE(PG8_SA(1, 1), a1 + hstepA, voffA);
;       PG8_WAIT_L(8); PG8_BAR; PG8_WAIT_L(0); PG8_MMA(0, 0, At, B0); PG8_BAR; PG8_SCHED;
;       PG8_LDB(B1, 0, 1); PG8_STAGE(PG8_SB(0, 0), b2, voffB);
;       PG8_BAR; PG8_WAIT_L(0); PG8_MMA(0, 1, At, B1); PG8_BAR;
;       PG8_LDA(At, 0, 1); PG8_STAGE(PG8_SA(0, 0), a2, voffA);
;       PG8_BAR; PG8_WAIT_L(0); PG8_MMA(1, 0, At, B0); PG8_BAR; PG8_SCHED;
;       PG8_STAGE(PG8_SB(0, 1), b2 + hstepB, voffB);
;       PG8_WAIT_V(6); PG8_BAR; PG8_MMA(1, 1, At, B1); PG8_BAR;
.LBB0_1858:
	s_add_u32 s42, vcc_lo, 0xfffc0080
	s_addc_u32 s43, vcc_hi, -1
	s_add_i32 s52, 0, 0x10000
	v_add_u32_e32 v154, s52, v139
	ds_read_b128 v[142:145], v154
	ds_read_b128 v[146:149], v154 offset:1024
	ds_read_b128 v[150:153], v154 offset:2048
	ds_read_b128 v[154:157], v154 offset:3072
	s_cmp_eq_u32 s41, 12
	s_cselect_b32 s89, s4, s43
	s_cselect_b32 s88, s5, s42
	s_cselect_b32 s43, s15, s29
	s_cselect_b32 s42, s16, s20
	s_add_i32 m0, s1, 0xc000
	ds_read_b128 v[158:161], v141
	ds_read_b128 v[162:165], v141 offset:1024
	ds_read_b128 v[166:169], v141 offset:2048
	ds_read_b128 v[170:173], v141 offset:3072
	ds_read_b128 v[174:177], v141 offset:4096
	ds_read_b128 v[178:181], v141 offset:5120
	ds_read_b128 v[182:185], v141 offset:6144
	ds_read_b128 v[186:189], v141 offset:7168
	global_load_lds_dwordx4 v134, vcc
	s_add_i32 m0, s1, 0xe000
	s_nop 0
	global_load_lds_dwordx4 v136, vcc
	s_waitcnt lgkmcnt(8)
	s_barrier
	s_waitcnt lgkmcnt(0)
	s_setprio 1
	s_waitcnt lgkmcnt(0)
	v_mfma_f32_16x16x32_bf16 v[124:127], v[142:145], v[158:161], v[124:127]
	v_mfma_f32_16x16x32_bf16 v[116:119], v[150:153], v[158:161], v[116:119]
	v_mfma_f32_16x16x32_bf16 v[108:111], v[142:145], v[166:169], v[108:111]
	v_mfma_f32_16x16x32_bf16 v[100:103], v[150:153], v[166:169], v[100:103]
	v_mfma_f32_16x16x32_bf16 v[92:95], v[142:145], v[174:177], v[92:95]
	v_mfma_f32_16x16x32_bf16 v[84:87], v[150:153], v[174:177], v[84:87]
	v_mfma_f32_16x16x32_bf16 v[76:79], v[142:145], v[182:185], v[76:79]
	v_mfma_f32_16x16x32_bf16 v[68:71], v[150:153], v[182:185], v[68:71]
	v_mfma_f32_16x16x32_bf16 v[124:127], v[146:149], v[162:165], v[124:127]
	v_mfma_f32_16x16x32_bf16 v[116:119], v[154:157], v[162:165], v[116:119]
	v_mfma_f32_16x16x32_bf16 v[108:111], v[146:149], v[170:173], v[108:111]
	v_mfma_f32_16x16x32_bf16 v[100:103], v[154:157], v[170:173], v[100:103]
	v_mfma_f32_16x16x32_bf16 v[92:95], v[146:149], v[178:181], v[92:95]
	v_mfma_f32_16x16x32_bf16 v[84:87], v[154:157], v[178:181], v[84:87]
	v_mfma_f32_16x16x32_bf16 v[76:79], v[146:149], v[186:189], v[76:79]
	v_mfma_f32_16x16x32_bf16 v[68:71], v[154:157], v[186:189], v[68:71]
	s_setprio 0
	s_barrier
	s_add_i32 s56, 0, 0x14000
	v_add_u32_e32 v190, s56, v139
	s_add_i32 s52, s52, s33
	ds_read_b128 v[210:213], v190
	ds_read_b128 v[214:217], v190 offset:1024
	ds_read_b128 v[234:237], v190 offset:2048
	ds_read_b128 v[238:241], v190 offset:3072
	v_lshl_add_u64 v[190:191], s[42:43], 0, v[220:221]
	s_mov_b32 m0, s52
	v_lshl_add_u64 v[194:195], s[42:43], 0, v[132:133]
	global_load_lds_dwordx4 v[190:191], off
	s_add_i32 m0, s52, 0x2000
	s_nop 0
	global_load_lds_dwordx4 v[194:195], off
	s_barrier
	s_waitcnt lgkmcnt(0)
	s_setprio 1
	s_waitcnt lgkmcnt(0)
	v_mfma_f32_16x16x32_bf16 v[120:123], v[210:213], v[158:161], v[120:123]
	v_mfma_f32_16x16x32_bf16 v[112:115], v[234:237], v[158:161], v[112:115]
	v_mfma_f32_16x16x32_bf16 v[104:107], v[210:213], v[166:169], v[104:107]
	v_mfma_f32_16x16x32_bf16 v[96:99], v[234:237], v[166:169], v[96:99]
	v_mfma_f32_16x16x32_bf16 v[88:91], v[210:213], v[174:177], v[88:91]
	v_mfma_f32_16x16x32_bf16 v[80:83], v[234:237], v[174:177], v[80:83]
	v_mfma_f32_16x16x32_bf16 v[72:75], v[210:213], v[182:185], v[72:75]
	v_mfma_f32_16x16x32_bf16 v[64:67], v[234:237], v[182:185], v[64:67]
	v_mfma_f32_16x16x32_bf16 v[120:123], v[214:217], v[162:165], v[120:123]
	v_mfma_f32_16x16x32_bf16 v[112:115], v[238:241], v[162:165], v[112:115]
	v_mfma_f32_16x16x32_bf16 v[104:107], v[214:217], v[170:173], v[104:107]
	v_mfma_f32_16x16x32_bf16 v[96:99], v[238:241], v[170:173], v[96:99]
	v_mfma_f32_16x16x32_bf16 v[88:91], v[214:217], v[178:181], v[88:91]
	v_mfma_f32_16x16x32_bf16 v[80:83], v[238:241], v[178:181], v[80:83]
	v_mfma_f32_16x16x32_bf16 v[72:75], v[214:217], v[186:189], v[72:75]
	v_mfma_f32_16x16x32_bf16 v[64:67], v[238:241], v[186:189], v[64:67]
	s_setprio 0
	s_mov_b32 m0, s1
	v_lshl_add_u64 v[200:201], s[88:89], 0, v[128:129]
	s_barrier
	ds_read_b128 v[158:161], v141 offset:16384
	ds_read_b128 v[162:165], v141 offset:17408
	ds_read_b128 v[166:169], v141 offset:18432
	ds_read_b128 v[170:173], v141 offset:19456
	ds_read_b128 v[174:177], v141 offset:20480
	ds_read_b128 v[178:181], v141 offset:21504
	ds_read_b128 v[182:185], v141 offset:22528
	ds_read_b128 v[186:189], v141 offset:23552
	global_load_lds_dwordx4 v[200:201], off
	v_lshl_add_u64 v[202:203], s[88:89], 0, v[130:131]
	s_mov_b32 m0, s34
	s_nop 0
	global_load_lds_dwordx4 v[202:203], off
	s_barrier
	s_waitcnt lgkmcnt(0)
	s_setprio 1
	s_waitcnt lgkmcnt(0)
	v_mfma_f32_16x16x32_bf16 v[60:63], v[142:145], v[158:161], v[60:63]
	v_mfma_f32_16x16x32_bf16 v[52:55], v[150:153], v[158:161], v[52:55]
	v_mfma_f32_16x16x32_bf16 v[44:47], v[142:145], v[166:169], v[44:47]
	v_mfma_f32_16x16x32_bf16 v[36:39], v[150:153], v[166:169], v[36:39]
	v_mfma_f32_16x16x32_bf16 v[28:31], v[142:145], v[174:177], v[28:31]
	v_mfma_f32_16x16x32_bf16 v[20:23], v[150:153], v[174:177], v[20:23]
	v_mfma_f32_16x16x32_bf16 v[12:15], v[142:145], v[182:185], v[12:15]
	v_mfma_f32_16x16x32_bf16 v[4:7], v[150:153], v[182:185], v[4:7]
	v_mfma_f32_16x16x32_bf16 v[60:63], v[146:149], v[162:165], v[60:63]
	v_mfma_f32_16x16x32_bf16 v[52:55], v[154:157], v[162:165], v[52:55]
	v_mfma_f32_16x16x32_bf16 v[44:47], v[146:149], v[170:173], v[44:47]
	v_mfma_f32_16x16x32_bf16 v[36:39], v[154:157], v[170:173], v[36:39]
	v_mfma_f32_16x16x32_bf16 v[28:31], v[146:149], v[178:181], v[28:31]
	v_mfma_f32_16x16x32_bf16 v[20:23], v[154:157], v[178:181], v[20:23]
	v_mfma_f32_16x16x32_bf16 v[12:15], v[146:149], v[186:189], v[12:15]
	v_mfma_f32_16x16x32_bf16 v[4:7], v[154:157], v[186:189], v[4:7]
	s_setprio 0
	s_barrier
; #define PG8_STAGE(bufoff, gbase, voff) do { _Pragma("unroll") for (int _i = 0; _i < 2; ++_i) \
;     __builtin_amdgcn_global_load_lds((const unsigned*)((const char*)(gbase) + (voff)[_i]), (LAS unsigned*)(lds + (bufoff) + ldsw + _i * 8192), 16, 0, 0); } while (0)
; #define PG8_LDA(dst, b, h) do { _Pragma("unroll") for (int m = 0; m < 4; ++m) _Pragma("unroll") for (int k = 0; k < 2; ++k) dst[m][k] = *(const LAS bf16x8*)(lds + PG8_SA(b, h) + aoff + m * 2048 + k * 1024); } while (0)
; #define PG8_LDB(dst, b, h) do { _Pragma("unroll") for (int n = 0; n < 2; ++n) _Pragma("unroll") for (int k = 0; k < 2; ++k) dst[n][k] = *(const LAS bf16x8*)(lds + PG8_SB(b, h) + boff + n * 2048 + k * 1024); } while (0)
; #define PG8_MMA(ai, bj, At, Bt_) do { __builtin_amdgcn_s_setprio(1); _Pragma("unroll") for (int m = 0; m < 4; ++m) _Pragma("unroll") for (int n = 0; n < 2; ++n) _Pragma("unroll") for (int k = 0; k < 2; ++k) \
;     acc[ai][bj][m][n] = __builtin_amdgcn_mfma_f32_16x16x32_bf16(Bt_[n][k], At[m][k], acc[ai][bj][m][n], 0, 0, 0); __builtin_amdgcn_s_setprio(0); } while (0)
; #define PG8_WAIT_V(n) asm volatile("s_waitcnt vmcnt(" #n ")" ::: "memory")
; #define PG8_WAIT_L(n) asm volatile("s_waitcnt lgkmcnt(" #n ")" ::: "memory")
; #define PG8_BAR __builtin_amdgcn_s_barrier()
; #define PG8_SCHED __builtin_amdgcn_sched_barrier(0)
; #define PG8_LDA(dst, b, h) do { _Pragma("unroll") for (int m = 0; m < 4; ++m) _Pragma("unroll") for (int k = 0; k < 2; ++k) dst[m][k] = *(const LAS bf16x8*)(lds + PG8_SA(b, h) + aoff + m * 2048 + k * 1024); } while (0)
; #define PG8_WAIT_V(n) asm volatile("s_waitcnt vmcnt(" #n ")" ::: "memory")
; template <class Epi>
; DI void gemm_phase(char* smem, const bf16_t* A, int lda, const bf16_t* Bt, int ldb, int K, const Order& S_, const Epi& E) {
;     ...
;       PG8_STAGE(PG8_SB(0, 1), b2 + hstepB, voffB);
;       PG8_WAIT_V(6); PG8_BAR; PG8_MMA(1, 1, At, B1); PG8_BAR;
;       PG8_LDB(B0, 1, 0); PG8_SCHED; PG8_LDA(At, 1, 0); PG8_STAGE(PG8_SA(0, 1), a2 + hstepA, voffA);
;       PG8_WAIT_L(8); PG8_BAR; PG8_WAIT_L(0); PG8_MMA(0, 0, At, B0); PG8_BAR; PG8_SCHED;
;       PG8_LDB(B1, 1, 1); PG8_STAGE(PG8_SB(1, 0), b3, voffB);
;       PG8_BAR; PG8_WAIT_L(0); PG8_MMA(0, 1, At, B1); PG8_BAR;
;       PG8_LDA(At, 1, 1); PG8_STAGE(PG8_SA(1, 0), a3, voffA);
;       PG8_BAR; PG8_WAIT_L(0); PG8_MMA(1, 0, At, B0); PG8_BAR; PG8_SCHED;
	s_add_u32 s52, s42, 0x40000
	s_addc_u32 s53, s43, 0
	s_add_i32 s56, s56, s33
	s_mov_b32 m0, s56
	s_nop 0
	global_load_lds_dwordx4 v220, s[52:53]
	s_add_i32 m0, s56, 0x2000
	s_nop 0
	global_load_lds_dwordx4 v132, s[52:53]
	s_waitcnt vmcnt(6)
	s_barrier
	s_setprio 1
	v_mfma_f32_16x16x32_bf16 v[56:59], v[210:213], v[158:161], v[56:59]
	v_mfma_f32_16x16x32_bf16 v[48:51], v[234:237], v[158:161], v[48:51]
	v_mfma_f32_16x16x32_bf16 v[40:43], v[210:213], v[166:169], v[40:43]
	v_mfma_f32_16x16x32_bf16 v[32:35], v[234:237], v[166:169], v[32:35]
	v_mfma_f32_16x16x32_bf16 v[24:27], v[210:213], v[174:177], v[24:27]
	v_mfma_f32_16x16x32_bf16 v[16:19], v[234:237], v[174:177], v[16:19]
	v_mfma_f32_16x16x32_bf16 v[8:11], v[210:213], v[182:185], v[8:11]
	v_mfma_f32_16x16x32_bf16 v[0:3], v[234:237], v[182:185], v[0:3]
	v_mfma_f32_16x16x32_bf16 v[56:59], v[214:217], v[162:165], v[56:59]
	v_mfma_f32_16x16x32_bf16 v[48:51], v[238:241], v[162:165], v[48:51]
	v_mfma_f32_16x16x32_bf16 v[40:43], v[214:217], v[170:173], v[40:43]
	v_mfma_f32_16x16x32_bf16 v[32:35], v[238:241], v[170:173], v[32:35]
	v_mfma_f32_16x16x32_bf16 v[24:27], v[214:217], v[178:181], v[24:27]
	v_mfma_f32_16x16x32_bf16 v[16:19], v[238:241], v[178:181], v[16:19]
	v_mfma_f32_16x16x32_bf16 v[8:11], v[214:217], v[186:189], v[8:11]
	v_mfma_f32_16x16x32_bf16 v[0:3], v[238:241], v[186:189], v[0:3]
	s_setprio 0
	s_add_i32 s56, 0, 0x18000
	v_add_u32_e32 v154, s56, v139
	s_barrier
	ds_read_b128 v[142:145], v154
	ds_read_b128 v[146:149], v154 offset:1024
	ds_read_b128 v[150:153], v154 offset:2048
	ds_read_b128 v[154:157], v154 offset:3072
	s_add_u32 s52, s88, 0x40000
	s_addc_u32 s53, s89, 0
	s_mov_b32 m0, s38
	ds_read_b128 v[158:161], v141 offset:32768
	ds_read_b128 v[162:165], v141 offset:33792
	ds_read_b128 v[166:169], v141 offset:34816
	ds_read_b128 v[170:173], v141 offset:35840
	ds_read_b128 v[174:177], v141 offset:36864
	ds_read_b128 v[178:181], v141 offset:37888
	ds_read_b128 v[182:185], v141 offset:38912
	ds_read_b128 v[186:189], v141 offset:39936
	global_load_lds_dwordx4 v128, s[52:53]
	s_mov_b32 m0, s39
	s_nop 0
	global_load_lds_dwordx4 v130, s[52:53]
	s_waitcnt lgkmcnt(8)
	s_barrier
	s_waitcnt lgkmcnt(0)
	s_setprio 1
	s_waitcnt lgkmcnt(0)
	v_mfma_f32_16x16x32_bf16 v[124:127], v[142:145], v[158:161], v[124:127]
	v_mfma_f32_16x16x32_bf16 v[116:119], v[150:153], v[158:161], v[116:119]
	v_mfma_f32_16x16x32_bf16 v[108:111], v[142:145], v[166:169], v[108:111]
	v_mfma_f32_16x16x32_bf16 v[100:103], v[150:153], v[166:169], v[100:103]
	v_mfma_f32_16x16x32_bf16 v[92:95], v[142:145], v[174:177], v[92:95]
	v_mfma_f32_16x16x32_bf16 v[84:87], v[150:153], v[174:177], v[84:87]
	v_mfma_f32_16x16x32_bf16 v[76:79], v[142:145], v[182:185], v[76:79]
	v_mfma_f32_16x16x32_bf16 v[68:71], v[150:153], v[182:185], v[68:71]
	v_mfma_f32_16x16x32_bf16 v[124:127], v[146:149], v[162:165], v[124:127]
	v_mfma_f32_16x16x32_bf16 v[116:119], v[154:157], v[162:165], v[116:119]
	v_mfma_f32_16x16x32_bf16 v[108:111], v[146:149], v[170:173], v[108:111]
	v_mfma_f32_16x16x32_bf16 v[100:103], v[154:157], v[170:173], v[100:103]
	v_mfma_f32_16x16x32_bf16 v[92:95], v[146:149], v[178:181], v[92:95]
	v_mfma_f32_16x16x32_bf16 v[84:87], v[154:157], v[178:181], v[84:87]
	v_mfma_f32_16x16x32_bf16 v[76:79], v[146:149], v[186:189], v[76:79]
	v_mfma_f32_16x16x32_bf16 v[68:71], v[154:157], v[186:189], v[68:71]
	s_setprio 0
	s_barrier
	s_add_i32 s52, 0, 0x1c000
	s_add_i32 s53, s56, s33
	v_add_u32_e32 v204, s52, v139
	v_lshl_add_u64 v[190:191], v[190:191], 0, s[58:59]
	s_mov_b32 m0, s53
	ds_read_b128 v[210:213], v204
	ds_read_b128 v[214:217], v204 offset:1024
	ds_read_b128 v[234:237], v204 offset:2048
	ds_read_b128 v[238:241], v204 offset:3072
	global_load_lds_dwordx4 v[190:191], off
	v_lshl_add_u64 v[190:191], v[194:195], 0, s[58:59]
	s_add_i32 m0, s53, 0x2000
	s_nop 0
	global_load_lds_dwordx4 v[190:191], off
	s_barrier
	s_waitcnt lgkmcnt(0)
	s_setprio 1
	s_waitcnt lgkmcnt(0)
	v_mfma_f32_16x16x32_bf16 v[120:123], v[210:213], v[158:161], v[120:123]
	v_mfma_f32_16x16x32_bf16 v[112:115], v[234:237], v[158:161], v[112:115]
	v_mfma_f32_16x16x32_bf16 v[104:107], v[210:213], v[166:169], v[104:107]
	v_mfma_f32_16x16x32_bf16 v[96:99], v[234:237], v[166:169], v[96:99]
	v_mfma_f32_16x16x32_bf16 v[88:91], v[210:213], v[174:177], v[88:91]
	v_mfma_f32_16x16x32_bf16 v[80:83], v[234:237], v[174:177], v[80:83]
	v_mfma_f32_16x16x32_bf16 v[72:75], v[210:213], v[182:185], v[72:75]
	v_mfma_f32_16x16x32_bf16 v[64:67], v[234:237], v[182:185], v[64:67]
	v_mfma_f32_16x16x32_bf16 v[120:123], v[214:217], v[162:165], v[120:123]
	v_mfma_f32_16x16x32_bf16 v[112:115], v[238:241], v[162:165], v[112:115]
	v_mfma_f32_16x16x32_bf16 v[104:107], v[214:217], v[170:173], v[104:107]
	v_mfma_f32_16x16x32_bf16 v[96:99], v[238:241], v[170:173], v[96:99]
	v_mfma_f32_16x16x32_bf16 v[88:91], v[214:217], v[178:181], v[88:91]
	v_mfma_f32_16x16x32_bf16 v[80:83], v[238:241], v[178:181], v[80:83]
	v_mfma_f32_16x16x32_bf16 v[72:75], v[214:217], v[186:189], v[72:75]
	v_mfma_f32_16x16x32_bf16 v[64:67], v[238:241], v[186:189], v[64:67]
	s_setprio 0
	s_mov_b32 m0, s47
	v_lshl_add_u64 v[190:191], v[200:201], 0, s[58:59]
	s_barrier
	ds_read_b128 v[158:161], v141 offset:49152
	ds_read_b128 v[162:165], v141 offset:50176
	ds_read_b128 v[166:169], v141 offset:51200
	ds_read_b128 v[170:173], v141 offset:52224
	ds_read_b128 v[174:177], v141 offset:53248
	ds_read_b128 v[178:181], v141 offset:54272
	ds_read_b128 v[182:185], v141 offset:55296
	ds_read_b128 v[186:189], v141 offset:56320
	global_load_lds_dwordx4 v[190:191], off
	v_lshl_add_u64 v[190:191], v[202:203], 0, s[58:59]
	s_mov_b32 m0, s49
	s_nop 0
	global_load_lds_dwordx4 v[190:191], off
	s_barrier
; DI float siluf_(float x) { return x * sigmoidf_(x); }
; #define PG8_STAGE(bufoff, gbase, voff) do { _Pragma("unroll") for (int _i = 0; _i < 2; ++_i) \
;     __builtin_amdgcn_global_load_lds((const unsigned*)((const char*)(gbase) + (voff)[_i]), (LAS unsigned*)(lds + (bufoff) + ldsw + _i * 8192), 16, 0, 0); } while (0)
; #define PG8_MMA(ai, bj, At, Bt_) do { __builtin_amdgcn_s_setprio(1); _Pragma("unroll") for (int m = 0; m < 4; ++m) _Pragma("unroll") for (int n = 0; n < 2; ++n) _Pragma("unroll") for (int k = 0; k < 2; ++k) \
;     acc[ai][bj][m][n] = __builtin_amdgcn_mfma_f32_16x16x32_bf16(Bt_[n][k], At[m][k], acc[ai][bj][m][n], 0, 0, 0); __builtin_amdgcn_s_setprio(0); } while (0)
; #define PG8_WAIT_V(n) asm volatile("s_waitcnt vmcnt(" #n ")" ::: "memory")
; #define PG8_BAR __builtin_amdgcn_s_barrier()
; DI u32x4 pack8v(const f32x4& a, const f32x4& b) { u32x4 w; w.x = pk2(a[0], a[1]); w.y = pk2(a[2], a[3]); w.z = pk2(b[0], b[1]); w.w = pk2(b[2], b[3]); return w; }
; #define PG8_MMA(ai, bj, At, Bt_) do { __builtin_amdgcn_s_setprio(1); _Pragma("unroll") for (int m = 0; m < 4; ++m) _Pragma("unroll") for (int n = 0; n < 2; ++n) _Pragma("unroll") for (int k = 0; k < 2; ++k) \
;     acc[ai][bj][m][n] = __builtin_amdgcn_mfma_f32_16x16x32_bf16(Bt_[n][k], At[m][k], acc[ai][bj][m][n], 0, 0, 0); __builtin_amdgcn_s_setprio(0); } while (0)
; #define PG8_WAIT_V(n) asm volatile("s_waitcnt vmcnt(" #n ")" ::: "memory")
; #define PG8_BAR __builtin_amdgcn_s_barrier()
; template <class Epi>
; DI void gemm_phase(char* smem, const bf16_t* A, int lda, const bf16_t* Bt, int ldb, int K, const Order& S_, const Epi& E) {
;     ...
;       PG8_STAGE(PG8_SB(1, 1), b3 + hstepB, voffB);
;       PG8_WAIT_V(6); PG8_BAR; PG8_MMA(1, 1, At, B1); PG8_BAR;
;     }
;     E(acc, cur, wr, wc, fr, fq);
;   DI void operator()(const acc_t& acc, const Unit& u, int wr, int wc, int fr, int fq) const {
;     const int row0 = u.pm * BM + wr * 64 + fr, col0 = u.pn * HALF + wc * 32 + 8 * fq;
; #pragma unroll
;     for (int ai = 0; ai < 2; ++ai)
; #pragma unroll
;       for (int m = 0; m < 4; ++m) {
;         f32x4 r0, r1;
; #pragma unroll
;         for (int e = 0; e < 4; ++e) { r0[e] = siluf_(acc[ai][0][m][0][e]) * acc[ai][1][m][0][e]; r1[e] = siluf_(acc[ai][0][m][1][e]) * acc[ai][1][m][1][e]; }
;         *(u32x4*)(G + (size_t)(row0 + ai * HALF + m * 16) * DFF + col0) = pack8v(r0, r1); }
	s_waitcnt lgkmcnt(0)
	s_setprio 1
	s_waitcnt lgkmcnt(0)
	v_mfma_f32_16x16x32_bf16 v[60:63], v[142:145], v[158:161], v[60:63]
	v_mfma_f32_16x16x32_bf16 v[52:55], v[150:153], v[158:161], v[52:55]
	v_mfma_f32_16x16x32_bf16 v[44:47], v[142:145], v[166:169], v[44:47]
	v_mfma_f32_16x16x32_bf16 v[36:39], v[150:153], v[166:169], v[36:39]
	v_mfma_f32_16x16x32_bf16 v[28:31], v[142:145], v[174:177], v[28:31]
	v_mfma_f32_16x16x32_bf16 v[20:23], v[150:153], v[174:177], v[20:23]
	v_mfma_f32_16x16x32_bf16 v[12:15], v[142:145], v[182:185], v[12:15]
	v_mfma_f32_16x16x32_bf16 v[4:7], v[150:153], v[182:185], v[4:7]
	v_mfma_f32_16x16x32_bf16 v[60:63], v[146:149], v[162:165], v[60:63]
	v_mfma_f32_16x16x32_bf16 v[52:55], v[154:157], v[162:165], v[52:55]
	v_mfma_f32_16x16x32_bf16 v[44:47], v[146:149], v[170:173], v[44:47]
	v_mfma_f32_16x16x32_bf16 v[36:39], v[154:157], v[170:173], v[36:39]
	v_mfma_f32_16x16x32_bf16 v[28:31], v[146:149], v[178:181], v[28:31]
	v_mfma_f32_16x16x32_bf16 v[20:23], v[154:157], v[178:181], v[20:23]
	v_mfma_f32_16x16x32_bf16 v[12:15], v[146:149], v[186:189], v[12:15]
	v_mfma_f32_16x16x32_bf16 v[4:7], v[154:157], v[186:189], v[4:7]
	s_setprio 0
	s_barrier
	s_add_u32 s42, s42, 0x40080
	s_addc_u32 s43, s43, 0
	s_add_i32 s52, s52, s33
	s_mov_b32 m0, s52
	s_nop 0
	global_load_lds_dwordx4 v220, s[42:43]
	s_add_i32 m0, s52, 0x2000
	s_nop 0
	global_load_lds_dwordx4 v132, s[42:43]
	s_waitcnt vmcnt(6)
	s_barrier
	s_setprio 1
	v_mfma_f32_16x16x32_bf16 v[56:59], v[210:213], v[158:161], v[56:59]
	v_mfma_f32_16x16x32_bf16 v[48:51], v[234:237], v[158:161], v[48:51]
	v_mfma_f32_16x16x32_bf16 v[40:43], v[210:213], v[166:169], v[40:43]
	v_mfma_f32_16x16x32_bf16 v[32:35], v[234:237], v[166:169], v[32:35]
	v_mfma_f32_16x16x32_bf16 v[24:27], v[210:213], v[174:177], v[24:27]
	v_mfma_f32_16x16x32_bf16 v[16:19], v[234:237], v[174:177], v[16:19]
	v_mfma_f32_16x16x32_bf16 v[8:11], v[210:213], v[182:185], v[8:11]
	v_mfma_f32_16x16x32_bf16 v[0:3], v[234:237], v[182:185], v[0:3]
	v_mfma_f32_16x16x32_bf16 v[56:59], v[214:217], v[162:165], v[56:59]
	v_mfma_f32_16x16x32_bf16 v[48:51], v[238:241], v[162:165], v[48:51]
	v_mfma_f32_16x16x32_bf16 v[40:43], v[214:217], v[170:173], v[40:43]
	v_mfma_f32_16x16x32_bf16 v[32:35], v[238:241], v[170:173], v[32:35]
	v_mfma_f32_16x16x32_bf16 v[24:27], v[214:217], v[178:181], v[24:27]
	v_mfma_f32_16x16x32_bf16 v[16:19], v[238:241], v[178:181], v[16:19]
	v_mfma_f32_16x16x32_bf16 v[8:11], v[214:217], v[186:189], v[8:11]
	v_mfma_f32_16x16x32_bf16 v[0:3], v[238:241], v[186:189], v[0:3]
	s_setprio 0
	s_add_i32 s41, s41, 2
	s_add_u32 vcc_lo, vcc_lo, 0x100
	s_addc_u32 vcc_hi, vcc_hi, 0
	s_add_u32 s20, s20, 0x100
	s_addc_u32 s29, s29, 0
	s_cmp_gt_u32 s41, 13
	s_barrier
	s_cbranch_scc0 .LBB0_1858
	v_mul_f32_e32 v143, 0xbfb8aa3b, v124
	v_exp_f32_e32 v143, v143
	v_readlane_b32 s4, v254, 43
	v_lshl_or_b32 v144, s0, 7, v140
	v_readlane_b32 s5, v254, 44
	v_add_f32_e32 v143, 1.0, v143
	v_rcp_f32_e32 v146, v143
	v_mul_f32_e32 v143, 0xbfb8aa3b, v116
	v_exp_f32_e32 v143, v143
	v_lshl_add_u32 v142, s46, 8, v138
	v_ashrrev_i32_e32 v145, 31, v144
	s_and_b64 vcc, exec, s[36:37]
	v_add_f32_e32 v143, 1.0, v143
	v_rcp_f32_e32 v148, v143
	v_mul_f32_e32 v143, 0xbfb8aa3b, v125
	v_exp_f32_e32 v143, v143
	s_mov_b32 s0, s90
	s_mov_b32 s46, s40
	s_mov_b64 s[88:89], s[44:45]
	v_add_f32_e32 v143, 1.0, v143
	v_rcp_f32_e32 v147, v143
	s_mov_b64 s[42:43], s[50:51]
	s_mov_b32 s51, 0x78787879
	v_pk_mul_f32 v[124:125], v[124:125], v[146:147]
	s_nop 0
	v_pk_mul_f32 v[120:121], v[124:125], v[120:121]
	v_mul_f32_e32 v124, 0xbfb8aa3b, v117
	v_exp_f32_e32 v124, v124
	s_nop 0
	v_add_f32_e32 v124, 1.0, v124
	v_rcp_f32_e32 v149, v124
	s_nop 0
	v_pk_mul_f32 v[116:117], v[116:117], v[148:149]
	s_nop 0
	v_pk_mul_f32 v[112:113], v[116:117], v[112:113]
	v_mul_f32_e32 v117, 0xbfb8aa3b, v118
	v_exp_f32_e32 v117, v117
	v_mul_f32_e32 v116, 0xbfb8aa3b, v126
	v_exp_f32_e32 v116, v116
	v_add_f32_e32 v117, 1.0, v117
	v_rcp_f32_e32 v124, v117
	v_mul_f32_e32 v117, 0xbfb8aa3b, v127
	v_exp_f32_e32 v117, v117
	v_add_f32_e32 v116, 1.0, v116
	v_rcp_f32_e32 v116, v116
	v_add_f32_e32 v117, 1.0, v117
	v_rcp_f32_e32 v117, v117
	s_nop 0
	v_pk_mul_f32 v[116:117], v[126:127], v[116:117]
	s_nop 0
	v_pk_mul_f32 v[122:123], v[116:117], v[122:123]
	v_mul_f32_e32 v116, 0xbfb8aa3b, v119
	v_exp_f32_e32 v116, v116
	s_nop 0
	v_add_f32_e32 v116, 1.0, v116
	v_rcp_f32_e32 v125, v116
	s_nop 0
	v_pk_mul_f32 v[116:117], v[118:119], v[124:125]
	s_nop 0
	v_pk_mul_f32 v[114:115], v[116:117], v[114:115]
	v_cvt_pk_bf16_f32 v118, v112, v113
	v_mov_b64_e32 v[112:113], s[4:5]
	v_cvt_pk_bf16_f32 v116, v120, v121
	v_cvt_pk_bf16_f32 v119, v114, v115
	v_mad_i64_i32 v[120:121], s[4:5], v142, s18, v[112:113]
	v_lshlrev_b64 v[114:115], 1, v[144:145]
	v_cvt_pk_bf16_f32 v117, v122, v123
	v_lshl_add_u64 v[120:121], v[120:121], 0, v[114:115]
	global_store_dwordx4 v[120:121], v[116:119], off
	s_nop 1
	v_mul_f32_e32 v117, 0xbfb8aa3b, v100
	v_exp_f32_e32 v117, v117
	v_mul_f32_e32 v116, 0xbfb8aa3b, v108
	v_exp_f32_e32 v116, v116
	v_add_f32_e32 v117, 1.0, v117
	v_rcp_f32_e32 v118, v117
	v_mul_f32_e32 v117, 0xbfb8aa3b, v109
	v_exp_f32_e32 v117, v117
	v_add_f32_e32 v116, 1.0, v116
	v_rcp_f32_e32 v116, v116
	v_add_f32_e32 v117, 1.0, v117
	v_rcp_f32_e32 v117, v117
	s_nop 0
	v_pk_mul_f32 v[108:109], v[108:109], v[116:117]
	s_nop 0
	v_pk_mul_f32 v[104:105], v[108:109], v[104:105]
	v_mul_f32_e32 v108, 0xbfb8aa3b, v101
	v_exp_f32_e32 v108, v108
	s_nop 0
	v_add_f32_e32 v108, 1.0, v108
	v_rcp_f32_e32 v119, v108
	s_nop 0
	v_pk_mul_f32 v[100:101], v[100:101], v[118:119]
	s_nop 0
	v_pk_mul_f32 v[100:101], v[100:101], v[96:97]
	v_mul_f32_e32 v97, 0xbfb8aa3b, v102
; DI float siluf_(float x) { return x * sigmoidf_(x); }
; DI u32x4 pack8v(const f32x4& a, const f32x4& b) { u32x4 w; w.x = pk2(a[0], a[1]); w.y = pk2(a[2], a[3]); w.z = pk2(b[0], b[1]); w.w = pk2(b[2], b[3]); return w; }
;   DI void operator()(const acc_t& acc, const Unit& u, int wr, int wc, int fr, int fq) const {
;     const int row0 = u.pm * BM + wr * 64 + fr, col0 = u.pn * HALF + wc * 32 + 8 * fq;
; #pragma unroll
;     for (int ai = 0; ai < 2; ++ai)
; #pragma unroll
;       for (int m = 0; m < 4; ++m) {
;         f32x4 r0, r1;
; #pragma unroll
;         for (int e = 0; e < 4; ++e) { r0[e] = siluf_(acc[ai][0][m][0][e]) * acc[ai][1][m][0][e]; r1[e] = siluf_(acc[ai][0][m][1][e]) * acc[ai][1][m][1][e]; }
;         *(u32x4*)(G + (size_t)(row0 + ai * HALF + m * 16) * DFF + col0) = pack8v(r0, r1); }
	v_exp_f32_e32 v97, v97
	v_mul_f32_e32 v96, 0xbfb8aa3b, v110
	v_exp_f32_e32 v96, v96
	v_add_f32_e32 v97, 1.0, v97
	v_rcp_f32_e32 v108, v97
	v_mul_f32_e32 v97, 0xbfb8aa3b, v111
	v_exp_f32_e32 v97, v97
	v_add_f32_e32 v96, 1.0, v96
	v_rcp_f32_e32 v96, v96
	v_add_f32_e32 v97, 1.0, v97
	v_rcp_f32_e32 v97, v97
	s_nop 0
	v_pk_mul_f32 v[96:97], v[110:111], v[96:97]
	s_nop 0
	v_pk_mul_f32 v[106:107], v[96:97], v[106:107]
	v_mul_f32_e32 v96, 0xbfb8aa3b, v103
	v_exp_f32_e32 v96, v96
	s_nop 0
	v_add_f32_e32 v96, 1.0, v96
	v_rcp_f32_e32 v109, v96
	s_nop 0
	v_pk_mul_f32 v[96:97], v[102:103], v[108:109]
	s_nop 0
	v_pk_mul_f32 v[102:103], v[96:97], v[98:99]
	v_cvt_pk_bf16_f32 v98, v100, v101
	v_or_b32_e32 v100, 16, v142
	v_mad_i64_i32 v[100:101], s[4:5], v100, s18, v[112:113]
	v_cvt_pk_bf16_f32 v96, v104, v105
	v_cvt_pk_bf16_f32 v97, v106, v107
	v_cvt_pk_bf16_f32 v99, v102, v103
	v_lshl_add_u64 v[100:101], v[100:101], 0, v[114:115]
	global_store_dwordx4 v[100:101], v[96:99], off
	s_nop 1
	v_mul_f32_e32 v97, 0xbfb8aa3b, v84
	v_exp_f32_e32 v97, v97
	v_mul_f32_e32 v96, 0xbfb8aa3b, v92
	v_exp_f32_e32 v96, v96
	v_add_f32_e32 v97, 1.0, v97
	v_rcp_f32_e32 v98, v97
	v_mul_f32_e32 v97, 0xbfb8aa3b, v93
	v_exp_f32_e32 v97, v97
	v_add_f32_e32 v96, 1.0, v96
	v_rcp_f32_e32 v96, v96
	v_add_f32_e32 v97, 1.0, v97
	v_rcp_f32_e32 v97, v97
	s_nop 0
	v_pk_mul_f32 v[92:93], v[92:93], v[96:97]
	s_nop 0
	v_pk_mul_f32 v[88:89], v[92:93], v[88:89]
	v_mul_f32_e32 v92, 0xbfb8aa3b, v85
	v_exp_f32_e32 v92, v92
	s_nop 0
	v_add_f32_e32 v92, 1.0, v92
	v_rcp_f32_e32 v99, v92
	s_nop 0
	v_pk_mul_f32 v[84:85], v[84:85], v[98:99]
	s_nop 0
	v_pk_mul_f32 v[84:85], v[84:85], v[80:81]
	v_mul_f32_e32 v81, 0xbfb8aa3b, v86
	v_exp_f32_e32 v81, v81
	v_mul_f32_e32 v80, 0xbfb8aa3b, v94
	v_exp_f32_e32 v80, v80
	v_add_f32_e32 v81, 1.0, v81
	v_rcp_f32_e32 v92, v81
	v_mul_f32_e32 v81, 0xbfb8aa3b, v95
	v_exp_f32_e32 v81, v81
	v_add_f32_e32 v80, 1.0, v80
	v_rcp_f32_e32 v80, v80
	v_add_f32_e32 v81, 1.0, v81
	v_rcp_f32_e32 v81, v81
	s_nop 0
	v_pk_mul_f32 v[80:81], v[94:95], v[80:81]
	s_nop 0
	v_pk_mul_f32 v[90:91], v[80:81], v[90:91]
	v_mul_f32_e32 v80, 0xbfb8aa3b, v87
	v_exp_f32_e32 v80, v80
	s_nop 0
	v_add_f32_e32 v80, 1.0, v80
	v_rcp_f32_e32 v93, v80
	s_nop 0
	v_pk_mul_f32 v[80:81], v[86:87], v[92:93]
	s_nop 0
	v_pk_mul_f32 v[86:87], v[80:81], v[82:83]
	v_cvt_pk_bf16_f32 v82, v84, v85
	v_or_b32_e32 v84, 32, v142
	v_mad_i64_i32 v[84:85], s[4:5], v84, s18, v[112:113]
	v_cvt_pk_bf16_f32 v80, v88, v89
	v_cvt_pk_bf16_f32 v81, v90, v91
	v_cvt_pk_bf16_f32 v83, v86, v87
	v_lshl_add_u64 v[84:85], v[84:85], 0, v[114:115]
	global_store_dwordx4 v[84:85], v[80:83], off
	s_nop 1
	v_mul_f32_e32 v81, 0xbfb8aa3b, v68
	v_exp_f32_e32 v81, v81
	v_mul_f32_e32 v80, 0xbfb8aa3b, v76
	v_exp_f32_e32 v80, v80
	v_add_f32_e32 v81, 1.0, v81
	v_rcp_f32_e32 v82, v81
	v_mul_f32_e32 v81, 0xbfb8aa3b, v77
	v_exp_f32_e32 v81, v81
	v_add_f32_e32 v80, 1.0, v80
	v_rcp_f32_e32 v80, v80
	v_add_f32_e32 v81, 1.0, v81
	v_rcp_f32_e32 v81, v81
	s_nop 0
	v_pk_mul_f32 v[76:77], v[76:77], v[80:81]
	s_nop 0
	v_pk_mul_f32 v[72:73], v[76:77], v[72:73]
	v_mul_f32_e32 v76, 0xbfb8aa3b, v69
	v_exp_f32_e32 v76, v76
	s_nop 0
	v_add_f32_e32 v76, 1.0, v76
	v_rcp_f32_e32 v83, v76
	s_nop 0
	v_pk_mul_f32 v[68:69], v[68:69], v[82:83]
	s_nop 0
	v_pk_mul_f32 v[68:69], v[68:69], v[64:65]
	v_mul_f32_e32 v65, 0xbfb8aa3b, v70
	v_exp_f32_e32 v65, v65
	v_mul_f32_e32 v64, 0xbfb8aa3b, v78
	v_exp_f32_e32 v64, v64
	v_add_f32_e32 v65, 1.0, v65
	v_rcp_f32_e32 v76, v65
	v_mul_f32_e32 v65, 0xbfb8aa3b, v79
	v_exp_f32_e32 v65, v65
	v_add_f32_e32 v64, 1.0, v64
	v_rcp_f32_e32 v64, v64
	v_add_f32_e32 v65, 1.0, v65
	v_rcp_f32_e32 v65, v65
	s_nop 0
	v_pk_mul_f32 v[64:65], v[78:79], v[64:65]
	s_nop 0
	v_pk_mul_f32 v[74:75], v[64:65], v[74:75]
	v_mul_f32_e32 v64, 0xbfb8aa3b, v71
	v_exp_f32_e32 v64, v64
	s_nop 0
	v_add_f32_e32 v64, 1.0, v64
	v_rcp_f32_e32 v77, v64
	s_nop 0
	v_pk_mul_f32 v[64:65], v[70:71], v[76:77]
	s_nop 0
	v_pk_mul_f32 v[70:71], v[64:65], v[66:67]
	v_cvt_pk_bf16_f32 v66, v68, v69
	v_or_b32_e32 v68, 48, v142
	v_mad_i64_i32 v[68:69], s[4:5], v68, s18, v[112:113]
	v_cvt_pk_bf16_f32 v64, v72, v73
	v_cvt_pk_bf16_f32 v65, v74, v75
	v_cvt_pk_bf16_f32 v67, v70, v71
	v_lshl_add_u64 v[68:69], v[68:69], 0, v[114:115]
	global_store_dwordx4 v[68:69], v[64:67], off
	v_add_u32_e32 v68, 0x80, v142
	s_nop 0
	v_mul_f32_e32 v65, 0xbfb8aa3b, v52
	v_exp_f32_e32 v65, v65
	v_mul_f32_e32 v64, 0xbfb8aa3b, v60
	v_exp_f32_e32 v64, v64
	v_add_f32_e32 v65, 1.0, v65
	v_rcp_f32_e32 v66, v65
	v_mul_f32_e32 v65, 0xbfb8aa3b, v61
	v_exp_f32_e32 v65, v65
	v_add_f32_e32 v64, 1.0, v64
	v_rcp_f32_e32 v64, v64
	v_add_f32_e32 v65, 1.0, v65
	v_rcp_f32_e32 v65, v65
	s_nop 0
	v_pk_mul_f32 v[60:61], v[60:61], v[64:65]
	s_nop 0
	v_pk_mul_f32 v[56:57], v[60:61], v[56:57]
	v_mul_f32_e32 v60, 0xbfb8aa3b, v53
	v_exp_f32_e32 v60, v60
	s_nop 0
	v_add_f32_e32 v60, 1.0, v60
	v_rcp_f32_e32 v67, v60
	s_nop 0
	v_pk_mul_f32 v[52:53], v[52:53], v[66:67]
	s_nop 0
	v_pk_mul_f32 v[52:53], v[52:53], v[48:49]
	v_mul_f32_e32 v49, 0xbfb8aa3b, v54
	v_exp_f32_e32 v49, v49
	v_mul_f32_e32 v48, 0xbfb8aa3b, v62
	v_exp_f32_e32 v48, v48
	v_add_f32_e32 v49, 1.0, v49
	v_rcp_f32_e32 v60, v49
	v_mul_f32_e32 v49, 0xbfb8aa3b, v63
	v_exp_f32_e32 v49, v49
	v_add_f32_e32 v48, 1.0, v48
	v_rcp_f32_e32 v48, v48
	v_add_f32_e32 v49, 1.0, v49
	v_rcp_f32_e32 v49, v49
	s_nop 0
	v_pk_mul_f32 v[48:49], v[62:63], v[48:49]
	s_nop 0
	v_pk_mul_f32 v[58:59], v[48:49], v[58:59]
	v_mul_f32_e32 v48, 0xbfb8aa3b, v55
; DI float siluf_(float x) { return x * sigmoidf_(x); }
; #define PG8_WAIT_V(n) asm volatile("s_waitcnt vmcnt(" #n ")" ::: "memory")
; #define PG8_BAR __builtin_amdgcn_s_barrier()
; DI u32x4 pack8v(const f32x4& a, const f32x4& b) { u32x4 w; w.x = pk2(a[0], a[1]); w.y = pk2(a[2], a[3]); w.z = pk2(b[0], b[1]); w.w = pk2(b[2], b[3]); return w; }
; #define PG8_WAIT_V(n) asm volatile("s_waitcnt vmcnt(" #n ")" ::: "memory")
; #define PG8_BAR __builtin_amdgcn_s_barrier()
; template <class Epi>
; DI void gemm_phase(char* smem, const bf16_t* A, int lda, const bf16_t* Bt, int ldb, int K, const Order& S_, const Epi& E) {
;     ...
;     if (!has_next) break;
; #pragma unroll
;     for (int a = 0; a < 2; ++a)
; #pragma unroll
;       for (int b = 0; b < 2; ++b)
; #pragma unroll
;         for (int m = 0; m < 4; ++m)
; #pragma unroll
;           for (int n = 0; n < 2; ++n) acc[a][b][m][n] = (f32x4){0.f, 0.f, 0.f, 0.f};
;     cur = nxt; cA = nA; cB = nB; ++ui;
;   }
;   PG8_WAIT_V(0);
;   if (wr == 0) PG8_BAR;
;   PG8_BAR;
;   DI void operator()(const acc_t& acc, const Unit& u, int wr, int wc, int fr, int fq) const {
;     const int row0 = u.pm * BM + wr * 64 + fr, col0 = u.pn * HALF + wc * 32 + 8 * fq;
; #pragma unroll
;     for (int ai = 0; ai < 2; ++ai)
; #pragma unroll
;       for (int m = 0; m < 4; ++m) {
;         f32x4 r0, r1;
; #pragma unroll
;         for (int e = 0; e < 4; ++e) { r0[e] = siluf_(acc[ai][0][m][0][e]) * acc[ai][1][m][0][e]; r1[e] = siluf_(acc[ai][0][m][1][e]) * acc[ai][1][m][1][e]; }
;         *(u32x4*)(G + (size_t)(row0 + ai * HALF + m * 16) * DFF + col0) = pack8v(r0, r1); }
	v_exp_f32_e32 v48, v48
	s_nop 0
	v_add_f32_e32 v48, 1.0, v48
	v_rcp_f32_e32 v61, v48
	s_nop 0
	v_pk_mul_f32 v[48:49], v[54:55], v[60:61]
	s_nop 0
	v_pk_mul_f32 v[54:55], v[48:49], v[50:51]
	v_cvt_pk_bf16_f32 v50, v52, v53
	v_mad_i64_i32 v[52:53], s[4:5], v68, s18, v[112:113]
	v_cvt_pk_bf16_f32 v48, v56, v57
	v_cvt_pk_bf16_f32 v49, v58, v59
	v_cvt_pk_bf16_f32 v51, v54, v55
	v_lshl_add_u64 v[52:53], v[52:53], 0, v[114:115]
	global_store_dwordx4 v[52:53], v[48:51], off
	s_nop 1
	v_mul_f32_e32 v49, 0xbfb8aa3b, v36
	v_exp_f32_e32 v49, v49
	v_mul_f32_e32 v48, 0xbfb8aa3b, v44
	v_exp_f32_e32 v48, v48
	v_add_f32_e32 v49, 1.0, v49
	v_rcp_f32_e32 v50, v49
	v_mul_f32_e32 v49, 0xbfb8aa3b, v45
	v_exp_f32_e32 v49, v49
	v_add_f32_e32 v48, 1.0, v48
	v_rcp_f32_e32 v48, v48
	v_add_f32_e32 v49, 1.0, v49
	v_rcp_f32_e32 v49, v49
	s_nop 0
	v_pk_mul_f32 v[44:45], v[44:45], v[48:49]
	s_nop 0
	v_pk_mul_f32 v[40:41], v[44:45], v[40:41]
	v_mul_f32_e32 v44, 0xbfb8aa3b, v37
	v_exp_f32_e32 v44, v44
	s_nop 0
	v_add_f32_e32 v44, 1.0, v44
	v_rcp_f32_e32 v51, v44
	s_nop 0
	v_pk_mul_f32 v[36:37], v[36:37], v[50:51]
	s_nop 0
	v_pk_mul_f32 v[36:37], v[36:37], v[32:33]
	v_mul_f32_e32 v33, 0xbfb8aa3b, v38
	v_exp_f32_e32 v33, v33
	v_mul_f32_e32 v32, 0xbfb8aa3b, v46
	v_exp_f32_e32 v32, v32
	v_add_f32_e32 v33, 1.0, v33
	v_rcp_f32_e32 v44, v33
	v_mul_f32_e32 v33, 0xbfb8aa3b, v47
	v_exp_f32_e32 v33, v33
	v_add_f32_e32 v32, 1.0, v32
	v_rcp_f32_e32 v32, v32
	v_add_f32_e32 v33, 1.0, v33
	v_rcp_f32_e32 v33, v33
	s_nop 0
	v_pk_mul_f32 v[32:33], v[46:47], v[32:33]
	s_nop 0
	v_pk_mul_f32 v[42:43], v[32:33], v[42:43]
	v_mul_f32_e32 v32, 0xbfb8aa3b, v39
	v_exp_f32_e32 v32, v32
	s_nop 0
	v_add_f32_e32 v32, 1.0, v32
	v_rcp_f32_e32 v45, v32
	s_nop 0
	v_pk_mul_f32 v[32:33], v[38:39], v[44:45]
	s_nop 0
	v_pk_mul_f32 v[38:39], v[32:33], v[34:35]
	v_cvt_pk_bf16_f32 v34, v36, v37
	v_add_u32_e32 v36, 0x90, v142
	v_mad_i64_i32 v[36:37], s[4:5], v36, s18, v[112:113]
	v_cvt_pk_bf16_f32 v32, v40, v41
	v_cvt_pk_bf16_f32 v33, v42, v43
	v_cvt_pk_bf16_f32 v35, v38, v39
	v_lshl_add_u64 v[36:37], v[36:37], 0, v[114:115]
	global_store_dwordx4 v[36:37], v[32:35], off
	s_nop 1
	v_mul_f32_e32 v33, 0xbfb8aa3b, v20
	v_exp_f32_e32 v33, v33
	v_mul_f32_e32 v32, 0xbfb8aa3b, v28
	v_exp_f32_e32 v32, v32
	v_add_f32_e32 v33, 1.0, v33
	v_rcp_f32_e32 v34, v33
	v_mul_f32_e32 v33, 0xbfb8aa3b, v29
	v_exp_f32_e32 v33, v33
	v_add_f32_e32 v32, 1.0, v32
	v_rcp_f32_e32 v32, v32
	v_add_f32_e32 v33, 1.0, v33
	v_rcp_f32_e32 v33, v33
	s_nop 0
	v_pk_mul_f32 v[28:29], v[28:29], v[32:33]
	s_nop 0
	v_pk_mul_f32 v[24:25], v[28:29], v[24:25]
	v_mul_f32_e32 v28, 0xbfb8aa3b, v21
	v_exp_f32_e32 v28, v28
	s_nop 0
	v_add_f32_e32 v28, 1.0, v28
	v_rcp_f32_e32 v35, v28
	s_nop 0
	v_pk_mul_f32 v[20:21], v[20:21], v[34:35]
	s_nop 0
	v_pk_mul_f32 v[20:21], v[20:21], v[16:17]
	v_mul_f32_e32 v17, 0xbfb8aa3b, v22
	v_exp_f32_e32 v17, v17
	v_mul_f32_e32 v16, 0xbfb8aa3b, v30
	v_exp_f32_e32 v16, v16
	v_add_f32_e32 v17, 1.0, v17
	v_rcp_f32_e32 v28, v17
	v_mul_f32_e32 v17, 0xbfb8aa3b, v31
	v_exp_f32_e32 v17, v17
	v_add_f32_e32 v16, 1.0, v16
	v_rcp_f32_e32 v16, v16
	v_add_f32_e32 v17, 1.0, v17
	v_rcp_f32_e32 v17, v17
	s_nop 0
	v_pk_mul_f32 v[16:17], v[30:31], v[16:17]
	s_nop 0
	v_pk_mul_f32 v[26:27], v[16:17], v[26:27]
	v_mul_f32_e32 v16, 0xbfb8aa3b, v23
	v_exp_f32_e32 v16, v16
	s_nop 0
	v_add_f32_e32 v16, 1.0, v16
	v_rcp_f32_e32 v29, v16
	s_nop 0
	v_pk_mul_f32 v[16:17], v[22:23], v[28:29]
	s_nop 0
	v_pk_mul_f32 v[22:23], v[16:17], v[18:19]
	v_cvt_pk_bf16_f32 v18, v20, v21
	v_add_u32_e32 v20, 0xa0, v142
	v_mad_i64_i32 v[20:21], s[4:5], v20, s18, v[112:113]
	v_cvt_pk_bf16_f32 v16, v24, v25
	v_cvt_pk_bf16_f32 v17, v26, v27
	v_cvt_pk_bf16_f32 v19, v22, v23
	v_lshl_add_u64 v[20:21], v[20:21], 0, v[114:115]
	global_store_dwordx4 v[20:21], v[16:19], off
	s_nop 1
	v_mul_f32_e32 v17, 0xbfb8aa3b, v4
	v_exp_f32_e32 v17, v17
	v_mul_f32_e32 v16, 0xbfb8aa3b, v12
	v_exp_f32_e32 v16, v16
	v_add_f32_e32 v17, 1.0, v17
	v_rcp_f32_e32 v18, v17
	v_mul_f32_e32 v17, 0xbfb8aa3b, v13
	v_exp_f32_e32 v17, v17
	v_add_f32_e32 v16, 1.0, v16
	v_rcp_f32_e32 v16, v16
	v_add_f32_e32 v17, 1.0, v17
	v_rcp_f32_e32 v17, v17
	s_nop 0
	v_pk_mul_f32 v[12:13], v[12:13], v[16:17]
	s_nop 0
	v_pk_mul_f32 v[8:9], v[12:13], v[8:9]
	v_mul_f32_e32 v12, 0xbfb8aa3b, v5
	v_exp_f32_e32 v12, v12
	s_nop 0
	v_add_f32_e32 v12, 1.0, v12
	v_rcp_f32_e32 v19, v12
	s_nop 0
	v_pk_mul_f32 v[4:5], v[4:5], v[18:19]
	s_nop 0
	v_pk_mul_f32 v[4:5], v[4:5], v[0:1]
	v_mul_f32_e32 v1, 0xbfb8aa3b, v6
	v_exp_f32_e32 v1, v1
	v_mul_f32_e32 v0, 0xbfb8aa3b, v14
	v_exp_f32_e32 v0, v0
	v_add_f32_e32 v1, 1.0, v1
	v_rcp_f32_e32 v12, v1
	v_mul_f32_e32 v1, 0xbfb8aa3b, v15
	v_exp_f32_e32 v1, v1
	v_add_f32_e32 v0, 1.0, v0
	v_rcp_f32_e32 v0, v0
	v_add_f32_e32 v1, 1.0, v1
	v_rcp_f32_e32 v1, v1
	s_nop 0
	v_pk_mul_f32 v[0:1], v[14:15], v[0:1]
	s_nop 0
	v_pk_mul_f32 v[10:11], v[0:1], v[10:11]
	v_mul_f32_e32 v0, 0xbfb8aa3b, v7
	v_exp_f32_e32 v0, v0
	s_nop 0
	v_add_f32_e32 v0, 1.0, v0
	v_rcp_f32_e32 v13, v0
	s_nop 0
	v_pk_mul_f32 v[0:1], v[6:7], v[12:13]
	s_nop 0
	v_pk_mul_f32 v[6:7], v[0:1], v[2:3]
	v_cvt_pk_bf16_f32 v2, v4, v5
	v_add_u32_e32 v4, 0xb0, v142
	v_mad_i64_i32 v[4:5], s[4:5], v4, s18, v[112:113]
	v_cvt_pk_bf16_f32 v0, v8, v9
	v_cvt_pk_bf16_f32 v1, v10, v11
	v_cvt_pk_bf16_f32 v3, v6, v7
	v_lshl_add_u64 v[4:5], v[4:5], 0, v[114:115]
	global_store_dwordx4 v[4:5], v[0:3], off
	s_cbranch_vccz .LBB0_1854
	s_waitcnt vmcnt(0)
	s_cmpk_gt_u32 s3, 0xff
	s_cbranch_scc1 .LBB0_1862
	s_barrier

; #define PG8_STAGE(bufoff, gbase, voff) do { _Pragma("unroll") for (int _i = 0; _i < 2; ++_i) \
;     __builtin_amdgcn_global_load_lds((const unsigned*)((const char*)(gbase) + (voff)[_i]), (LAS unsigned*)(lds + (bufoff) + ldsw + _i * 8192), 16, 0, 0); } while (0)
; #define PG8_WAIT_V(n) asm volatile("s_waitcnt vmcnt(" #n ")" ::: "memory")
; #define PG8_BAR __builtin_amdgcn_s_barrier()
; #define PG8_WAIT_V(n) asm volatile("s_waitcnt vmcnt(" #n ")" ::: "memory")
; #define PG8_BAR __builtin_amdgcn_s_barrier()
; template <class Epi>
; DI void gemm_phase(char* smem, const bf16_t* A, int lda, const bf16_t* Bt, int ldb, int K, const Order& S_, const Epi& E) {
;     ...
;   for (int i = 0; i < 2; ++i) { int R, C; stage_rc(tid * 16 + i * 8192, R, C); const int Rb = Epi::PERM ? ((R & ~31) + perm32(R & 31)) : R;
;     voffA[i] = (unsigned)(R * lda + C) * 2u; voffB[i] = (unsigned)(Rb * ldb + C) * 2u; }
;     ...
;   PG8_STAGE(PG8_SB(0, 0), cB, voffB); PG8_STAGE(PG8_SA(0, 0), cA, voffA); PG8_STAGE(PG8_SB(0, 1), cB + hstepB, voffB); PG8_STAGE(PG8_SA(0, 1), cA + hstepA, voffA);
;   if (wr == 1) PG8_BAR;
;   PG8_WAIT_V(4); PG8_BAR;
;   PG8_STAGE(PG8_SB(1, 0), cB + kstep, voffB); PG8_STAGE(PG8_SA(1, 0), cA + kstep, voffA); PG8_STAGE(PG8_SB(1, 1), cB + hstepB + kstep, voffB);
;   PG8_WAIT_V(6); PG8_BAR;
.LBB0_1920:
	v_bfe_u32 v17, v9, 4, 2
	v_and_b32_e32 v18, 15, v9
	v_lshlrev_b32_e32 v19, 4, v17
	v_lshlrev_b32_e32 v9, 2, v9
	v_lshl_or_b32 v152, s0, 6, v18
	v_lshl_or_b32 v18, v18, 6, v19
	s_lshl_b32 s0, s0, 13
	v_and_b32_e32 v9, 32, v9
	v_bitop3_b32 v19, v18, s0, v9 bitop3:0xde
	s_lshl_b32 s0, s4, 5
	s_and_b32 s4, s0, 0x60
	s_add_i32 m0, s27, 0x18000
	v_lshl_add_u64 v[6:7], v[6:7], 0, s[58:59]
	s_lshl_b32 s0, s4, 7
	s_waitcnt vmcnt(4)
	s_barrier
	global_load_lds_dwordx4 v[6:7], off
	v_lshl_add_u64 v[4:5], v[4:5], 0, s[58:59]
	s_add_i32 m0, s27, 0x1a000
	s_add_i32 s38, s27, 0x8000
	s_add_i32 s20, s27, 0xa000
	v_bitop3_b32 v153, v18, s0, v9 bitop3:0xde
	global_load_lds_dwordx4 v[4:5], off
	v_lshl_add_u64 v[2:3], v[2:3], 0, s[58:59]
	s_mov_b32 m0, s38
	s_add_u32 s0, s44, 0xb0080
	s_sext_i32_i8 s49, s1
	global_load_lds_dwordx4 v[2:3], off
	v_lshl_add_u64 v[0:1], v[0:1], 0, s[58:59]
	s_mov_b32 m0, s20
	s_addc_u32 s1, s45, 0
	global_load_lds_dwordx4 v[0:1], off
	s_add_i32 m0, s27, 0x1c000
	global_load_lds_dwordx4 v220, s[0:1]
	s_add_i32 m0, s27, 0x1e000
	v_lshl_or_b32 v154, v17, 2, s4
	global_load_lds_dwordx4 v144, s[0:1]
	v_lshrrev_b32_e32 v1, 1, v8
	v_mul_lo_u32 v0, v11, s40
	s_mov_b32 s4, 0xb000
	v_mad_u64_u32 v[0:1], s[0:1], v1, s4, v[0:1]
	v_or_b32_e32 v0, v0, v10
	v_add_lshl_u32 v0, v0, v12, 1
	v_mov_b32_e32 v1, v221
	s_mov_b64 s[36:37], 0xb0080
	v_lshl_add_u64 v[146:147], v[0:1], 0, s[36:37]
	v_lshrrev_b32_e32 v1, 1, v13
	v_mul_lo_u32 v0, v15, s40
	v_mad_u64_u32 v[0:1], s[0:1], v1, s4, v[0:1]
	s_waitcnt vmcnt(6)
	v_or_b32_e32 v0, v0, v14
	v_add_lshl_u32 v0, v0, v16, 1
	v_mov_b32_e32 v1, v221
	s_mov_b32 s87, s61
	v_lshl_add_u64 v[148:149], v[0:1], 0, s[36:37]
	s_mov_b32 s16, 0
	v_add_u32_e32 v155, 0, v19
	s_barrier

; #define PG8_STAGE(bufoff, gbase, voff) do { _Pragma("unroll") for (int _i = 0; _i < 2; ++_i) \
;     __builtin_amdgcn_global_load_lds((const unsigned*)((const char*)(gbase) + (voff)[_i]), (LAS unsigned*)(lds + (bufoff) + ldsw + _i * 8192), 16, 0, 0); } while (0)
; #define PG8_LDA(dst, b, h) do { _Pragma("unroll") for (int m = 0; m < 4; ++m) _Pragma("unroll") for (int k = 0; k < 2; ++k) dst[m][k] = *(const LAS bf16x8*)(lds + PG8_SA(b, h) + aoff + m * 2048 + k * 1024); } while (0)
; #define PG8_LDB(dst, b, h) do { _Pragma("unroll") for (int n = 0; n < 2; ++n) _Pragma("unroll") for (int k = 0; k < 2; ++k) dst[n][k] = *(const LAS bf16x8*)(lds + PG8_SB(b, h) + boff + n * 2048 + k * 1024); } while (0)
; #define PG8_MMA(ai, bj, At, Bt_) do { __builtin_amdgcn_s_setprio(1); _Pragma("unroll") for (int m = 0; m < 4; ++m) _Pragma("unroll") for (int n = 0; n < 2; ++n) _Pragma("unroll") for (int k = 0; k < 2; ++k) \
;     acc[ai][bj][m][n] = __builtin_amdgcn_mfma_f32_16x16x32_bf16(Bt_[n][k], At[m][k], acc[ai][bj][m][n], 0, 0, 0); __builtin_amdgcn_s_setprio(0); } while (0)
; #define PG8_WAIT_V(n) asm volatile("s_waitcnt vmcnt(" #n ")" ::: "memory")
; #define PG8_WAIT_L(n) asm volatile("s_waitcnt lgkmcnt(" #n ")" ::: "memory")
; #define PG8_BAR __builtin_amdgcn_s_barrier()
; #define PG8_SCHED __builtin_amdgcn_sched_barrier(0)
; template <class Epi>
; DI void gemm_phase(char* smem, const bf16_t* A, int lda, const bf16_t* Bt, int ldb, int K, const Order& S_, const Epi& E) {
;     ...
;     for (int t = 0; t < nt; t += 2) {
;       const bool last = (t == nt - 2);
;       const char* a1 = cA + (size_t)(t + 1) * kstep;
;       const char* a2 = last ? nA : cA + (size_t)(t + 2) * kstep; const char* b2 = last ? nB : cB + (size_t)(t + 2) * kstep;
;       const char* a3 = a2 + kstep; const char* b3 = b2 + kstep;
;       PG8_LDB(B0, 0, 0); PG8_SCHED; PG8_LDA(At, 0, 0); PG8_STAGE(PG8_SA(1, 1), a1 + hstepA, voffA);
;       PG8_WAIT_L(8); PG8_BAR; PG8_WAIT_L(0); PG8_MMA(0, 0, At, B0); PG8_BAR; PG8_SCHED;
;       PG8_LDB(B1, 0, 1); PG8_STAGE(PG8_SB(0, 0), b2, voffB);
;       PG8_BAR; PG8_WAIT_L(0); PG8_MMA(0, 1, At, B1); PG8_BAR;
;       PG8_LDA(At, 0, 1); PG8_STAGE(PG8_SA(0, 0), a2, voffA);
;       PG8_BAR; PG8_WAIT_L(0); PG8_MMA(1, 0, At, B0); PG8_BAR; PG8_SCHED;
;       PG8_STAGE(PG8_SB(0, 1), b2 + hstepB, voffB);
;       PG8_WAIT_V(6); PG8_BAR; PG8_MMA(1, 1, At, B1); PG8_BAR;
.LBB0_1929:
	s_add_u32 s44, s42, 0x100
	s_addc_u32 s45, s43, 0
	s_add_i32 s57, 0, 0x10000
	v_add_u32_e32 v140, s57, v153
	ds_read_b128 v[128:131], v140
	ds_read_b128 v[132:135], v140 offset:1024
	ds_read_b128 v[136:139], v140 offset:2048
	ds_read_b128 v[140:143], v140 offset:3072
	s_cmp_eq_u32 s56, 40
	s_cselect_b32 s51, s1, s45
	s_cselect_b32 s50, s0, s44
	s_cselect_b32 s47, s41, s53
	s_cselect_b32 s46, s40, s52
	v_lshl_add_u64 v[150:151], s[42:43], 0, v[146:147]
	s_add_i32 m0, s27, 0xc000
	ds_read_b128 v[156:159], v155
	ds_read_b128 v[160:163], v155 offset:1024
	ds_read_b128 v[164:167], v155 offset:2048
	ds_read_b128 v[168:171], v155 offset:3072
	ds_read_b128 v[172:175], v155 offset:4096
	ds_read_b128 v[176:179], v155 offset:5120
	ds_read_b128 v[180:183], v155 offset:6144
	ds_read_b128 v[184:187], v155 offset:7168
	global_load_lds_dwordx4 v[150:151], off
	v_lshl_add_u64 v[150:151], s[42:43], 0, v[148:149]
	s_add_i32 m0, s27, 0xe000
	s_nop 0
	global_load_lds_dwordx4 v[150:151], off
	s_waitcnt lgkmcnt(8)
	s_barrier
	s_waitcnt lgkmcnt(0)
	s_setprio 1
	s_waitcnt lgkmcnt(0)
	v_mfma_f32_16x16x32_bf16 v[124:127], v[128:131], v[156:159], v[124:127]
	v_mfma_f32_16x16x32_bf16 v[120:123], v[136:139], v[156:159], v[120:123]
	v_mfma_f32_16x16x32_bf16 v[116:119], v[128:131], v[164:167], v[116:119]
	v_mfma_f32_16x16x32_bf16 v[108:111], v[136:139], v[164:167], v[108:111]
	v_mfma_f32_16x16x32_bf16 v[92:95], v[128:131], v[172:175], v[92:95]
	v_mfma_f32_16x16x32_bf16 v[88:91], v[136:139], v[172:175], v[88:91]
	v_mfma_f32_16x16x32_bf16 v[84:87], v[128:131], v[180:183], v[84:87]
	v_mfma_f32_16x16x32_bf16 v[80:83], v[136:139], v[180:183], v[80:83]
	v_mfma_f32_16x16x32_bf16 v[124:127], v[132:135], v[160:163], v[124:127]
	v_mfma_f32_16x16x32_bf16 v[120:123], v[140:143], v[160:163], v[120:123]
	v_mfma_f32_16x16x32_bf16 v[116:119], v[132:135], v[168:171], v[116:119]
	v_mfma_f32_16x16x32_bf16 v[108:111], v[140:143], v[168:171], v[108:111]
	v_mfma_f32_16x16x32_bf16 v[92:95], v[132:135], v[176:179], v[92:95]
	v_mfma_f32_16x16x32_bf16 v[88:91], v[140:143], v[176:179], v[88:91]
	v_mfma_f32_16x16x32_bf16 v[84:87], v[132:135], v[184:187], v[84:87]
	v_mfma_f32_16x16x32_bf16 v[80:83], v[140:143], v[184:187], v[80:83]
	s_setprio 0
	s_barrier
	s_add_i32 s60, 0, 0x14000
	v_add_u32_e32 v150, s60, v153
	s_add_i32 s42, s57, s15
	ds_read_b128 v[188:191], v150
	ds_read_b128 v[210:213], v150 offset:1024
	ds_read_b128 v[214:217], v150 offset:2048
	ds_read_b128 v[234:237], v150 offset:3072
	v_lshl_add_u64 v[150:151], s[46:47], 0, v[220:221]
	s_mov_b32 m0, s42
	v_lshl_add_u64 v[194:195], s[46:47], 0, v[144:145]
	global_load_lds_dwordx4 v[150:151], off
	s_add_i32 m0, s42, 0x2000
	s_nop 0
	global_load_lds_dwordx4 v[194:195], off
	s_barrier
	s_waitcnt lgkmcnt(0)
	s_setprio 1
	s_waitcnt lgkmcnt(0)
	v_mfma_f32_16x16x32_bf16 v[112:115], v[188:191], v[156:159], v[112:115]
	v_mfma_f32_16x16x32_bf16 v[104:107], v[214:217], v[156:159], v[104:107]
	v_mfma_f32_16x16x32_bf16 v[100:103], v[188:191], v[164:167], v[100:103]
	v_mfma_f32_16x16x32_bf16 v[96:99], v[214:217], v[164:167], v[96:99]
	v_mfma_f32_16x16x32_bf16 v[76:79], v[188:191], v[172:175], v[76:79]
	v_mfma_f32_16x16x32_bf16 v[72:75], v[214:217], v[172:175], v[72:75]
	v_mfma_f32_16x16x32_bf16 v[68:71], v[188:191], v[180:183], v[68:71]
	v_mfma_f32_16x16x32_bf16 v[64:67], v[214:217], v[180:183], v[64:67]
	v_mfma_f32_16x16x32_bf16 v[112:115], v[210:213], v[160:163], v[112:115]
	v_mfma_f32_16x16x32_bf16 v[104:107], v[234:237], v[160:163], v[104:107]
	v_mfma_f32_16x16x32_bf16 v[100:103], v[210:213], v[168:171], v[100:103]
	v_mfma_f32_16x16x32_bf16 v[96:99], v[234:237], v[168:171], v[96:99]
	v_mfma_f32_16x16x32_bf16 v[76:79], v[210:213], v[176:179], v[76:79]
	v_mfma_f32_16x16x32_bf16 v[72:75], v[234:237], v[176:179], v[72:75]
	v_mfma_f32_16x16x32_bf16 v[68:71], v[210:213], v[184:187], v[68:71]
	v_mfma_f32_16x16x32_bf16 v[64:67], v[234:237], v[184:187], v[64:67]
	s_setprio 0
	s_mov_b32 m0, s27
	v_lshl_add_u64 v[200:201], s[50:51], 0, v[220:221]
	s_barrier
	ds_read_b128 v[156:159], v155 offset:16384
	ds_read_b128 v[160:163], v155 offset:17408
	ds_read_b128 v[164:167], v155 offset:18432
	ds_read_b128 v[168:171], v155 offset:19456
	ds_read_b128 v[172:175], v155 offset:20480
	ds_read_b128 v[176:179], v155 offset:21504
	ds_read_b128 v[180:183], v155 offset:22528
	ds_read_b128 v[184:187], v155 offset:23552
	global_load_lds_dwordx4 v[200:201], off
	v_lshl_add_u64 v[202:203], s[50:51], 0, v[144:145]
	s_mov_b32 m0, s29
	s_nop 0
	global_load_lds_dwordx4 v[202:203], off
	s_barrier
	s_waitcnt lgkmcnt(0)
	s_setprio 1
	s_waitcnt lgkmcnt(0)
	v_mfma_f32_16x16x32_bf16 v[60:63], v[128:131], v[156:159], v[60:63]
	v_mfma_f32_16x16x32_bf16 v[56:59], v[136:139], v[156:159], v[56:59]
	v_mfma_f32_16x16x32_bf16 v[52:55], v[128:131], v[164:167], v[52:55]
	v_mfma_f32_16x16x32_bf16 v[48:51], v[136:139], v[164:167], v[48:51]
	v_mfma_f32_16x16x32_bf16 v[28:31], v[128:131], v[172:175], v[28:31]
	v_mfma_f32_16x16x32_bf16 v[24:27], v[136:139], v[172:175], v[24:27]
	v_mfma_f32_16x16x32_bf16 v[20:23], v[128:131], v[180:183], v[20:23]
	v_mfma_f32_16x16x32_bf16 v[16:19], v[136:139], v[180:183], v[16:19]
	v_mfma_f32_16x16x32_bf16 v[60:63], v[132:135], v[160:163], v[60:63]
	v_mfma_f32_16x16x32_bf16 v[56:59], v[140:143], v[160:163], v[56:59]
	v_mfma_f32_16x16x32_bf16 v[52:55], v[132:135], v[168:171], v[52:55]
	v_mfma_f32_16x16x32_bf16 v[48:51], v[140:143], v[168:171], v[48:51]
	v_mfma_f32_16x16x32_bf16 v[28:31], v[132:135], v[176:179], v[28:31]
	v_mfma_f32_16x16x32_bf16 v[24:27], v[140:143], v[176:179], v[24:27]
	v_mfma_f32_16x16x32_bf16 v[20:23], v[132:135], v[184:187], v[20:23]
	v_mfma_f32_16x16x32_bf16 v[16:19], v[140:143], v[184:187], v[16:19]
	s_setprio 0
	s_barrier
; #define PG8_STAGE(bufoff, gbase, voff) do { _Pragma("unroll") for (int _i = 0; _i < 2; ++_i) \
;     __builtin_amdgcn_global_load_lds((const unsigned*)((const char*)(gbase) + (voff)[_i]), (LAS unsigned*)(lds + (bufoff) + ldsw + _i * 8192), 16, 0, 0); } while (0)
; #define PG8_LDA(dst, b, h) do { _Pragma("unroll") for (int m = 0; m < 4; ++m) _Pragma("unroll") for (int k = 0; k < 2; ++k) dst[m][k] = *(const LAS bf16x8*)(lds + PG8_SA(b, h) + aoff + m * 2048 + k * 1024); } while (0)
; #define PG8_LDB(dst, b, h) do { _Pragma("unroll") for (int n = 0; n < 2; ++n) _Pragma("unroll") for (int k = 0; k < 2; ++k) dst[n][k] = *(const LAS bf16x8*)(lds + PG8_SB(b, h) + boff + n * 2048 + k * 1024); } while (0)
; #define PG8_MMA(ai, bj, At, Bt_) do { __builtin_amdgcn_s_setprio(1); _Pragma("unroll") for (int m = 0; m < 4; ++m) _Pragma("unroll") for (int n = 0; n < 2; ++n) _Pragma("unroll") for (int k = 0; k < 2; ++k) \
;     acc[ai][bj][m][n] = __builtin_amdgcn_mfma_f32_16x16x32_bf16(Bt_[n][k], At[m][k], acc[ai][bj][m][n], 0, 0, 0); __builtin_amdgcn_s_setprio(0); } while (0)
; #define PG8_WAIT_V(n) asm volatile("s_waitcnt vmcnt(" #n ")" ::: "memory")
; #define PG8_WAIT_L(n) asm volatile("s_waitcnt lgkmcnt(" #n ")" ::: "memory")
; #define PG8_BAR __builtin_amdgcn_s_barrier()
; #define PG8_SCHED __builtin_amdgcn_sched_barrier(0)
; #define PG8_LDA(dst, b, h) do { _Pragma("unroll") for (int m = 0; m < 4; ++m) _Pragma("unroll") for (int k = 0; k < 2; ++k) dst[m][k] = *(const LAS bf16x8*)(lds + PG8_SA(b, h) + aoff + m * 2048 + k * 1024); } while (0)
; #define PG8_WAIT_V(n) asm volatile("s_waitcnt vmcnt(" #n ")" ::: "memory")
; template <class Epi>
; DI void gemm_phase(char* smem, const bf16_t* A, int lda, const bf16_t* Bt, int ldb, int K, const Order& S_, const Epi& E) {
;     ...
;       PG8_STAGE(PG8_SB(0, 1), b2 + hstepB, voffB);
;       PG8_WAIT_V(6); PG8_BAR; PG8_MMA(1, 1, At, B1); PG8_BAR;
;       PG8_LDB(B0, 1, 0); PG8_SCHED; PG8_LDA(At, 1, 0); PG8_STAGE(PG8_SA(0, 1), a2 + hstepA, voffA);
;       PG8_WAIT_L(8); PG8_BAR; PG8_WAIT_L(0); PG8_MMA(0, 0, At, B0); PG8_BAR; PG8_SCHED;
;       PG8_LDB(B1, 1, 1); PG8_STAGE(PG8_SB(1, 0), b3, voffB);
;       PG8_BAR; PG8_WAIT_L(0); PG8_MMA(0, 1, At, B1); PG8_BAR;
;       PG8_LDA(At, 1, 1); PG8_STAGE(PG8_SA(1, 0), a3, voffA);
;       PG8_BAR; PG8_WAIT_L(0); PG8_MMA(1, 0, At, B0); PG8_BAR; PG8_SCHED;
	s_add_u32 s42, s46, 0xb0000
	s_addc_u32 s43, s47, 0
	s_add_i32 s57, s60, s15
	s_mov_b32 m0, s57
	s_nop 0
	global_load_lds_dwordx4 v220, s[42:43]
	s_add_i32 m0, s57, 0x2000
	s_nop 0
	global_load_lds_dwordx4 v144, s[42:43]
	s_waitcnt vmcnt(6)
	s_barrier
	s_setprio 1
	v_mfma_f32_16x16x32_bf16 v[44:47], v[188:191], v[156:159], v[44:47]
	v_mfma_f32_16x16x32_bf16 v[40:43], v[214:217], v[156:159], v[40:43]
	v_mfma_f32_16x16x32_bf16 v[36:39], v[188:191], v[164:167], v[36:39]
	v_mfma_f32_16x16x32_bf16 v[32:35], v[214:217], v[164:167], v[32:35]
	v_mfma_f32_16x16x32_bf16 v[12:15], v[188:191], v[172:175], v[12:15]
	v_mfma_f32_16x16x32_bf16 v[8:11], v[214:217], v[172:175], v[8:11]
	v_mfma_f32_16x16x32_bf16 v[4:7], v[188:191], v[180:183], v[4:7]
	v_mfma_f32_16x16x32_bf16 v[0:3], v[214:217], v[180:183], v[0:3]
	v_mfma_f32_16x16x32_bf16 v[44:47], v[210:213], v[160:163], v[44:47]
	v_mfma_f32_16x16x32_bf16 v[40:43], v[234:237], v[160:163], v[40:43]
	v_mfma_f32_16x16x32_bf16 v[36:39], v[210:213], v[168:171], v[36:39]
	v_mfma_f32_16x16x32_bf16 v[32:35], v[234:237], v[168:171], v[32:35]
	v_mfma_f32_16x16x32_bf16 v[12:15], v[210:213], v[176:179], v[12:15]
	v_mfma_f32_16x16x32_bf16 v[8:11], v[234:237], v[176:179], v[8:11]
	v_mfma_f32_16x16x32_bf16 v[4:7], v[210:213], v[184:187], v[4:7]
	v_mfma_f32_16x16x32_bf16 v[0:3], v[234:237], v[184:187], v[0:3]
	s_setprio 0
	s_add_i32 s57, 0, 0x18000
	v_add_u32_e32 v140, s57, v153
	s_barrier
	ds_read_b128 v[128:131], v140
	ds_read_b128 v[132:135], v140 offset:1024
	ds_read_b128 v[136:139], v140 offset:2048
	ds_read_b128 v[140:143], v140 offset:3072
	s_add_u32 s42, s50, 0xb0000
	s_addc_u32 s43, s51, 0
	s_mov_b32 m0, s33
	ds_read_b128 v[156:159], v155 offset:32768
	ds_read_b128 v[160:163], v155 offset:33792
	ds_read_b128 v[164:167], v155 offset:34816
	ds_read_b128 v[168:171], v155 offset:35840
	ds_read_b128 v[172:175], v155 offset:36864
	ds_read_b128 v[176:179], v155 offset:37888
	ds_read_b128 v[180:183], v155 offset:38912
	ds_read_b128 v[184:187], v155 offset:39936
	global_load_lds_dwordx4 v220, s[42:43]
	s_mov_b32 m0, s34
	s_nop 0
	global_load_lds_dwordx4 v144, s[42:43]
	s_waitcnt lgkmcnt(8)
	s_barrier
	s_waitcnt lgkmcnt(0)
	s_setprio 1
	s_waitcnt lgkmcnt(0)
	v_mfma_f32_16x16x32_bf16 v[124:127], v[128:131], v[156:159], v[124:127]
	v_mfma_f32_16x16x32_bf16 v[120:123], v[136:139], v[156:159], v[120:123]
	v_mfma_f32_16x16x32_bf16 v[116:119], v[128:131], v[164:167], v[116:119]
	v_mfma_f32_16x16x32_bf16 v[108:111], v[136:139], v[164:167], v[108:111]
	v_mfma_f32_16x16x32_bf16 v[92:95], v[128:131], v[172:175], v[92:95]
	v_mfma_f32_16x16x32_bf16 v[88:91], v[136:139], v[172:175], v[88:91]
	v_mfma_f32_16x16x32_bf16 v[84:87], v[128:131], v[180:183], v[84:87]
	v_mfma_f32_16x16x32_bf16 v[80:83], v[136:139], v[180:183], v[80:83]
	v_mfma_f32_16x16x32_bf16 v[124:127], v[132:135], v[160:163], v[124:127]
	v_mfma_f32_16x16x32_bf16 v[120:123], v[140:143], v[160:163], v[120:123]
	v_mfma_f32_16x16x32_bf16 v[116:119], v[132:135], v[168:171], v[116:119]
	v_mfma_f32_16x16x32_bf16 v[108:111], v[140:143], v[168:171], v[108:111]
	v_mfma_f32_16x16x32_bf16 v[92:95], v[132:135], v[176:179], v[92:95]
	v_mfma_f32_16x16x32_bf16 v[88:91], v[140:143], v[176:179], v[88:91]
	v_mfma_f32_16x16x32_bf16 v[84:87], v[132:135], v[184:187], v[84:87]
	v_mfma_f32_16x16x32_bf16 v[80:83], v[140:143], v[184:187], v[80:83]
	s_setprio 0
	s_barrier
	s_add_i32 s50, 0, 0x1c000
	s_add_i32 s42, s57, s15
	v_add_u32_e32 v204, s50, v153
	v_lshl_add_u64 v[150:151], v[150:151], 0, s[58:59]
	s_mov_b32 m0, s42
	ds_read_b128 v[188:191], v204
	ds_read_b128 v[210:213], v204 offset:1024
	ds_read_b128 v[214:217], v204 offset:2048
	ds_read_b128 v[234:237], v204 offset:3072
	global_load_lds_dwordx4 v[150:151], off
	v_lshl_add_u64 v[150:151], v[194:195], 0, s[58:59]
	s_add_i32 m0, s42, 0x2000
	s_nop 0
	global_load_lds_dwordx4 v[150:151], off
	s_barrier
	s_waitcnt lgkmcnt(0)
	s_setprio 1
	s_waitcnt lgkmcnt(0)
	v_mfma_f32_16x16x32_bf16 v[112:115], v[188:191], v[156:159], v[112:115]
	v_mfma_f32_16x16x32_bf16 v[104:107], v[214:217], v[156:159], v[104:107]
	v_mfma_f32_16x16x32_bf16 v[100:103], v[188:191], v[164:167], v[100:103]
	v_mfma_f32_16x16x32_bf16 v[96:99], v[214:217], v[164:167], v[96:99]
	v_mfma_f32_16x16x32_bf16 v[76:79], v[188:191], v[172:175], v[76:79]
	v_mfma_f32_16x16x32_bf16 v[72:75], v[214:217], v[172:175], v[72:75]
	v_mfma_f32_16x16x32_bf16 v[68:71], v[188:191], v[180:183], v[68:71]
	v_mfma_f32_16x16x32_bf16 v[64:67], v[214:217], v[180:183], v[64:67]
	v_mfma_f32_16x16x32_bf16 v[112:115], v[210:213], v[160:163], v[112:115]
	v_mfma_f32_16x16x32_bf16 v[104:107], v[234:237], v[160:163], v[104:107]
	v_mfma_f32_16x16x32_bf16 v[100:103], v[210:213], v[168:171], v[100:103]
	v_mfma_f32_16x16x32_bf16 v[96:99], v[234:237], v[168:171], v[96:99]
	v_mfma_f32_16x16x32_bf16 v[76:79], v[210:213], v[176:179], v[76:79]
	v_mfma_f32_16x16x32_bf16 v[72:75], v[234:237], v[176:179], v[72:75]
	v_mfma_f32_16x16x32_bf16 v[68:71], v[210:213], v[184:187], v[68:71]
	v_mfma_f32_16x16x32_bf16 v[64:67], v[234:237], v[184:187], v[64:67]
	s_setprio 0
	s_mov_b32 m0, s38
	v_lshl_add_u64 v[150:151], v[200:201], 0, s[58:59]
	s_barrier
	ds_read_b128 v[156:159], v155 offset:49152
	ds_read_b128 v[160:163], v155 offset:50176
	ds_read_b128 v[164:167], v155 offset:51200
	ds_read_b128 v[168:171], v155 offset:52224
	ds_read_b128 v[172:175], v155 offset:53248
	ds_read_b128 v[176:179], v155 offset:54272
	ds_read_b128 v[180:183], v155 offset:55296
	ds_read_b128 v[184:187], v155 offset:56320
	global_load_lds_dwordx4 v[150:151], off
	v_lshl_add_u64 v[150:151], v[202:203], 0, s[58:59]
	s_mov_b32 m0, s20
	s_nop 0
	global_load_lds_dwordx4 v[150:151], off
	s_barrier
; #define MEMBAR() asm volatile("" ::: "memory")
; DI float* modp(const Params& p, int layer, int g, int chunk) { return (float*)(p.ws + OFF_MOD) + ((size_t)(layer * 9 + g) * 6 + chunk) * 1024; }
; #define PG8_STAGE(bufoff, gbase, voff) do { _Pragma("unroll") for (int _i = 0; _i < 2; ++_i) \
;     __builtin_amdgcn_global_load_lds((const unsigned*)((const char*)(gbase) + (voff)[_i]), (LAS unsigned*)(lds + (bufoff) + ldsw + _i * 8192), 16, 0, 0); } while (0)
; #define PG8_WAIT_V(n) asm volatile("s_waitcnt vmcnt(" #n ")" ::: "memory")
; #define PG8_BAR __builtin_amdgcn_s_barrier()
; #define PG8_WAIT_V(n) asm volatile("s_waitcnt vmcnt(" #n ")" ::: "memory")
; #define PG8_BAR __builtin_amdgcn_s_barrier()
; template <class Epi>
; DI void gemm_phase(char* smem, const bf16_t* A, int lda, const bf16_t* Bt, int ldb, int K, const Order& S_, const Epi& E) {
;     ...
;       PG8_STAGE(PG8_SB(1, 1), b3 + hstepB, voffB);
;       PG8_WAIT_V(6); PG8_BAR; PG8_MMA(1, 1, At, B1); PG8_BAR;
;     }
;     E(acc, cur, wr, wc, fr, fq);
;   DI void operator()(const acc_t& acc, const Unit& u, int wr, int wc, int fr, int fq) const {
;     const int row0 = u.pm * BM + wr * 64 + fr, col0 = u.pn * BM + wc * 32 + 4 * fq;
;     const int b = u.pm / 17, g = (u.pm - b * 17) == 0 ? 8 : b;
;     const float* gate = modp(p, layer, g, chunk);
;     f32x4 gv[2][2];
; #pragma unroll
;     for (int bj = 0; bj < 2; ++bj)
; #pragma unroll
;       for (int n = 0; n < 2; ++n) gv[bj][n] = *(const f32x4*)(gate + col0 + bj * HALF + n * 16);
; #pragma unroll
;     for (int q = 0; q < 4; ++q) {
;       const int ai = q >> 1, mh = q & 1;
;       MEMBAR();
;       f32x4 xv[2][2][2];
; #pragma unroll
;       for (int mm = 0; mm < 2; ++mm) { const int t = row0 + ai * HALF + (2 * mh + mm) * 16;
;         const float* xi = from_input ? xrow_in(p, t) : xrow_ws(p, t);
; #pragma unroll
;         for (int bj = 0; bj < 2; ++bj)
; #pragma unroll
;           for (int n = 0; n < 2; ++n) xv[mm][bj][n] = *(const f32x4*)(xi + col0 + bj * HALF + n * 16); }
;       MEMBAR();
; #pragma unroll
;       for (int mm = 0; mm < 2; ++mm) { const int t = row0 + ai * HALF + (2 * mh + mm) * 16;
;         float* xo = xrow_ws(p, t);
; #pragma unroll
;         for (int bj = 0; bj < 2; ++bj)
; #pragma unroll
;           for (int n = 0; n < 2; ++n) *(f32x4*)(xo + col0 + bj * HALF + n * 16) = xv[mm][bj][n] + gv[bj][n] * acc[ai][bj][2 * mh + mm][n]; }
	s_waitcnt lgkmcnt(0)
	s_setprio 1
	s_waitcnt lgkmcnt(0)
	v_mfma_f32_16x16x32_bf16 v[60:63], v[128:131], v[156:159], v[60:63]
	v_mfma_f32_16x16x32_bf16 v[56:59], v[136:139], v[156:159], v[56:59]
	v_mfma_f32_16x16x32_bf16 v[52:55], v[128:131], v[164:167], v[52:55]
	v_mfma_f32_16x16x32_bf16 v[48:51], v[136:139], v[164:167], v[48:51]
	v_mfma_f32_16x16x32_bf16 v[28:31], v[128:131], v[172:175], v[28:31]
	v_mfma_f32_16x16x32_bf16 v[24:27], v[136:139], v[172:175], v[24:27]
	v_mfma_f32_16x16x32_bf16 v[20:23], v[128:131], v[180:183], v[20:23]
	v_mfma_f32_16x16x32_bf16 v[16:19], v[136:139], v[180:183], v[16:19]
	v_mfma_f32_16x16x32_bf16 v[60:63], v[132:135], v[160:163], v[60:63]
	v_mfma_f32_16x16x32_bf16 v[56:59], v[140:143], v[160:163], v[56:59]
	v_mfma_f32_16x16x32_bf16 v[52:55], v[132:135], v[168:171], v[52:55]
	v_mfma_f32_16x16x32_bf16 v[48:51], v[140:143], v[168:171], v[48:51]
	v_mfma_f32_16x16x32_bf16 v[28:31], v[132:135], v[176:179], v[28:31]
	v_mfma_f32_16x16x32_bf16 v[24:27], v[140:143], v[176:179], v[24:27]
	v_mfma_f32_16x16x32_bf16 v[20:23], v[132:135], v[184:187], v[20:23]
	v_mfma_f32_16x16x32_bf16 v[16:19], v[140:143], v[184:187], v[16:19]
	s_setprio 0
	s_barrier
	s_add_u32 s42, s46, 0xb0080
	s_addc_u32 s43, s47, 0
	s_add_i32 s46, s50, s15
	s_mov_b32 m0, s46
	s_nop 0
	global_load_lds_dwordx4 v220, s[42:43]
	s_add_i32 m0, s46, 0x2000
	s_nop 0
	global_load_lds_dwordx4 v144, s[42:43]
	s_waitcnt vmcnt(6)
	s_barrier
	s_setprio 1
	v_mfma_f32_16x16x32_bf16 v[44:47], v[188:191], v[156:159], v[44:47]
	v_mfma_f32_16x16x32_bf16 v[40:43], v[214:217], v[156:159], v[40:43]
	v_mfma_f32_16x16x32_bf16 v[36:39], v[188:191], v[164:167], v[36:39]
	v_mfma_f32_16x16x32_bf16 v[32:35], v[214:217], v[164:167], v[32:35]
	v_mfma_f32_16x16x32_bf16 v[12:15], v[188:191], v[172:175], v[12:15]
	v_mfma_f32_16x16x32_bf16 v[8:11], v[214:217], v[172:175], v[8:11]
	v_mfma_f32_16x16x32_bf16 v[4:7], v[188:191], v[180:183], v[4:7]
	v_mfma_f32_16x16x32_bf16 v[0:3], v[214:217], v[180:183], v[0:3]
	v_mfma_f32_16x16x32_bf16 v[44:47], v[210:213], v[160:163], v[44:47]
	v_mfma_f32_16x16x32_bf16 v[40:43], v[234:237], v[160:163], v[40:43]
	v_mfma_f32_16x16x32_bf16 v[36:39], v[210:213], v[168:171], v[36:39]
	v_mfma_f32_16x16x32_bf16 v[32:35], v[234:237], v[168:171], v[32:35]
	v_mfma_f32_16x16x32_bf16 v[12:15], v[210:213], v[176:179], v[12:15]
	v_mfma_f32_16x16x32_bf16 v[8:11], v[234:237], v[176:179], v[8:11]
	v_mfma_f32_16x16x32_bf16 v[4:7], v[210:213], v[184:187], v[4:7]
	v_mfma_f32_16x16x32_bf16 v[0:3], v[234:237], v[184:187], v[0:3]
	s_setprio 0
	s_add_i32 s56, s56, 2
	s_add_u32 s52, s52, 0x100
	s_addc_u32 s53, s53, 0
	s_cmp_gt_u32 s56, 41
	s_mov_b64 s[42:43], s[44:45]
	s_barrier
	s_cbranch_scc0 .LBB0_1929
	v_lshl_add_u32 v157, s39, 8, v152
	s_mov_b32 s51, 0x78787879
	v_mul_hi_i32 v156, v157, s51
	v_lshrrev_b32_e32 v158, 31, v156
	v_ashrrev_i32_e32 v156, 11, v156
	v_add_u32_e32 v162, v156, v158
	s_mul_hi_i32 s42, s39, 0x78787879
	v_mad_i32_i24 v161, v162, s80, v157
	s_movk_i32 s50, 0x100
	s_lshr_b32 s43, s42, 31
	s_ashr_i32 s42, s42, 3
	v_ashrrev_i32_e32 v166, 31, v161
	v_add_u32_e32 v168, 0xffffff00, v161
	v_cmp_gt_i32_e32 vcc, s50, v161
	s_add_i32 s42, s42, s43
	v_ashrrev_i32_e32 v163, 31, v162
	v_cndmask_b32_e32 v167, 0, v166, vcc
	v_cndmask_b32_e32 v166, v168, v161, vcc
	v_cndmask_b32_e64 v161, 24, 20, vcc
	s_mul_i32 s43, s42, 0xffffffef
	s_sub_i32 s44, 0, s39
	v_lshlrev_b64 v[162:163], v161, v[162:163]
	v_or_b32_e32 v161, 16, v157
	s_cmp_lg_u32 s43, s44
	v_mul_hi_i32 v178, v161, s51
	s_cselect_b32 s42, s42, 8
	v_readlane_b32 s43, v254, 59
	v_lshrrev_b32_e32 v179, 31, v178
	v_ashrrev_i32_e32 v178, 11, v178
	s_add_i32 s42, s42, s43
	v_readlane_b32 s39, v254, 42
	v_add_u32_e32 v178, v178, v179
	s_mul_i32 s42, s42, 6
	v_mov_b32_e32 v156, s93
	v_mov_b32_e32 v158, s83
	v_mov_b32_e32 v159, s92
	v_mov_b32_e32 v160, s39
	v_mad_i32_i24 v161, v178, s80, v161
	s_ashr_i32 s43, s42, 31
	v_cndmask_b32_e32 v165, v156, v158, vcc
	v_cndmask_b32_e32 v164, v159, v160, vcc
	v_cmp_gt_i32_e32 vcc, s50, v161
	v_lshl_or_b32 v128, s49, 8, v154
	s_lshl_b64 s[42:43], s[42:43], 12
	v_readlane_b32 s44, v253, 29
	v_ashrrev_i32_e32 v179, 31, v178
	v_cndmask_b32_e64 v180, 24, 20, vcc
	v_ashrrev_i32_e32 v182, 31, v161
	v_add_u32_e32 v184, 0xffffff00, v161
	s_add_u32 s42, s44, s42
	v_readlane_b32 s44, v253, 30
	v_ashrrev_i32_e32 v129, 31, v128
	v_lshlrev_b64 v[178:179], v180, v[178:179]
	v_cndmask_b32_e32 v181, v156, v158, vcc
	v_cndmask_b32_e32 v180, v159, v160, vcc
	v_cndmask_b32_e32 v183, 0, v182, vcc
	v_cndmask_b32_e32 v182, v184, v161, vcc
	s_addc_u32 s43, s44, s43
	v_lshlrev_b64 v[150:151], 2, v[128:129]
	v_lshl_add_u64 v[162:163], v[164:165], 0, v[162:163]
	v_lshlrev_b64 v[164:165], 12, v[166:167]
	v_lshl_add_u64 v[178:179], v[180:181], 0, v[178:179]
	v_lshlrev_b64 v[180:181], 12, v[182:183]
	v_lshl_add_u64 v[128:129], s[42:43], 0, v[150:151]
	v_lshl_add_u64 v[162:163], v[162:163], 0, v[164:165]
	v_lshl_add_u64 v[178:179], v[178:179], 0, v[180:181]
	global_load_dwordx4 v[140:143], v[128:129], off
	global_load_dwordx4 v[136:139], v[128:129], off offset:64
	global_load_dwordx4 v[132:135], v[128:129], off offset:512
	s_nop 0
	global_load_dwordx4 v[128:131], v[128:129], off offset:576
	v_lshl_add_u64 v[190:191], v[162:163], 0, v[150:151]
	v_lshl_add_u64 v[194:195], v[178:179], 0, v[150:151]
	global_load_dwordx4 v[162:165], v[190:191], off
	global_load_dwordx4 v[166:169], v[190:191], off offset:64
	global_load_dwordx4 v[170:173], v[190:191], off offset:512
	global_load_dwordx4 v[174:177], v[190:191], off offset:576
	global_load_dwordx4 v[178:181], v[194:195], off
	global_load_dwordx4 v[182:185], v[194:195], off offset:64
	global_load_dwordx4 v[186:189], v[194:195], off offset:512
	global_load_dwordx4 v[210:213], v[194:195], off offset:576
	v_add_u32_e32 v161, 0x80, v157
	v_readlane_b32 s46, v254, 46
	s_mov_b32 s49, s4
	s_mov_b32 s39, s5
	s_mov_b64 s[44:45], s[40:41]
	s_mov_b64 s[42:43], s[0:1]
	v_readlane_b32 s47, v254, 47
	s_waitcnt vmcnt(0)
; #define MEMBAR() asm volatile("" ::: "memory")
;   DI void operator()(const acc_t& acc, const Unit& u, int wr, int wc, int fr, int fq) const {
;     ...
;       for (int mm = 0; mm < 2; ++mm) { const int t = row0 + ai * HALF + (2 * mh + mm) * 16;
;         const float* xi = from_input ? xrow_in(p, t) : xrow_ws(p, t);
; #pragma unroll
;         for (int bj = 0; bj < 2; ++bj)
; #pragma unroll
;           for (int n = 0; n < 2; ++n) xv[mm][bj][n] = *(const f32x4*)(xi + col0 + bj * HALF + n * 16); }
;       MEMBAR();
; #pragma unroll
;       for (int mm = 0; mm < 2; ++mm) { const int t = row0 + ai * HALF + (2 * mh + mm) * 16;
;         float* xo = xrow_ws(p, t);
; #pragma unroll
;         for (int bj = 0; bj < 2; ++bj)
; #pragma unroll
;           for (int n = 0; n < 2; ++n) *(f32x4*)(xo + col0 + bj * HALF + n * 16) = xv[mm][bj][n] + gv[bj][n] * acc[ai][bj][2 * mh + mm][n]; }
	v_pk_fma_f32 v[126:127], v[126:127], v[142:143], v[164:165]
	v_pk_fma_f32 v[124:125], v[124:125], v[140:141], v[162:163]
	v_pk_fma_f32 v[122:123], v[122:123], v[138:139], v[168:169]
	v_pk_fma_f32 v[120:121], v[120:121], v[136:137], v[166:167]
	v_pk_fma_f32 v[98:99], v[98:99], v[130:131], v[212:213]
	v_pk_fma_f32 v[96:97], v[96:97], v[128:129], v[210:211]
	v_pk_fma_f32 v[114:115], v[114:115], v[134:135], v[172:173]
	v_pk_fma_f32 v[112:113], v[112:113], v[132:133], v[170:171]
	v_pk_fma_f32 v[106:107], v[106:107], v[130:131], v[176:177]
	v_pk_fma_f32 v[104:105], v[104:105], v[128:129], v[174:175]
	v_pk_fma_f32 v[118:119], v[118:119], v[142:143], v[180:181]
	v_pk_fma_f32 v[116:117], v[116:117], v[140:141], v[178:179]
	v_pk_fma_f32 v[110:111], v[110:111], v[138:139], v[184:185]
	v_pk_fma_f32 v[108:109], v[108:109], v[136:137], v[182:183]
	v_pk_fma_f32 v[102:103], v[102:103], v[134:135], v[188:189]
	v_pk_fma_f32 v[100:101], v[100:101], v[132:133], v[186:187]
	global_store_dwordx4 v[190:191], v[124:127], off
	global_store_dwordx4 v[190:191], v[120:123], off offset:64
	global_store_dwordx4 v[190:191], v[112:115], off offset:512
	global_store_dwordx4 v[190:191], v[104:107], off offset:576
	global_store_dwordx4 v[194:195], v[116:119], off
	global_store_dwordx4 v[194:195], v[108:111], off offset:64
	global_store_dwordx4 v[194:195], v[100:103], off offset:512
	global_store_dwordx4 v[194:195], v[96:99], off offset:576
	v_or_b32_e32 v113, 48, v157
	v_mul_hi_i32 v112, v113, s51
	v_or_b32_e32 v97, 32, v157
	v_mul_hi_i32 v96, v97, s51
	v_lshrrev_b32_e32 v98, 31, v96
	v_ashrrev_i32_e32 v96, 11, v96
	v_add_u32_e32 v96, v96, v98
	v_lshrrev_b32_e32 v114, 31, v112
	v_ashrrev_i32_e32 v112, 11, v112
	v_mad_i32_i24 v100, v96, s80, v97
	v_add_u32_e32 v112, v112, v114
	v_ashrrev_i32_e32 v101, 31, v100
	v_add_u32_e32 v102, 0xffffff00, v100
	v_cmp_gt_i32_e32 vcc, s50, v100
	v_mad_i32_i24 v116, v112, s80, v113
	v_ashrrev_i32_e32 v97, 31, v96
	v_cndmask_b32_e32 v99, v156, v158, vcc
	v_cndmask_b32_e32 v98, v159, v160, vcc
	v_cndmask_b32_e32 v101, 0, v101, vcc
	v_cndmask_b32_e32 v100, v102, v100, vcc
	v_cndmask_b32_e64 v102, 24, 20, vcc
	v_cmp_gt_i32_e32 vcc, s50, v116
	v_ashrrev_i32_e32 v113, 31, v112
	v_ashrrev_i32_e32 v117, 31, v116
	v_cndmask_b32_e64 v114, 24, 20, vcc
	v_add_u32_e32 v118, 0xffffff00, v116
	v_lshlrev_b64 v[96:97], v102, v[96:97]
	v_lshlrev_b64 v[112:113], v114, v[112:113]
	v_cndmask_b32_e32 v115, v156, v158, vcc
	v_cndmask_b32_e32 v114, v159, v160, vcc
	v_cndmask_b32_e32 v117, 0, v117, vcc
	v_cndmask_b32_e32 v116, v118, v116, vcc
	v_lshl_add_u64 v[96:97], v[98:99], 0, v[96:97]
	v_lshlrev_b64 v[98:99], 12, v[100:101]
	v_lshl_add_u64 v[112:113], v[114:115], 0, v[112:113]
	v_lshlrev_b64 v[114:115], 12, v[116:117]
	v_lshl_add_u64 v[96:97], v[96:97], 0, v[98:99]
	v_lshl_add_u64 v[112:113], v[112:113], 0, v[114:115]
	v_lshl_add_u64 v[162:163], v[96:97], 0, v[150:151]
	v_lshl_add_u64 v[164:165], v[112:113], 0, v[150:151]
	global_load_dwordx4 v[96:99], v[162:163], off
	global_load_dwordx4 v[100:103], v[162:163], off offset:64
	global_load_dwordx4 v[104:107], v[162:163], off offset:512
	global_load_dwordx4 v[108:111], v[162:163], off offset:576
	global_load_dwordx4 v[112:115], v[164:165], off
	global_load_dwordx4 v[116:119], v[164:165], off offset:64
	global_load_dwordx4 v[120:123], v[164:165], off offset:512
	global_load_dwordx4 v[124:127], v[164:165], off offset:576
	v_mul_hi_i32 v166, v161, s51
	v_lshrrev_b32_e32 v167, 31, v166
	v_ashrrev_i32_e32 v166, 11, v166
	v_add_u32_e32 v166, v166, v167
	v_ashrrev_i32_e32 v167, 31, v166
	s_waitcnt vmcnt(0)
	v_pk_fma_f32 v[94:95], v[94:95], v[142:143], v[98:99]
	v_pk_fma_f32 v[92:93], v[92:93], v[140:141], v[96:97]
	v_pk_fma_f32 v[80:81], v[80:81], v[136:137], v[116:117]
	v_pk_fma_f32 v[90:91], v[90:91], v[138:139], v[102:103]
	v_pk_fma_f32 v[88:89], v[88:89], v[136:137], v[100:101]
	v_pk_fma_f32 v[78:79], v[78:79], v[134:135], v[106:107]
	v_pk_fma_f32 v[76:77], v[76:77], v[132:133], v[104:105]
	v_pk_fma_f32 v[74:75], v[74:75], v[130:131], v[110:111]
	v_pk_fma_f32 v[72:73], v[72:73], v[128:129], v[108:109]
	v_pk_fma_f32 v[86:87], v[86:87], v[142:143], v[114:115]
	v_pk_fma_f32 v[84:85], v[84:85], v[140:141], v[112:113]
	v_pk_fma_f32 v[82:83], v[82:83], v[138:139], v[118:119]
	v_pk_fma_f32 v[70:71], v[70:71], v[134:135], v[122:123]
	v_pk_fma_f32 v[68:69], v[68:69], v[132:133], v[120:121]
	v_pk_fma_f32 v[66:67], v[66:67], v[130:131], v[126:127]
	v_pk_fma_f32 v[64:65], v[64:65], v[128:129], v[124:125]
	global_store_dwordx4 v[162:163], v[92:95], off
	global_store_dwordx4 v[162:163], v[88:91], off offset:64
	global_store_dwordx4 v[162:163], v[76:79], off offset:512
	global_store_dwordx4 v[162:163], v[72:75], off offset:576
	global_store_dwordx4 v[164:165], v[84:87], off
	global_store_dwordx4 v[164:165], v[80:83], off offset:64
	global_store_dwordx4 v[164:165], v[68:71], off offset:512
	global_store_dwordx4 v[164:165], v[64:67], off offset:576
	v_add_u32_e32 v81, 0x90, v157
	v_mul_hi_i32 v80, v81, s51
	v_lshrrev_b32_e32 v82, 31, v80
	v_ashrrev_i32_e32 v80, 11, v80
	v_mad_i32_i24 v66, v166, s80, v161
	v_add_u32_e32 v80, v80, v82
	v_ashrrev_i32_e32 v67, 31, v66
	v_add_u32_e32 v68, 0xffffff00, v66
	v_cmp_gt_i32_e32 vcc, s50, v66
	v_mad_i32_i24 v84, v80, s80, v81
	v_ashrrev_i32_e32 v81, 31, v80
	v_cndmask_b32_e32 v65, v156, v158, vcc
	v_cndmask_b32_e32 v64, v159, v160, vcc
	v_cndmask_b32_e32 v67, 0, v67, vcc
	v_cndmask_b32_e32 v66, v68, v66, vcc
	v_cndmask_b32_e64 v68, 24, 20, vcc
	v_cmp_gt_i32_e32 vcc, s50, v84
	v_ashrrev_i32_e32 v85, 31, v84
	v_add_u32_e32 v86, 0xffffff00, v84
	v_cndmask_b32_e64 v82, 24, 20, vcc
	v_lshlrev_b64 v[68:69], v68, v[166:167]
	v_lshlrev_b64 v[80:81], v82, v[80:81]
	v_cndmask_b32_e32 v83, v156, v158, vcc
	v_cndmask_b32_e32 v82, v159, v160, vcc
	v_cndmask_b32_e32 v85, 0, v85, vcc
	v_cndmask_b32_e32 v84, v86, v84, vcc
	v_lshl_add_u64 v[64:65], v[64:65], 0, v[68:69]
	v_lshlrev_b64 v[66:67], 12, v[66:67]
	v_lshl_add_u64 v[80:81], v[82:83], 0, v[80:81]
	v_lshlrev_b64 v[82:83], 12, v[84:85]
	v_lshl_add_u64 v[64:65], v[64:65], 0, v[66:67]
	v_lshl_add_u64 v[80:81], v[80:81], 0, v[82:83]
	v_lshl_add_u64 v[96:97], v[64:65], 0, v[150:151]
	v_lshl_add_u64 v[98:99], v[80:81], 0, v[150:151]
	global_load_dwordx4 v[64:67], v[96:97], off
	global_load_dwordx4 v[68:71], v[96:97], off offset:64
	global_load_dwordx4 v[72:75], v[96:97], off offset:512
	global_load_dwordx4 v[76:79], v[96:97], off offset:576
	global_load_dwordx4 v[80:83], v[98:99], off
	global_load_dwordx4 v[84:87], v[98:99], off offset:64
	global_load_dwordx4 v[88:91], v[98:99], off offset:512
	global_load_dwordx4 v[92:95], v[98:99], off offset:576
	v_add_u32_e32 v101, 0xa0, v157
	v_mul_hi_i32 v100, v101, s51
	v_lshrrev_b32_e32 v102, 31, v100
	v_ashrrev_i32_e32 v100, 11, v100
	v_add_u32_e32 v100, v100, v102
	v_mad_i32_i24 v104, v100, s80, v101
	v_ashrrev_i32_e32 v105, 31, v104
	v_add_u32_e32 v106, 0xffffff00, v104
	v_cmp_gt_i32_e32 vcc, s50, v104
	v_ashrrev_i32_e32 v101, 31, v100
	s_waitcnt vmcnt(0)
; #define MEMBAR() asm volatile("" ::: "memory")
; #define PG8_WAIT_V(n) asm volatile("s_waitcnt vmcnt(" #n ")" ::: "memory")
; #define PG8_BAR __builtin_amdgcn_s_barrier()
; #define PG8_WAIT_V(n) asm volatile("s_waitcnt vmcnt(" #n ")" ::: "memory")
; #define PG8_BAR __builtin_amdgcn_s_barrier()
; template <class Epi>
; DI void gemm_phase(char* smem, const bf16_t* A, int lda, const bf16_t* Bt, int ldb, int K, const Order& S_, const Epi& E) {
;     ...
;     if (!has_next) break;
; #pragma unroll
;     for (int a = 0; a < 2; ++a)
; #pragma unroll
;       for (int b = 0; b < 2; ++b)
; #pragma unroll
;         for (int m = 0; m < 4; ++m)
; #pragma unroll
;           for (int n = 0; n < 2; ++n) acc[a][b][m][n] = (f32x4){0.f, 0.f, 0.f, 0.f};
;     cur = nxt; cA = nA; cB = nB; ++ui;
;   }
;   PG8_WAIT_V(0);
;   if (wr == 0) PG8_BAR;
;   PG8_BAR;
;   DI void operator()(const acc_t& acc, const Unit& u, int wr, int wc, int fr, int fq) const {
;     ...
;       for (int mm = 0; mm < 2; ++mm) { const int t = row0 + ai * HALF + (2 * mh + mm) * 16;
;         const float* xi = from_input ? xrow_in(p, t) : xrow_ws(p, t);
; #pragma unroll
;         for (int bj = 0; bj < 2; ++bj)
; #pragma unroll
;           for (int n = 0; n < 2; ++n) xv[mm][bj][n] = *(const f32x4*)(xi + col0 + bj * HALF + n * 16); }
;       MEMBAR();
; #pragma unroll
;       for (int mm = 0; mm < 2; ++mm) { const int t = row0 + ai * HALF + (2 * mh + mm) * 16;
;         float* xo = xrow_ws(p, t);
; #pragma unroll
;         for (int bj = 0; bj < 2; ++bj)
; #pragma unroll
;           for (int n = 0; n < 2; ++n) *(f32x4*)(xo + col0 + bj * HALF + n * 16) = xv[mm][bj][n] + gv[bj][n] * acc[ai][bj][2 * mh + mm][n]; }
	v_pk_fma_f32 v[62:63], v[62:63], v[142:143], v[66:67]
	v_pk_fma_f32 v[60:61], v[60:61], v[140:141], v[64:65]
	v_pk_fma_f32 v[48:49], v[48:49], v[136:137], v[84:85]
	v_pk_fma_f32 v[58:59], v[58:59], v[138:139], v[70:71]
	v_pk_fma_f32 v[56:57], v[56:57], v[136:137], v[68:69]
	v_pk_fma_f32 v[46:47], v[46:47], v[134:135], v[74:75]
	v_pk_fma_f32 v[44:45], v[44:45], v[132:133], v[72:73]
	v_pk_fma_f32 v[42:43], v[42:43], v[130:131], v[78:79]
	v_pk_fma_f32 v[40:41], v[40:41], v[128:129], v[76:77]
	v_pk_fma_f32 v[54:55], v[54:55], v[142:143], v[82:83]
	v_pk_fma_f32 v[52:53], v[52:53], v[140:141], v[80:81]
	v_pk_fma_f32 v[50:51], v[50:51], v[138:139], v[86:87]
	v_pk_fma_f32 v[38:39], v[38:39], v[134:135], v[90:91]
	v_pk_fma_f32 v[36:37], v[36:37], v[132:133], v[88:89]
	v_pk_fma_f32 v[34:35], v[34:35], v[130:131], v[94:95]
	v_pk_fma_f32 v[32:33], v[32:33], v[128:129], v[92:93]
	global_store_dwordx4 v[96:97], v[60:63], off
	global_store_dwordx4 v[96:97], v[56:59], off offset:64
	global_store_dwordx4 v[96:97], v[44:47], off offset:512
	global_store_dwordx4 v[96:97], v[40:43], off offset:576
	global_store_dwordx4 v[98:99], v[52:55], off
	global_store_dwordx4 v[98:99], v[48:51], off offset:64
	global_store_dwordx4 v[98:99], v[36:39], off offset:512
	global_store_dwordx4 v[98:99], v[32:35], off offset:576
	v_add_u32_e32 v49, 0xb0, v157
	v_mul_hi_i32 v48, v49, s51
	v_lshrrev_b32_e32 v50, 31, v48
	v_ashrrev_i32_e32 v48, 11, v48
	v_add_u32_e32 v48, v48, v50
	v_mad_i32_i24 v52, v48, s80, v49
	v_cndmask_b32_e32 v103, v156, v158, vcc
	v_cndmask_b32_e32 v102, v159, v160, vcc
	v_cndmask_b32_e32 v105, 0, v105, vcc
	v_cndmask_b32_e32 v104, v106, v104, vcc
	v_cndmask_b32_e64 v32, 24, 20, vcc
	v_cmp_gt_i32_e32 vcc, s50, v52
	v_ashrrev_i32_e32 v49, 31, v48
	v_ashrrev_i32_e32 v53, 31, v52
	v_cndmask_b32_e64 v50, 24, 20, vcc
	v_add_u32_e32 v54, 0xffffff00, v52
	v_lshlrev_b64 v[32:33], v32, v[100:101]
	v_lshlrev_b64 v[48:49], v50, v[48:49]
	v_cndmask_b32_e32 v51, v156, v158, vcc
	v_cndmask_b32_e32 v50, v159, v160, vcc
	v_cndmask_b32_e32 v53, 0, v53, vcc
	v_cndmask_b32_e32 v52, v54, v52, vcc
	v_lshl_add_u64 v[32:33], v[102:103], 0, v[32:33]
	v_lshlrev_b64 v[34:35], 12, v[104:105]
	v_lshl_add_u64 v[48:49], v[50:51], 0, v[48:49]
	v_lshlrev_b64 v[50:51], 12, v[52:53]
	v_lshl_add_u64 v[32:33], v[32:33], 0, v[34:35]
	v_lshl_add_u64 v[48:49], v[48:49], 0, v[50:51]
	v_lshl_add_u64 v[64:65], v[32:33], 0, v[150:151]
	v_lshl_add_u64 v[66:67], v[48:49], 0, v[150:151]
	global_load_dwordx4 v[32:35], v[64:65], off
	global_load_dwordx4 v[36:39], v[64:65], off offset:64
	global_load_dwordx4 v[40:43], v[64:65], off offset:512
	global_load_dwordx4 v[44:47], v[64:65], off offset:576
	global_load_dwordx4 v[48:51], v[66:67], off
	global_load_dwordx4 v[52:55], v[66:67], off offset:64
	global_load_dwordx4 v[56:59], v[66:67], off offset:512
	global_load_dwordx4 v[60:63], v[66:67], off offset:576
	s_and_b64 vcc, exec, s[36:37]
	s_waitcnt vmcnt(0)
	v_pk_fma_f32 v[30:31], v[30:31], v[142:143], v[34:35]
	v_pk_fma_f32 v[28:29], v[28:29], v[140:141], v[32:33]
	v_pk_fma_f32 v[26:27], v[26:27], v[138:139], v[38:39]
	v_pk_fma_f32 v[24:25], v[24:25], v[136:137], v[36:37]
	v_pk_fma_f32 v[14:15], v[14:15], v[134:135], v[42:43]
	v_pk_fma_f32 v[12:13], v[12:13], v[132:133], v[40:41]
	v_pk_fma_f32 v[10:11], v[10:11], v[130:131], v[46:47]
	v_pk_fma_f32 v[8:9], v[8:9], v[128:129], v[44:45]
	v_pk_fma_f32 v[22:23], v[22:23], v[142:143], v[50:51]
	v_pk_fma_f32 v[20:21], v[20:21], v[140:141], v[48:49]
	v_pk_fma_f32 v[18:19], v[18:19], v[138:139], v[54:55]
	v_pk_fma_f32 v[16:17], v[16:17], v[136:137], v[52:53]
	v_pk_fma_f32 v[6:7], v[6:7], v[134:135], v[58:59]
	v_pk_fma_f32 v[4:5], v[4:5], v[132:133], v[56:57]
	v_pk_fma_f32 v[2:3], v[2:3], v[130:131], v[62:63]
	v_pk_fma_f32 v[0:1], v[0:1], v[128:129], v[60:61]
	global_store_dwordx4 v[64:65], v[28:31], off
	global_store_dwordx4 v[64:65], v[24:27], off offset:64
	global_store_dwordx4 v[64:65], v[12:15], off offset:512
	global_store_dwordx4 v[64:65], v[8:11], off offset:576
	global_store_dwordx4 v[66:67], v[20:23], off
	global_store_dwordx4 v[66:67], v[16:19], off offset:64
	global_store_dwordx4 v[66:67], v[4:7], off offset:512
	global_store_dwordx4 v[66:67], v[0:3], off offset:576
	s_cbranch_vccz .LBB0_1921
	s_waitcnt vmcnt(0)
	s_cmpk_gt_u32 s3, 0xff
	s_cbranch_scc1 .LBB0_1933
	s_barrier
